# static priority raise (s_setprio 1) during the GEMM k-loops for the block that arrived second on its CU
# speedup vs baseline: 1.0106x; 1.0106x over previous
.LBB0_152:
	s_or_saveexec_b64 s[0:1], s[0:1]
	v_mov_b32_e32 v176, 0
	v_mov_b32_e32 v94, 0
	v_mov_b32_e32 v182, 0
	v_mov_b32_e32 v92, 0
	v_mov_b32_e32 v184, 0
	v_mov_b32_e32 v90, 0
	v_mov_b32_e32 v186, 0
	v_mov_b32_e32 v88, 0
	v_mov_b32_e32 v188, 0
	v_mov_b32_e32 v86, 0
	v_mov_b32_e32 v190, 0
	v_mov_b32_e32 v84, 0
	v_mov_b32_e32 v192, 0
	v_mov_b32_e32 v82, 0
	v_mov_b32_e32 v194, 0
	v_mov_b32_e32 v80, 0
	v_mov_b32_e32 v128, 0
	v_mov_b32_e32 v46, 0
	v_mov_b32_e32 v130, 0
	v_mov_b32_e32 v44, 0
	v_mov_b32_e32 v132, 0
	v_mov_b32_e32 v42, 0
	v_mov_b32_e32 v134, 0
	v_mov_b32_e32 v40, 0
	v_mov_b32_e32 v136, 0
	v_mov_b32_e32 v38, 0
	v_mov_b32_e32 v138, 0
	v_mov_b32_e32 v36, 0
	v_mov_b32_e32 v172, 0
	v_mov_b32_e32 v34, 0
	v_mov_b32_e32 v174, 0
	v_mov_b32_e32 v32, 0
	v_mov_b32_e32 v177, 0
	v_mov_b32_e32 v95, 0
	v_mov_b32_e32 v183, 0
	v_mov_b32_e32 v93, 0
	v_mov_b32_e32 v185, 0
	v_mov_b32_e32 v91, 0
	v_mov_b32_e32 v187, 0
	v_mov_b32_e32 v89, 0
	v_mov_b32_e32 v189, 0
	v_mov_b32_e32 v87, 0
	v_mov_b32_e32 v191, 0
	v_mov_b32_e32 v85, 0
	v_mov_b32_e32 v193, 0
	v_mov_b32_e32 v83, 0
	v_mov_b32_e32 v195, 0
	v_mov_b32_e32 v81, 0
	v_mov_b32_e32 v129, 0
	v_mov_b32_e32 v47, 0
	v_mov_b32_e32 v131, 0
	v_mov_b32_e32 v45, 0
	v_mov_b32_e32 v133, 0
	v_mov_b32_e32 v43, 0
	v_mov_b32_e32 v135, 0
	v_mov_b32_e32 v41, 0
	v_mov_b32_e32 v137, 0
	v_mov_b32_e32 v39, 0
	v_mov_b32_e32 v139, 0
	v_mov_b32_e32 v37, 0
	v_mov_b32_e32 v173, 0
	v_mov_b32_e32 v35, 0
	v_mov_b32_e32 v175, 0
	v_mov_b32_e32 v33, 0
	s_xor_b64 exec, exec, s[0:1]
	s_cbranch_execz .LBB0_156
	v_readfirstlane_b32 s78, v170
	v_readfirstlane_b32 s79, v168
	v_readfirstlane_b32 s76, v204
	v_mbcnt_lo_u32_b32 v136, -1, 0
	v_mbcnt_hi_u32_b32 v136, -1, v136
	s_nop 3
	s_lshl_b32 s78, s78, 14
	s_lshl_b32 s79, s79, 13
	s_add_u32 s72, s90, s78
	s_addc_u32 s73, s91, 0
	s_add_u32 s74, s90, s79
	s_addc_u32 s75, s91, 0
	s_add_u32 s74, s74, 0x1ab88000
	s_addc_u32 s75, s75, 0
	v_lshrrev_b32_e32 v137, 2, v136
	v_lshrrev_b32_e32 v138, 4, v136
	v_xor_b32_e32 v138, v138, v136
	v_and_b32_e32 v138, 3, v138
	v_lshlrev_b32_e32 v138, 4, v138
	v_lshl_or_b32 v137, v137, 6, v138
	v_or_b32_e32 v132, v137, v204
	v_add_u32_e32 v133, 0x1000, v132
	v_add_u32_e32 v134, 0x2000, v132
	v_add_u32_e32 v135, 0x3000, v132
	v_and_b32_e32 v137, 15, v136
	v_lshrrev_b32_e32 v138, 4, v136
	v_bfe_u32 v139, v136, 2, 2
	v_xor_b32_e32 v139, v139, v138
	v_lshlrev_b32_e32 v139, 4, v139
	v_lshl_or_b32 v128, v137, 6, v139
	v_lshrrev_b32_e32 v139, 10, v204
	v_lshrrev_b32_e32 v139, 1, v139
	v_lshl_or_b32 v128, v139, 11, v128
	v_and_b32_e32 v139, 3, v136
	v_bfe_u32 v137, v136, 2, 1
	v_lshl_or_b32 v139, v137, 3, v139
	v_bfe_u32 v137, v136, 3, 1
	v_lshl_or_b32 v139, v137, 2, v139
	v_lshrrev_b32_e32 v137, 2, v139
	v_xor_b32_e32 v137, v137, v138
	v_lshlrev_b32_e32 v137, 4, v137
	v_lshl_or_b32 v130, v139, 6, v137
	v_lshrrev_b32_e32 v139, 10, v204
	v_and_b32_e32 v139, 1, v139
	v_lshl_or_b32 v130, v139, 12, v130
	v_or_b32_e32 v130, 0x4000, v130
	s_cmp_eq_u32 s99, 0x7fffffff
	s_cbranch_scc0 .Lgprio_p1
	s_setprio 1
.Lgprio_p1:
	s_add_u32 m0, s76, 0x2000
	s_nop 0
	global_load_lds_dwordx4 v134, s[72:73]
	s_add_u32 m0, s76, 0x3000
	s_nop 0
	global_load_lds_dwordx4 v135, s[72:73]
	s_add_u32 m0, s76, 0x4000
	s_nop 0
	global_load_lds_dwordx4 v132, s[74:75]
	s_add_u32 m0, s76, 0x5000
	s_nop 0
	global_load_lds_dwordx4 v133, s[74:75]
	s_add_u32 s72, s72, 0x202000
	s_addc_u32 s73, s73, 0
	s_add_u32 s74, s74, 0x2c000
	s_addc_u32 s75, s75, 0
	s_add_u32 m0, s76, 0x6000
	s_nop 0
	global_load_lds_dwordx4 v132, s[72:73]
	s_add_u32 m0, s76, 0x7000
	s_nop 0
	global_load_lds_dwordx4 v133, s[72:73]
	s_add_u32 m0, s76, 0x8000
	s_nop 0
	global_load_lds_dwordx4 v134, s[72:73]
	s_add_u32 m0, s76, 0x9000
	s_nop 0
	global_load_lds_dwordx4 v135, s[72:73]
	s_add_u32 m0, s76, 0xa000
	s_nop 0
	global_load_lds_dwordx4 v132, s[74:75]
	s_add_u32 m0, s76, 0xb000
	s_nop 0
	global_load_lds_dwordx4 v133, s[74:75]
	s_add_u32 s72, s72, 0x202000
	s_addc_u32 s73, s73, 0
	s_add_u32 s74, s74, 0x2c000
	s_addc_u32 s75, s75, 0
	s_add_u32 m0, s76, 0xc000
	s_nop 0
	global_load_lds_dwordx4 v132, s[72:73]
	s_add_u32 m0, s76, 0xd000
	s_nop 0
	global_load_lds_dwordx4 v133, s[72:73]
	s_add_u32 m0, s76, 0xe000
	s_nop 0
	global_load_lds_dwordx4 v134, s[72:73]
	s_add_u32 m0, s76, 0xf000
	s_nop 0
	global_load_lds_dwordx4 v135, s[72:73]
	s_add_u32 m0, s76, 0x10000
	s_nop 0
	global_load_lds_dwordx4 v132, s[74:75]
	s_add_u32 m0, s76, 0x11000
	s_nop 0
	global_load_lds_dwordx4 v133, s[74:75]
	s_add_u32 s72, s72, 0x202000
	s_addc_u32 s73, s73, 0
	s_add_u32 s74, s74, 0x2c000
	s_addc_u32 s75, s75, 0
	s_waitcnt vmcnt(12)
	s_barrier
	ds_read_b128 v[172:175], v130
	ds_read_b128 v[176:179], v130 offset:1024
	ds_read_b128 v[180:183], v130 offset:2048
	ds_read_b128 v[184:187], v130 offset:3072
	ds_read_b128 v[228:231], v128
	ds_read_b128 v[232:235], v128 offset:1024
	ds_read_b128 v[236:239], v128 offset:4096
	ds_read_b128 v[240:243], v128 offset:5120
	s_waitcnt lgkmcnt(0)
	v_mfma_f32_16x16x32_bf16 v[64:67], v[172:175], v[228:231], 0
	ds_read_b128 v[244:247], v128 offset:8192
	v_mfma_f32_16x16x32_bf16 v[68:71], v[172:175], v[232:235], 0
	ds_read_b128 v[248:251], v128 offset:9216
	v_mfma_f32_16x16x32_bf16 v[72:75], v[176:179], v[228:231], 0
	v_mfma_f32_16x16x32_bf16 v[76:79], v[176:179], v[232:235], 0
	v_mfma_f32_16x16x32_bf16 v[48:51], v[180:183], v[228:231], 0
	v_mfma_f32_16x16x32_bf16 v[52:55], v[180:183], v[232:235], 0
	v_mfma_f32_16x16x32_bf16 v[56:59], v[184:187], v[228:231], 0
	v_mfma_f32_16x16x32_bf16 v[60:63], v[184:187], v[232:235], 0
	s_waitcnt lgkmcnt(2)
	v_mfma_f32_16x16x32_bf16 v[16:19], v[172:175], v[236:239], 0
	ds_read_b128 v[228:231], v128 offset:12288
	v_mfma_f32_16x16x32_bf16 v[20:23], v[172:175], v[240:243], 0
	ds_read_b128 v[232:235], v128 offset:13312
	v_mfma_f32_16x16x32_bf16 v[24:27], v[176:179], v[236:239], 0
	v_mfma_f32_16x16x32_bf16 v[28:31], v[176:179], v[240:243], 0
	v_mfma_f32_16x16x32_bf16 v[0:3], v[180:183], v[236:239], 0
	v_mfma_f32_16x16x32_bf16 v[4:7], v[180:183], v[240:243], 0
	v_mfma_f32_16x16x32_bf16 v[8:11], v[184:187], v[236:239], 0
	v_mfma_f32_16x16x32_bf16 v[12:15], v[184:187], v[240:243], 0
	s_waitcnt lgkmcnt(0)
	s_waitcnt vmcnt(6)
	s_barrier
	ds_read_b128 v[188:191], v130 offset:24576
	ds_read_b128 v[192:195], v130 offset:25600
	v_mfma_f32_16x16x32_bf16 v[80:83], v[172:175], v[244:247], 0
	ds_read_b128 v[220:223], v130 offset:26624
	ds_read_b128 v[224:227], v130 offset:27648
	v_mfma_f32_16x16x32_bf16 v[84:87], v[172:175], v[248:251], 0
	ds_read_b128 v[236:239], v128 offset:24576
	ds_read_b128 v[240:243], v128 offset:25600
	s_add_u32 m0, s76, 0x0
	v_mfma_f32_16x16x32_bf16 v[88:91], v[176:179], v[244:247], 0
	global_load_lds_dwordx4 v132, s[72:73]
	s_add_u32 m0, s76, 0x1000
	v_mfma_f32_16x16x32_bf16 v[92:95], v[176:179], v[248:251], 0
	global_load_lds_dwordx4 v133, s[72:73]
	s_add_u32 m0, s76, 0x2000
	v_mfma_f32_16x16x32_bf16 v[112:115], v[180:183], v[244:247], 0
	global_load_lds_dwordx4 v134, s[72:73]
	v_mfma_f32_16x16x32_bf16 v[116:119], v[180:183], v[248:251], 0
	v_mfma_f32_16x16x32_bf16 v[120:123], v[184:187], v[244:247], 0
	v_mfma_f32_16x16x32_bf16 v[124:127], v[184:187], v[248:251], 0
	ds_read_b128 v[244:247], v128 offset:28672
	ds_read_b128 v[248:251], v128 offset:29696
	v_mfma_f32_16x16x32_bf16 v[32:35], v[172:175], v[228:231], 0
	s_add_u32 m0, s76, 0x3000
	v_mfma_f32_16x16x32_bf16 v[36:39], v[172:175], v[232:235], 0
	global_load_lds_dwordx4 v135, s[72:73]
	s_add_u32 m0, s76, 0x4000
	v_mfma_f32_16x16x32_bf16 v[40:43], v[176:179], v[228:231], 0
	global_load_lds_dwordx4 v132, s[74:75]
	s_add_u32 m0, s76, 0x5000
	v_mfma_f32_16x16x32_bf16 v[44:47], v[176:179], v[232:235], 0
	global_load_lds_dwordx4 v133, s[74:75]
	s_add_u32 s72, s72, 0x202000
	s_addc_u32 s73, s73, 0
	v_mfma_f32_16x16x32_bf16 v[96:99], v[180:183], v[228:231], 0
	s_add_u32 s74, s74, 0x2c000
	s_addc_u32 s75, s75, 0
	v_mfma_f32_16x16x32_bf16 v[100:103], v[180:183], v[232:235], 0
	v_mfma_f32_16x16x32_bf16 v[104:107], v[184:187], v[228:231], 0
	v_mfma_f32_16x16x32_bf16 v[108:111], v[184:187], v[232:235], 0
	s_waitcnt lgkmcnt(2)
	v_mfma_f32_16x16x32_bf16 v[64:67], v[188:191], v[236:239], v[64:67]
	ds_read_b128 v[228:231], v128 offset:32768
	v_mfma_f32_16x16x32_bf16 v[68:71], v[188:191], v[240:243], v[68:71]
	ds_read_b128 v[232:235], v128 offset:33792
	v_mfma_f32_16x16x32_bf16 v[72:75], v[192:195], v[236:239], v[72:75]
	v_mfma_f32_16x16x32_bf16 v[76:79], v[192:195], v[240:243], v[76:79]
	v_mfma_f32_16x16x32_bf16 v[48:51], v[220:223], v[236:239], v[48:51]
	v_mfma_f32_16x16x32_bf16 v[52:55], v[220:223], v[240:243], v[52:55]
	v_mfma_f32_16x16x32_bf16 v[56:59], v[224:227], v[236:239], v[56:59]
	v_mfma_f32_16x16x32_bf16 v[60:63], v[224:227], v[240:243], v[60:63]
	s_waitcnt lgkmcnt(2)
	v_mfma_f32_16x16x32_bf16 v[16:19], v[188:191], v[244:247], v[16:19]
	ds_read_b128 v[236:239], v128 offset:36864
	v_mfma_f32_16x16x32_bf16 v[20:23], v[188:191], v[248:251], v[20:23]
	ds_read_b128 v[240:243], v128 offset:37888
	v_mfma_f32_16x16x32_bf16 v[24:27], v[192:195], v[244:247], v[24:27]
	v_mfma_f32_16x16x32_bf16 v[28:31], v[192:195], v[248:251], v[28:31]
	v_mfma_f32_16x16x32_bf16 v[0:3], v[220:223], v[244:247], v[0:3]
	v_mfma_f32_16x16x32_bf16 v[4:7], v[220:223], v[248:251], v[4:7]
	v_mfma_f32_16x16x32_bf16 v[8:11], v[224:227], v[244:247], v[8:11]
	v_mfma_f32_16x16x32_bf16 v[12:15], v[224:227], v[248:251], v[12:15]
	s_waitcnt lgkmcnt(0)
	s_waitcnt vmcnt(6)
	s_barrier
	ds_read_b128 v[172:175], v130 offset:49152
	ds_read_b128 v[176:179], v130 offset:50176
	v_mfma_f32_16x16x32_bf16 v[80:83], v[188:191], v[228:231], v[80:83]
	ds_read_b128 v[180:183], v130 offset:51200
	ds_read_b128 v[184:187], v130 offset:52224
	v_mfma_f32_16x16x32_bf16 v[84:87], v[188:191], v[232:235], v[84:87]
	ds_read_b128 v[244:247], v128 offset:49152
	ds_read_b128 v[248:251], v128 offset:50176
	s_add_u32 m0, s76, 0x6000
	v_mfma_f32_16x16x32_bf16 v[88:91], v[192:195], v[228:231], v[88:91]
	global_load_lds_dwordx4 v132, s[72:73]
	s_add_u32 m0, s76, 0x7000
	v_mfma_f32_16x16x32_bf16 v[92:95], v[192:195], v[232:235], v[92:95]
	global_load_lds_dwordx4 v133, s[72:73]
	s_add_u32 m0, s76, 0x8000
	v_mfma_f32_16x16x32_bf16 v[112:115], v[220:223], v[228:231], v[112:115]
	global_load_lds_dwordx4 v134, s[72:73]
	v_mfma_f32_16x16x32_bf16 v[116:119], v[220:223], v[232:235], v[116:119]
	v_mfma_f32_16x16x32_bf16 v[120:123], v[224:227], v[228:231], v[120:123]
	v_mfma_f32_16x16x32_bf16 v[124:127], v[224:227], v[232:235], v[124:127]
	ds_read_b128 v[228:231], v128 offset:53248
	ds_read_b128 v[232:235], v128 offset:54272
	v_mfma_f32_16x16x32_bf16 v[32:35], v[188:191], v[236:239], v[32:35]
	s_add_u32 m0, s76, 0x9000
	v_mfma_f32_16x16x32_bf16 v[36:39], v[188:191], v[240:243], v[36:39]
	global_load_lds_dwordx4 v135, s[72:73]
	s_add_u32 m0, s76, 0xa000
	v_mfma_f32_16x16x32_bf16 v[40:43], v[192:195], v[236:239], v[40:43]
	global_load_lds_dwordx4 v132, s[74:75]
	s_add_u32 m0, s76, 0xb000
	v_mfma_f32_16x16x32_bf16 v[44:47], v[192:195], v[240:243], v[44:47]
	global_load_lds_dwordx4 v133, s[74:75]
	s_add_u32 s72, s72, 0x202000
	s_addc_u32 s73, s73, 0
	v_mfma_f32_16x16x32_bf16 v[96:99], v[220:223], v[236:239], v[96:99]
	s_add_u32 s74, s74, 0x2c000
	s_addc_u32 s75, s75, 0
	v_mfma_f32_16x16x32_bf16 v[100:103], v[220:223], v[240:243], v[100:103]
	v_mfma_f32_16x16x32_bf16 v[104:107], v[224:227], v[236:239], v[104:107]
	v_mfma_f32_16x16x32_bf16 v[108:111], v[224:227], v[240:243], v[108:111]
	s_waitcnt lgkmcnt(2)
	v_mfma_f32_16x16x32_bf16 v[64:67], v[172:175], v[244:247], v[64:67]
	ds_read_b128 v[236:239], v128 offset:57344
	v_mfma_f32_16x16x32_bf16 v[68:71], v[172:175], v[248:251], v[68:71]
	ds_read_b128 v[240:243], v128 offset:58368
	v_mfma_f32_16x16x32_bf16 v[72:75], v[176:179], v[244:247], v[72:75]
	v_mfma_f32_16x16x32_bf16 v[76:79], v[176:179], v[248:251], v[76:79]
	v_mfma_f32_16x16x32_bf16 v[48:51], v[180:183], v[244:247], v[48:51]
	v_mfma_f32_16x16x32_bf16 v[52:55], v[180:183], v[248:251], v[52:55]
	v_mfma_f32_16x16x32_bf16 v[56:59], v[184:187], v[244:247], v[56:59]
	v_mfma_f32_16x16x32_bf16 v[60:63], v[184:187], v[248:251], v[60:63]
	s_waitcnt lgkmcnt(2)
	v_mfma_f32_16x16x32_bf16 v[16:19], v[172:175], v[228:231], v[16:19]
	ds_read_b128 v[244:247], v128 offset:61440
	v_mfma_f32_16x16x32_bf16 v[20:23], v[172:175], v[232:235], v[20:23]
	ds_read_b128 v[248:251], v128 offset:62464
	v_mfma_f32_16x16x32_bf16 v[24:27], v[176:179], v[228:231], v[24:27]
	v_mfma_f32_16x16x32_bf16 v[28:31], v[176:179], v[232:235], v[28:31]
	v_mfma_f32_16x16x32_bf16 v[0:3], v[180:183], v[228:231], v[0:3]
	v_mfma_f32_16x16x32_bf16 v[4:7], v[180:183], v[232:235], v[4:7]
	v_mfma_f32_16x16x32_bf16 v[8:11], v[184:187], v[228:231], v[8:11]
	v_mfma_f32_16x16x32_bf16 v[12:15], v[184:187], v[232:235], v[12:15]
	s_waitcnt lgkmcnt(0)
	s_waitcnt vmcnt(6)
	s_barrier
	ds_read_b128 v[188:191], v130
	ds_read_b128 v[192:195], v130 offset:1024
	v_mfma_f32_16x16x32_bf16 v[80:83], v[172:175], v[236:239], v[80:83]
	ds_read_b128 v[220:223], v130 offset:2048
	ds_read_b128 v[224:227], v130 offset:3072
	v_mfma_f32_16x16x32_bf16 v[84:87], v[172:175], v[240:243], v[84:87]
	ds_read_b128 v[228:231], v128
	ds_read_b128 v[232:235], v128 offset:1024
	s_add_u32 m0, s76, 0xc000
	v_mfma_f32_16x16x32_bf16 v[88:91], v[176:179], v[236:239], v[88:91]
	global_load_lds_dwordx4 v132, s[72:73]
	s_add_u32 m0, s76, 0xd000
	v_mfma_f32_16x16x32_bf16 v[92:95], v[176:179], v[240:243], v[92:95]
	global_load_lds_dwordx4 v133, s[72:73]
	s_add_u32 m0, s76, 0xe000
	v_mfma_f32_16x16x32_bf16 v[112:115], v[180:183], v[236:239], v[112:115]
	global_load_lds_dwordx4 v134, s[72:73]
	v_mfma_f32_16x16x32_bf16 v[116:119], v[180:183], v[240:243], v[116:119]
	v_mfma_f32_16x16x32_bf16 v[120:123], v[184:187], v[236:239], v[120:123]
	v_mfma_f32_16x16x32_bf16 v[124:127], v[184:187], v[240:243], v[124:127]
	ds_read_b128 v[236:239], v128 offset:4096
	ds_read_b128 v[240:243], v128 offset:5120
	v_mfma_f32_16x16x32_bf16 v[32:35], v[172:175], v[244:247], v[32:35]
	s_add_u32 m0, s76, 0xf000
	v_mfma_f32_16x16x32_bf16 v[36:39], v[172:175], v[248:251], v[36:39]
	global_load_lds_dwordx4 v135, s[72:73]
	s_add_u32 m0, s76, 0x10000
	v_mfma_f32_16x16x32_bf16 v[40:43], v[176:179], v[244:247], v[40:43]
	global_load_lds_dwordx4 v132, s[74:75]
	s_add_u32 m0, s76, 0x11000
	v_mfma_f32_16x16x32_bf16 v[44:47], v[176:179], v[248:251], v[44:47]
	global_load_lds_dwordx4 v133, s[74:75]
	s_add_u32 s72, s72, 0x202000
	s_addc_u32 s73, s73, 0
	v_mfma_f32_16x16x32_bf16 v[96:99], v[180:183], v[244:247], v[96:99]
	s_add_u32 s74, s74, 0x2c000
	s_addc_u32 s75, s75, 0
	v_mfma_f32_16x16x32_bf16 v[100:103], v[180:183], v[248:251], v[100:103]
	v_mfma_f32_16x16x32_bf16 v[104:107], v[184:187], v[244:247], v[104:107]
	v_mfma_f32_16x16x32_bf16 v[108:111], v[184:187], v[248:251], v[108:111]
	s_waitcnt lgkmcnt(2)
	v_mfma_f32_16x16x32_bf16 v[64:67], v[188:191], v[228:231], v[64:67]
	ds_read_b128 v[244:247], v128 offset:8192
	v_mfma_f32_16x16x32_bf16 v[68:71], v[188:191], v[232:235], v[68:71]
	ds_read_b128 v[248:251], v128 offset:9216
	v_mfma_f32_16x16x32_bf16 v[72:75], v[192:195], v[228:231], v[72:75]
	v_mfma_f32_16x16x32_bf16 v[76:79], v[192:195], v[232:235], v[76:79]
	v_mfma_f32_16x16x32_bf16 v[48:51], v[220:223], v[228:231], v[48:51]
	v_mfma_f32_16x16x32_bf16 v[52:55], v[220:223], v[232:235], v[52:55]
	v_mfma_f32_16x16x32_bf16 v[56:59], v[224:227], v[228:231], v[56:59]
	v_mfma_f32_16x16x32_bf16 v[60:63], v[224:227], v[232:235], v[60:63]
	s_waitcnt lgkmcnt(2)
	v_mfma_f32_16x16x32_bf16 v[16:19], v[188:191], v[236:239], v[16:19]
	ds_read_b128 v[228:231], v128 offset:12288
	v_mfma_f32_16x16x32_bf16 v[20:23], v[188:191], v[240:243], v[20:23]
	ds_read_b128 v[232:235], v128 offset:13312
	v_mfma_f32_16x16x32_bf16 v[24:27], v[192:195], v[236:239], v[24:27]
	v_mfma_f32_16x16x32_bf16 v[28:31], v[192:195], v[240:243], v[28:31]
	v_mfma_f32_16x16x32_bf16 v[0:3], v[220:223], v[236:239], v[0:3]
	v_mfma_f32_16x16x32_bf16 v[4:7], v[220:223], v[240:243], v[4:7]
	v_mfma_f32_16x16x32_bf16 v[8:11], v[224:227], v[236:239], v[8:11]
	v_mfma_f32_16x16x32_bf16 v[12:15], v[224:227], v[240:243], v[12:15]
	s_waitcnt lgkmcnt(0)
	s_waitcnt vmcnt(6)
	s_barrier
	ds_read_b128 v[172:175], v130 offset:24576
	ds_read_b128 v[176:179], v130 offset:25600
	v_mfma_f32_16x16x32_bf16 v[80:83], v[188:191], v[244:247], v[80:83]
	ds_read_b128 v[180:183], v130 offset:26624
	ds_read_b128 v[184:187], v130 offset:27648
	v_mfma_f32_16x16x32_bf16 v[84:87], v[188:191], v[248:251], v[84:87]
	ds_read_b128 v[236:239], v128 offset:24576
	ds_read_b128 v[240:243], v128 offset:25600
	s_add_u32 m0, s76, 0x0
	v_mfma_f32_16x16x32_bf16 v[88:91], v[192:195], v[244:247], v[88:91]
	global_load_lds_dwordx4 v132, s[72:73]
	s_add_u32 m0, s76, 0x1000
	v_mfma_f32_16x16x32_bf16 v[92:95], v[192:195], v[248:251], v[92:95]
	global_load_lds_dwordx4 v133, s[72:73]
	s_add_u32 m0, s76, 0x2000
	v_mfma_f32_16x16x32_bf16 v[112:115], v[220:223], v[244:247], v[112:115]
	global_load_lds_dwordx4 v134, s[72:73]
	v_mfma_f32_16x16x32_bf16 v[116:119], v[220:223], v[248:251], v[116:119]
	v_mfma_f32_16x16x32_bf16 v[120:123], v[224:227], v[244:247], v[120:123]
	v_mfma_f32_16x16x32_bf16 v[124:127], v[224:227], v[248:251], v[124:127]
	ds_read_b128 v[244:247], v128 offset:28672
	ds_read_b128 v[248:251], v128 offset:29696
	v_mfma_f32_16x16x32_bf16 v[32:35], v[188:191], v[228:231], v[32:35]
	s_add_u32 m0, s76, 0x3000
	v_mfma_f32_16x16x32_bf16 v[36:39], v[188:191], v[232:235], v[36:39]
	global_load_lds_dwordx4 v135, s[72:73]
	s_add_u32 m0, s76, 0x4000
	v_mfma_f32_16x16x32_bf16 v[40:43], v[192:195], v[228:231], v[40:43]
	global_load_lds_dwordx4 v132, s[74:75]
	s_add_u32 m0, s76, 0x5000
	v_mfma_f32_16x16x32_bf16 v[44:47], v[192:195], v[232:235], v[44:47]
	global_load_lds_dwordx4 v133, s[74:75]
	s_add_u32 s72, s72, 0x202000
	s_addc_u32 s73, s73, 0
	v_mfma_f32_16x16x32_bf16 v[96:99], v[220:223], v[228:231], v[96:99]
	s_add_u32 s74, s74, 0x2c000
	s_addc_u32 s75, s75, 0
	v_mfma_f32_16x16x32_bf16 v[100:103], v[220:223], v[232:235], v[100:103]
	v_mfma_f32_16x16x32_bf16 v[104:107], v[224:227], v[228:231], v[104:107]
	v_mfma_f32_16x16x32_bf16 v[108:111], v[224:227], v[232:235], v[108:111]
	s_waitcnt lgkmcnt(2)
	v_mfma_f32_16x16x32_bf16 v[64:67], v[172:175], v[236:239], v[64:67]
	ds_read_b128 v[228:231], v128 offset:32768
	v_mfma_f32_16x16x32_bf16 v[68:71], v[172:175], v[240:243], v[68:71]
	ds_read_b128 v[232:235], v128 offset:33792
	v_mfma_f32_16x16x32_bf16 v[72:75], v[176:179], v[236:239], v[72:75]
	v_mfma_f32_16x16x32_bf16 v[76:79], v[176:179], v[240:243], v[76:79]
	v_mfma_f32_16x16x32_bf16 v[48:51], v[180:183], v[236:239], v[48:51]
	v_mfma_f32_16x16x32_bf16 v[52:55], v[180:183], v[240:243], v[52:55]
	v_mfma_f32_16x16x32_bf16 v[56:59], v[184:187], v[236:239], v[56:59]
	v_mfma_f32_16x16x32_bf16 v[60:63], v[184:187], v[240:243], v[60:63]
	s_waitcnt lgkmcnt(2)
	v_mfma_f32_16x16x32_bf16 v[16:19], v[172:175], v[244:247], v[16:19]
	ds_read_b128 v[236:239], v128 offset:36864
	v_mfma_f32_16x16x32_bf16 v[20:23], v[172:175], v[248:251], v[20:23]
	ds_read_b128 v[240:243], v128 offset:37888
	v_mfma_f32_16x16x32_bf16 v[24:27], v[176:179], v[244:247], v[24:27]
	v_mfma_f32_16x16x32_bf16 v[28:31], v[176:179], v[248:251], v[28:31]
	v_mfma_f32_16x16x32_bf16 v[0:3], v[180:183], v[244:247], v[0:3]
	v_mfma_f32_16x16x32_bf16 v[4:7], v[180:183], v[248:251], v[4:7]
	v_mfma_f32_16x16x32_bf16 v[8:11], v[184:187], v[244:247], v[8:11]
	v_mfma_f32_16x16x32_bf16 v[12:15], v[184:187], v[248:251], v[12:15]
	s_waitcnt lgkmcnt(0)
	s_waitcnt vmcnt(6)
	s_barrier
	ds_read_b128 v[188:191], v130 offset:49152
	ds_read_b128 v[192:195], v130 offset:50176
	v_mfma_f32_16x16x32_bf16 v[80:83], v[172:175], v[228:231], v[80:83]
	ds_read_b128 v[220:223], v130 offset:51200
	ds_read_b128 v[224:227], v130 offset:52224
	v_mfma_f32_16x16x32_bf16 v[84:87], v[172:175], v[232:235], v[84:87]
	ds_read_b128 v[244:247], v128 offset:49152
	ds_read_b128 v[248:251], v128 offset:50176
	s_add_u32 m0, s76, 0x6000
	v_mfma_f32_16x16x32_bf16 v[88:91], v[176:179], v[228:231], v[88:91]
	global_load_lds_dwordx4 v132, s[72:73]
	s_add_u32 m0, s76, 0x7000
	v_mfma_f32_16x16x32_bf16 v[92:95], v[176:179], v[232:235], v[92:95]
	global_load_lds_dwordx4 v133, s[72:73]
	s_add_u32 m0, s76, 0x8000
	v_mfma_f32_16x16x32_bf16 v[112:115], v[180:183], v[228:231], v[112:115]
	global_load_lds_dwordx4 v134, s[72:73]
	v_mfma_f32_16x16x32_bf16 v[116:119], v[180:183], v[232:235], v[116:119]
	v_mfma_f32_16x16x32_bf16 v[120:123], v[184:187], v[228:231], v[120:123]
	v_mfma_f32_16x16x32_bf16 v[124:127], v[184:187], v[232:235], v[124:127]
	ds_read_b128 v[228:231], v128 offset:53248
	ds_read_b128 v[232:235], v128 offset:54272
	v_mfma_f32_16x16x32_bf16 v[32:35], v[172:175], v[236:239], v[32:35]
	s_add_u32 m0, s76, 0x9000
	v_mfma_f32_16x16x32_bf16 v[36:39], v[172:175], v[240:243], v[36:39]
	global_load_lds_dwordx4 v135, s[72:73]
	s_add_u32 m0, s76, 0xa000
	v_mfma_f32_16x16x32_bf16 v[40:43], v[176:179], v[236:239], v[40:43]
	global_load_lds_dwordx4 v132, s[74:75]
	s_add_u32 m0, s76, 0xb000
	v_mfma_f32_16x16x32_bf16 v[44:47], v[176:179], v[240:243], v[44:47]
	global_load_lds_dwordx4 v133, s[74:75]
	s_add_u32 s72, s72, 0x202000
	s_addc_u32 s73, s73, 0
	v_mfma_f32_16x16x32_bf16 v[96:99], v[180:183], v[236:239], v[96:99]
	s_add_u32 s74, s74, 0x2c000
	s_addc_u32 s75, s75, 0
	v_mfma_f32_16x16x32_bf16 v[100:103], v[180:183], v[240:243], v[100:103]
	v_mfma_f32_16x16x32_bf16 v[104:107], v[184:187], v[236:239], v[104:107]
	v_mfma_f32_16x16x32_bf16 v[108:111], v[184:187], v[240:243], v[108:111]
	s_waitcnt lgkmcnt(2)
	v_mfma_f32_16x16x32_bf16 v[64:67], v[188:191], v[244:247], v[64:67]
	ds_read_b128 v[236:239], v128 offset:57344
	v_mfma_f32_16x16x32_bf16 v[68:71], v[188:191], v[248:251], v[68:71]
	ds_read_b128 v[240:243], v128 offset:58368
	v_mfma_f32_16x16x32_bf16 v[72:75], v[192:195], v[244:247], v[72:75]
	v_mfma_f32_16x16x32_bf16 v[76:79], v[192:195], v[248:251], v[76:79]
	v_mfma_f32_16x16x32_bf16 v[48:51], v[220:223], v[244:247], v[48:51]
	v_mfma_f32_16x16x32_bf16 v[52:55], v[220:223], v[248:251], v[52:55]
	v_mfma_f32_16x16x32_bf16 v[56:59], v[224:227], v[244:247], v[56:59]
	v_mfma_f32_16x16x32_bf16 v[60:63], v[224:227], v[248:251], v[60:63]
	s_waitcnt lgkmcnt(2)
	v_mfma_f32_16x16x32_bf16 v[16:19], v[188:191], v[228:231], v[16:19]
	ds_read_b128 v[244:247], v128 offset:61440
	v_mfma_f32_16x16x32_bf16 v[20:23], v[188:191], v[232:235], v[20:23]
	ds_read_b128 v[248:251], v128 offset:62464
	v_mfma_f32_16x16x32_bf16 v[24:27], v[192:195], v[228:231], v[24:27]
	v_mfma_f32_16x16x32_bf16 v[28:31], v[192:195], v[232:235], v[28:31]
	v_mfma_f32_16x16x32_bf16 v[0:3], v[220:223], v[228:231], v[0:3]
	v_mfma_f32_16x16x32_bf16 v[4:7], v[220:223], v[232:235], v[4:7]
	v_mfma_f32_16x16x32_bf16 v[8:11], v[224:227], v[228:231], v[8:11]
	v_mfma_f32_16x16x32_bf16 v[12:15], v[224:227], v[232:235], v[12:15]
	s_waitcnt lgkmcnt(0)
	s_waitcnt vmcnt(6)
	s_barrier
	ds_read_b128 v[172:175], v130
	ds_read_b128 v[176:179], v130 offset:1024
	v_mfma_f32_16x16x32_bf16 v[80:83], v[188:191], v[236:239], v[80:83]
	ds_read_b128 v[180:183], v130 offset:2048
	ds_read_b128 v[184:187], v130 offset:3072
	v_mfma_f32_16x16x32_bf16 v[84:87], v[188:191], v[240:243], v[84:87]
	ds_read_b128 v[228:231], v128
	ds_read_b128 v[232:235], v128 offset:1024
	s_add_u32 m0, s76, 0xc000
	v_mfma_f32_16x16x32_bf16 v[88:91], v[192:195], v[236:239], v[88:91]
	global_load_lds_dwordx4 v132, s[72:73]
	s_add_u32 m0, s76, 0xd000
	v_mfma_f32_16x16x32_bf16 v[92:95], v[192:195], v[240:243], v[92:95]
	global_load_lds_dwordx4 v133, s[72:73]
	s_add_u32 m0, s76, 0xe000
	v_mfma_f32_16x16x32_bf16 v[112:115], v[220:223], v[236:239], v[112:115]
	global_load_lds_dwordx4 v134, s[72:73]
	v_mfma_f32_16x16x32_bf16 v[116:119], v[220:223], v[240:243], v[116:119]
	v_mfma_f32_16x16x32_bf16 v[120:123], v[224:227], v[236:239], v[120:123]
	v_mfma_f32_16x16x32_bf16 v[124:127], v[224:227], v[240:243], v[124:127]
	ds_read_b128 v[236:239], v128 offset:4096
	ds_read_b128 v[240:243], v128 offset:5120
	v_mfma_f32_16x16x32_bf16 v[32:35], v[188:191], v[244:247], v[32:35]
	s_add_u32 m0, s76, 0xf000
	v_mfma_f32_16x16x32_bf16 v[36:39], v[188:191], v[248:251], v[36:39]
	global_load_lds_dwordx4 v135, s[72:73]
	s_add_u32 m0, s76, 0x10000
	v_mfma_f32_16x16x32_bf16 v[40:43], v[192:195], v[244:247], v[40:43]
	global_load_lds_dwordx4 v132, s[74:75]
	s_add_u32 m0, s76, 0x11000
	v_mfma_f32_16x16x32_bf16 v[44:47], v[192:195], v[248:251], v[44:47]
	global_load_lds_dwordx4 v133, s[74:75]
	s_add_u32 s72, s72, 0x202000
	s_addc_u32 s73, s73, 0
	v_mfma_f32_16x16x32_bf16 v[96:99], v[220:223], v[244:247], v[96:99]
	s_add_u32 s74, s74, 0x2c000
	s_addc_u32 s75, s75, 0
	v_mfma_f32_16x16x32_bf16 v[100:103], v[220:223], v[248:251], v[100:103]
	v_mfma_f32_16x16x32_bf16 v[104:107], v[224:227], v[244:247], v[104:107]
	v_mfma_f32_16x16x32_bf16 v[108:111], v[224:227], v[248:251], v[108:111]
	s_mov_b32 s77, 3
.Lgemm_p1_loop:
	s_waitcnt lgkmcnt(2)
	v_mfma_f32_16x16x32_bf16 v[64:67], v[172:175], v[228:231], v[64:67]
	ds_read_b128 v[244:247], v128 offset:8192
	v_mfma_f32_16x16x32_bf16 v[68:71], v[172:175], v[232:235], v[68:71]
	ds_read_b128 v[248:251], v128 offset:9216
	v_mfma_f32_16x16x32_bf16 v[72:75], v[176:179], v[228:231], v[72:75]
	v_mfma_f32_16x16x32_bf16 v[76:79], v[176:179], v[232:235], v[76:79]
	v_mfma_f32_16x16x32_bf16 v[48:51], v[180:183], v[228:231], v[48:51]
	v_mfma_f32_16x16x32_bf16 v[52:55], v[180:183], v[232:235], v[52:55]
	v_mfma_f32_16x16x32_bf16 v[56:59], v[184:187], v[228:231], v[56:59]
	v_mfma_f32_16x16x32_bf16 v[60:63], v[184:187], v[232:235], v[60:63]
	s_waitcnt lgkmcnt(2)
	v_mfma_f32_16x16x32_bf16 v[16:19], v[172:175], v[236:239], v[16:19]
	ds_read_b128 v[228:231], v128 offset:12288
	v_mfma_f32_16x16x32_bf16 v[20:23], v[172:175], v[240:243], v[20:23]
	ds_read_b128 v[232:235], v128 offset:13312
	v_mfma_f32_16x16x32_bf16 v[24:27], v[176:179], v[236:239], v[24:27]
	v_mfma_f32_16x16x32_bf16 v[28:31], v[176:179], v[240:243], v[28:31]
	v_mfma_f32_16x16x32_bf16 v[0:3], v[180:183], v[236:239], v[0:3]
	v_mfma_f32_16x16x32_bf16 v[4:7], v[180:183], v[240:243], v[4:7]
	v_mfma_f32_16x16x32_bf16 v[8:11], v[184:187], v[236:239], v[8:11]
	v_mfma_f32_16x16x32_bf16 v[12:15], v[184:187], v[240:243], v[12:15]
	s_waitcnt lgkmcnt(0)
	s_waitcnt vmcnt(6)
	s_barrier
	ds_read_b128 v[188:191], v130 offset:24576
	ds_read_b128 v[192:195], v130 offset:25600
	v_mfma_f32_16x16x32_bf16 v[80:83], v[172:175], v[244:247], v[80:83]
	ds_read_b128 v[220:223], v130 offset:26624
	ds_read_b128 v[224:227], v130 offset:27648
	v_mfma_f32_16x16x32_bf16 v[84:87], v[172:175], v[248:251], v[84:87]
	ds_read_b128 v[236:239], v128 offset:24576
	ds_read_b128 v[240:243], v128 offset:25600
	s_add_u32 m0, s76, 0x0
	v_mfma_f32_16x16x32_bf16 v[88:91], v[176:179], v[244:247], v[88:91]
	global_load_lds_dwordx4 v132, s[72:73]
	s_add_u32 m0, s76, 0x1000
	v_mfma_f32_16x16x32_bf16 v[92:95], v[176:179], v[248:251], v[92:95]
	global_load_lds_dwordx4 v133, s[72:73]
	s_add_u32 m0, s76, 0x2000
	v_mfma_f32_16x16x32_bf16 v[112:115], v[180:183], v[244:247], v[112:115]
	global_load_lds_dwordx4 v134, s[72:73]
	v_mfma_f32_16x16x32_bf16 v[116:119], v[180:183], v[248:251], v[116:119]
	v_mfma_f32_16x16x32_bf16 v[120:123], v[184:187], v[244:247], v[120:123]
	v_mfma_f32_16x16x32_bf16 v[124:127], v[184:187], v[248:251], v[124:127]
	ds_read_b128 v[244:247], v128 offset:28672
	ds_read_b128 v[248:251], v128 offset:29696
	v_mfma_f32_16x16x32_bf16 v[32:35], v[172:175], v[228:231], v[32:35]
	s_add_u32 m0, s76, 0x3000
	v_mfma_f32_16x16x32_bf16 v[36:39], v[172:175], v[232:235], v[36:39]
	global_load_lds_dwordx4 v135, s[72:73]
	s_add_u32 m0, s76, 0x4000
	v_mfma_f32_16x16x32_bf16 v[40:43], v[176:179], v[228:231], v[40:43]
	global_load_lds_dwordx4 v132, s[74:75]
	s_add_u32 m0, s76, 0x5000
	v_mfma_f32_16x16x32_bf16 v[44:47], v[176:179], v[232:235], v[44:47]
	global_load_lds_dwordx4 v133, s[74:75]
	s_add_u32 s72, s72, 0x202000
	s_addc_u32 s73, s73, 0
	v_mfma_f32_16x16x32_bf16 v[96:99], v[180:183], v[228:231], v[96:99]
	s_add_u32 s74, s74, 0x2c000
	s_addc_u32 s75, s75, 0
	v_mfma_f32_16x16x32_bf16 v[100:103], v[180:183], v[232:235], v[100:103]
	v_mfma_f32_16x16x32_bf16 v[104:107], v[184:187], v[228:231], v[104:107]
	v_mfma_f32_16x16x32_bf16 v[108:111], v[184:187], v[232:235], v[108:111]
	s_waitcnt lgkmcnt(2)
	v_mfma_f32_16x16x32_bf16 v[64:67], v[188:191], v[236:239], v[64:67]
	ds_read_b128 v[228:231], v128 offset:32768
	v_mfma_f32_16x16x32_bf16 v[68:71], v[188:191], v[240:243], v[68:71]
	ds_read_b128 v[232:235], v128 offset:33792
	v_mfma_f32_16x16x32_bf16 v[72:75], v[192:195], v[236:239], v[72:75]
	v_mfma_f32_16x16x32_bf16 v[76:79], v[192:195], v[240:243], v[76:79]
	v_mfma_f32_16x16x32_bf16 v[48:51], v[220:223], v[236:239], v[48:51]
	v_mfma_f32_16x16x32_bf16 v[52:55], v[220:223], v[240:243], v[52:55]
	v_mfma_f32_16x16x32_bf16 v[56:59], v[224:227], v[236:239], v[56:59]
	v_mfma_f32_16x16x32_bf16 v[60:63], v[224:227], v[240:243], v[60:63]
	s_waitcnt lgkmcnt(2)
	v_mfma_f32_16x16x32_bf16 v[16:19], v[188:191], v[244:247], v[16:19]
	ds_read_b128 v[236:239], v128 offset:36864
	v_mfma_f32_16x16x32_bf16 v[20:23], v[188:191], v[248:251], v[20:23]
	ds_read_b128 v[240:243], v128 offset:37888
	v_mfma_f32_16x16x32_bf16 v[24:27], v[192:195], v[244:247], v[24:27]
	v_mfma_f32_16x16x32_bf16 v[28:31], v[192:195], v[248:251], v[28:31]
	v_mfma_f32_16x16x32_bf16 v[0:3], v[220:223], v[244:247], v[0:3]
	v_mfma_f32_16x16x32_bf16 v[4:7], v[220:223], v[248:251], v[4:7]
	v_mfma_f32_16x16x32_bf16 v[8:11], v[224:227], v[244:247], v[8:11]
	v_mfma_f32_16x16x32_bf16 v[12:15], v[224:227], v[248:251], v[12:15]
	s_waitcnt lgkmcnt(0)
	s_waitcnt vmcnt(6)
	s_barrier
	ds_read_b128 v[172:175], v130 offset:49152
	ds_read_b128 v[176:179], v130 offset:50176
	v_mfma_f32_16x16x32_bf16 v[80:83], v[188:191], v[228:231], v[80:83]
	ds_read_b128 v[180:183], v130 offset:51200
	ds_read_b128 v[184:187], v130 offset:52224
	v_mfma_f32_16x16x32_bf16 v[84:87], v[188:191], v[232:235], v[84:87]
	ds_read_b128 v[244:247], v128 offset:49152
	ds_read_b128 v[248:251], v128 offset:50176
	s_add_u32 m0, s76, 0x6000
	v_mfma_f32_16x16x32_bf16 v[88:91], v[192:195], v[228:231], v[88:91]
	global_load_lds_dwordx4 v132, s[72:73]
	s_add_u32 m0, s76, 0x7000
	v_mfma_f32_16x16x32_bf16 v[92:95], v[192:195], v[232:235], v[92:95]
	global_load_lds_dwordx4 v133, s[72:73]
	s_add_u32 m0, s76, 0x8000
	v_mfma_f32_16x16x32_bf16 v[112:115], v[220:223], v[228:231], v[112:115]
	global_load_lds_dwordx4 v134, s[72:73]
	v_mfma_f32_16x16x32_bf16 v[116:119], v[220:223], v[232:235], v[116:119]
	v_mfma_f32_16x16x32_bf16 v[120:123], v[224:227], v[228:231], v[120:123]
	v_mfma_f32_16x16x32_bf16 v[124:127], v[224:227], v[232:235], v[124:127]
	ds_read_b128 v[228:231], v128 offset:53248
	ds_read_b128 v[232:235], v128 offset:54272
	v_mfma_f32_16x16x32_bf16 v[32:35], v[188:191], v[236:239], v[32:35]
	s_add_u32 m0, s76, 0x9000
	v_mfma_f32_16x16x32_bf16 v[36:39], v[188:191], v[240:243], v[36:39]
	global_load_lds_dwordx4 v135, s[72:73]
	s_add_u32 m0, s76, 0xa000
	v_mfma_f32_16x16x32_bf16 v[40:43], v[192:195], v[236:239], v[40:43]
	global_load_lds_dwordx4 v132, s[74:75]
	s_add_u32 m0, s76, 0xb000
	v_mfma_f32_16x16x32_bf16 v[44:47], v[192:195], v[240:243], v[44:47]
	global_load_lds_dwordx4 v133, s[74:75]
	s_add_u32 s72, s72, 0x202000
	s_addc_u32 s73, s73, 0
	v_mfma_f32_16x16x32_bf16 v[96:99], v[220:223], v[236:239], v[96:99]
	s_add_u32 s74, s74, 0x2c000
	s_addc_u32 s75, s75, 0
	v_mfma_f32_16x16x32_bf16 v[100:103], v[220:223], v[240:243], v[100:103]
	v_mfma_f32_16x16x32_bf16 v[104:107], v[224:227], v[236:239], v[104:107]
	v_mfma_f32_16x16x32_bf16 v[108:111], v[224:227], v[240:243], v[108:111]
	s_waitcnt lgkmcnt(2)
	v_mfma_f32_16x16x32_bf16 v[64:67], v[172:175], v[244:247], v[64:67]
	ds_read_b128 v[236:239], v128 offset:57344
	v_mfma_f32_16x16x32_bf16 v[68:71], v[172:175], v[248:251], v[68:71]
	ds_read_b128 v[240:243], v128 offset:58368
	v_mfma_f32_16x16x32_bf16 v[72:75], v[176:179], v[244:247], v[72:75]
	v_mfma_f32_16x16x32_bf16 v[76:79], v[176:179], v[248:251], v[76:79]
	v_mfma_f32_16x16x32_bf16 v[48:51], v[180:183], v[244:247], v[48:51]
	v_mfma_f32_16x16x32_bf16 v[52:55], v[180:183], v[248:251], v[52:55]
	v_mfma_f32_16x16x32_bf16 v[56:59], v[184:187], v[244:247], v[56:59]
	v_mfma_f32_16x16x32_bf16 v[60:63], v[184:187], v[248:251], v[60:63]
	s_waitcnt lgkmcnt(2)
	v_mfma_f32_16x16x32_bf16 v[16:19], v[172:175], v[228:231], v[16:19]
	ds_read_b128 v[244:247], v128 offset:61440
	v_mfma_f32_16x16x32_bf16 v[20:23], v[172:175], v[232:235], v[20:23]
	ds_read_b128 v[248:251], v128 offset:62464
	v_mfma_f32_16x16x32_bf16 v[24:27], v[176:179], v[228:231], v[24:27]
	v_mfma_f32_16x16x32_bf16 v[28:31], v[176:179], v[232:235], v[28:31]
	v_mfma_f32_16x16x32_bf16 v[0:3], v[180:183], v[228:231], v[0:3]
	v_mfma_f32_16x16x32_bf16 v[4:7], v[180:183], v[232:235], v[4:7]
	v_mfma_f32_16x16x32_bf16 v[8:11], v[184:187], v[228:231], v[8:11]
	v_mfma_f32_16x16x32_bf16 v[12:15], v[184:187], v[232:235], v[12:15]
	s_waitcnt lgkmcnt(0)
	s_waitcnt vmcnt(6)
	s_barrier
	ds_read_b128 v[188:191], v130
	ds_read_b128 v[192:195], v130 offset:1024
	v_mfma_f32_16x16x32_bf16 v[80:83], v[172:175], v[236:239], v[80:83]
	ds_read_b128 v[220:223], v130 offset:2048
	ds_read_b128 v[224:227], v130 offset:3072
	v_mfma_f32_16x16x32_bf16 v[84:87], v[172:175], v[240:243], v[84:87]
	ds_read_b128 v[228:231], v128
	ds_read_b128 v[232:235], v128 offset:1024
	s_add_u32 m0, s76, 0xc000
	v_mfma_f32_16x16x32_bf16 v[88:91], v[176:179], v[236:239], v[88:91]
	global_load_lds_dwordx4 v132, s[72:73]
	s_add_u32 m0, s76, 0xd000
	v_mfma_f32_16x16x32_bf16 v[92:95], v[176:179], v[240:243], v[92:95]
	global_load_lds_dwordx4 v133, s[72:73]
	s_add_u32 m0, s76, 0xe000
	v_mfma_f32_16x16x32_bf16 v[112:115], v[180:183], v[236:239], v[112:115]
	global_load_lds_dwordx4 v134, s[72:73]
	v_mfma_f32_16x16x32_bf16 v[116:119], v[180:183], v[240:243], v[116:119]
	v_mfma_f32_16x16x32_bf16 v[120:123], v[184:187], v[236:239], v[120:123]
	v_mfma_f32_16x16x32_bf16 v[124:127], v[184:187], v[240:243], v[124:127]
	ds_read_b128 v[236:239], v128 offset:4096
	ds_read_b128 v[240:243], v128 offset:5120
	v_mfma_f32_16x16x32_bf16 v[32:35], v[172:175], v[244:247], v[32:35]
	s_add_u32 m0, s76, 0xf000
	v_mfma_f32_16x16x32_bf16 v[36:39], v[172:175], v[248:251], v[36:39]
	global_load_lds_dwordx4 v135, s[72:73]
	s_add_u32 m0, s76, 0x10000
	v_mfma_f32_16x16x32_bf16 v[40:43], v[176:179], v[244:247], v[40:43]
	global_load_lds_dwordx4 v132, s[74:75]
	s_add_u32 m0, s76, 0x11000
	v_mfma_f32_16x16x32_bf16 v[44:47], v[176:179], v[248:251], v[44:47]
	global_load_lds_dwordx4 v133, s[74:75]
	s_add_u32 s72, s72, 0x202000
	s_addc_u32 s73, s73, 0
	v_mfma_f32_16x16x32_bf16 v[96:99], v[180:183], v[244:247], v[96:99]
	s_add_u32 s74, s74, 0x2c000
	s_addc_u32 s75, s75, 0
	v_mfma_f32_16x16x32_bf16 v[100:103], v[180:183], v[248:251], v[100:103]
	v_mfma_f32_16x16x32_bf16 v[104:107], v[184:187], v[244:247], v[104:107]
	v_mfma_f32_16x16x32_bf16 v[108:111], v[184:187], v[248:251], v[108:111]
	s_waitcnt lgkmcnt(2)
	v_mfma_f32_16x16x32_bf16 v[64:67], v[188:191], v[228:231], v[64:67]
	ds_read_b128 v[244:247], v128 offset:8192
	v_mfma_f32_16x16x32_bf16 v[68:71], v[188:191], v[232:235], v[68:71]
	ds_read_b128 v[248:251], v128 offset:9216
	v_mfma_f32_16x16x32_bf16 v[72:75], v[192:195], v[228:231], v[72:75]
	v_mfma_f32_16x16x32_bf16 v[76:79], v[192:195], v[232:235], v[76:79]
	v_mfma_f32_16x16x32_bf16 v[48:51], v[220:223], v[228:231], v[48:51]
	v_mfma_f32_16x16x32_bf16 v[52:55], v[220:223], v[232:235], v[52:55]
	v_mfma_f32_16x16x32_bf16 v[56:59], v[224:227], v[228:231], v[56:59]
	v_mfma_f32_16x16x32_bf16 v[60:63], v[224:227], v[232:235], v[60:63]
	s_waitcnt lgkmcnt(2)
	v_mfma_f32_16x16x32_bf16 v[16:19], v[188:191], v[236:239], v[16:19]
	ds_read_b128 v[228:231], v128 offset:12288
	v_mfma_f32_16x16x32_bf16 v[20:23], v[188:191], v[240:243], v[20:23]
	ds_read_b128 v[232:235], v128 offset:13312
	v_mfma_f32_16x16x32_bf16 v[24:27], v[192:195], v[236:239], v[24:27]
	v_mfma_f32_16x16x32_bf16 v[28:31], v[192:195], v[240:243], v[28:31]
	v_mfma_f32_16x16x32_bf16 v[0:3], v[220:223], v[236:239], v[0:3]
	v_mfma_f32_16x16x32_bf16 v[4:7], v[220:223], v[240:243], v[4:7]
	v_mfma_f32_16x16x32_bf16 v[8:11], v[224:227], v[236:239], v[8:11]
	v_mfma_f32_16x16x32_bf16 v[12:15], v[224:227], v[240:243], v[12:15]
	s_waitcnt lgkmcnt(0)
	s_waitcnt vmcnt(6)
	s_barrier
	ds_read_b128 v[172:175], v130 offset:24576
	ds_read_b128 v[176:179], v130 offset:25600
	v_mfma_f32_16x16x32_bf16 v[80:83], v[188:191], v[244:247], v[80:83]
	ds_read_b128 v[180:183], v130 offset:26624
	ds_read_b128 v[184:187], v130 offset:27648
	v_mfma_f32_16x16x32_bf16 v[84:87], v[188:191], v[248:251], v[84:87]
	ds_read_b128 v[236:239], v128 offset:24576
	ds_read_b128 v[240:243], v128 offset:25600
	s_add_u32 m0, s76, 0x0
	v_mfma_f32_16x16x32_bf16 v[88:91], v[192:195], v[244:247], v[88:91]
	global_load_lds_dwordx4 v132, s[72:73]
	s_add_u32 m0, s76, 0x1000
	v_mfma_f32_16x16x32_bf16 v[92:95], v[192:195], v[248:251], v[92:95]
	global_load_lds_dwordx4 v133, s[72:73]
	s_add_u32 m0, s76, 0x2000
	v_mfma_f32_16x16x32_bf16 v[112:115], v[220:223], v[244:247], v[112:115]
	global_load_lds_dwordx4 v134, s[72:73]
	v_mfma_f32_16x16x32_bf16 v[116:119], v[220:223], v[248:251], v[116:119]
	v_mfma_f32_16x16x32_bf16 v[120:123], v[224:227], v[244:247], v[120:123]
	v_mfma_f32_16x16x32_bf16 v[124:127], v[224:227], v[248:251], v[124:127]
	ds_read_b128 v[244:247], v128 offset:28672
	ds_read_b128 v[248:251], v128 offset:29696
	v_mfma_f32_16x16x32_bf16 v[32:35], v[188:191], v[228:231], v[32:35]
	s_add_u32 m0, s76, 0x3000
	v_mfma_f32_16x16x32_bf16 v[36:39], v[188:191], v[232:235], v[36:39]
	global_load_lds_dwordx4 v135, s[72:73]
	s_add_u32 m0, s76, 0x4000
	v_mfma_f32_16x16x32_bf16 v[40:43], v[192:195], v[228:231], v[40:43]
	global_load_lds_dwordx4 v132, s[74:75]
	s_add_u32 m0, s76, 0x5000
	v_mfma_f32_16x16x32_bf16 v[44:47], v[192:195], v[232:235], v[44:47]
	global_load_lds_dwordx4 v133, s[74:75]
	s_add_u32 s72, s72, 0x202000
	s_addc_u32 s73, s73, 0
	v_mfma_f32_16x16x32_bf16 v[96:99], v[220:223], v[228:231], v[96:99]
	s_add_u32 s74, s74, 0x2c000
	s_addc_u32 s75, s75, 0
	v_mfma_f32_16x16x32_bf16 v[100:103], v[220:223], v[232:235], v[100:103]
	v_mfma_f32_16x16x32_bf16 v[104:107], v[224:227], v[228:231], v[104:107]
	v_mfma_f32_16x16x32_bf16 v[108:111], v[224:227], v[232:235], v[108:111]
	s_waitcnt lgkmcnt(2)
	v_mfma_f32_16x16x32_bf16 v[64:67], v[172:175], v[236:239], v[64:67]
	ds_read_b128 v[228:231], v128 offset:32768
	v_mfma_f32_16x16x32_bf16 v[68:71], v[172:175], v[240:243], v[68:71]
	ds_read_b128 v[232:235], v128 offset:33792
	v_mfma_f32_16x16x32_bf16 v[72:75], v[176:179], v[236:239], v[72:75]
	v_mfma_f32_16x16x32_bf16 v[76:79], v[176:179], v[240:243], v[76:79]
	v_mfma_f32_16x16x32_bf16 v[48:51], v[180:183], v[236:239], v[48:51]
	v_mfma_f32_16x16x32_bf16 v[52:55], v[180:183], v[240:243], v[52:55]
	v_mfma_f32_16x16x32_bf16 v[56:59], v[184:187], v[236:239], v[56:59]
	v_mfma_f32_16x16x32_bf16 v[60:63], v[184:187], v[240:243], v[60:63]
	s_waitcnt lgkmcnt(2)
	v_mfma_f32_16x16x32_bf16 v[16:19], v[172:175], v[244:247], v[16:19]
	ds_read_b128 v[236:239], v128 offset:36864
	v_mfma_f32_16x16x32_bf16 v[20:23], v[172:175], v[248:251], v[20:23]
	ds_read_b128 v[240:243], v128 offset:37888
	v_mfma_f32_16x16x32_bf16 v[24:27], v[176:179], v[244:247], v[24:27]
	v_mfma_f32_16x16x32_bf16 v[28:31], v[176:179], v[248:251], v[28:31]
	v_mfma_f32_16x16x32_bf16 v[0:3], v[180:183], v[244:247], v[0:3]
	v_mfma_f32_16x16x32_bf16 v[4:7], v[180:183], v[248:251], v[4:7]
	v_mfma_f32_16x16x32_bf16 v[8:11], v[184:187], v[244:247], v[8:11]
	v_mfma_f32_16x16x32_bf16 v[12:15], v[184:187], v[248:251], v[12:15]
	s_waitcnt lgkmcnt(0)
	s_waitcnt vmcnt(6)
	s_barrier
	ds_read_b128 v[188:191], v130 offset:49152
	ds_read_b128 v[192:195], v130 offset:50176
	v_mfma_f32_16x16x32_bf16 v[80:83], v[172:175], v[228:231], v[80:83]
	ds_read_b128 v[220:223], v130 offset:51200
	ds_read_b128 v[224:227], v130 offset:52224
	v_mfma_f32_16x16x32_bf16 v[84:87], v[172:175], v[232:235], v[84:87]
	ds_read_b128 v[244:247], v128 offset:49152
	ds_read_b128 v[248:251], v128 offset:50176
	s_add_u32 m0, s76, 0x6000
	v_mfma_f32_16x16x32_bf16 v[88:91], v[176:179], v[228:231], v[88:91]
	global_load_lds_dwordx4 v132, s[72:73]
	s_add_u32 m0, s76, 0x7000
	v_mfma_f32_16x16x32_bf16 v[92:95], v[176:179], v[232:235], v[92:95]
	global_load_lds_dwordx4 v133, s[72:73]
	s_add_u32 m0, s76, 0x8000
	v_mfma_f32_16x16x32_bf16 v[112:115], v[180:183], v[228:231], v[112:115]
	global_load_lds_dwordx4 v134, s[72:73]
	v_mfma_f32_16x16x32_bf16 v[116:119], v[180:183], v[232:235], v[116:119]
	v_mfma_f32_16x16x32_bf16 v[120:123], v[184:187], v[228:231], v[120:123]
	v_mfma_f32_16x16x32_bf16 v[124:127], v[184:187], v[232:235], v[124:127]
	ds_read_b128 v[228:231], v128 offset:53248
	ds_read_b128 v[232:235], v128 offset:54272
	v_mfma_f32_16x16x32_bf16 v[32:35], v[172:175], v[236:239], v[32:35]
	s_add_u32 m0, s76, 0x9000
	v_mfma_f32_16x16x32_bf16 v[36:39], v[172:175], v[240:243], v[36:39]
	global_load_lds_dwordx4 v135, s[72:73]
	s_add_u32 m0, s76, 0xa000
	v_mfma_f32_16x16x32_bf16 v[40:43], v[176:179], v[236:239], v[40:43]
	global_load_lds_dwordx4 v132, s[74:75]
	s_add_u32 m0, s76, 0xb000
	v_mfma_f32_16x16x32_bf16 v[44:47], v[176:179], v[240:243], v[44:47]
	global_load_lds_dwordx4 v133, s[74:75]
	s_add_u32 s72, s72, 0x202000
	s_addc_u32 s73, s73, 0
	v_mfma_f32_16x16x32_bf16 v[96:99], v[180:183], v[236:239], v[96:99]
	s_add_u32 s74, s74, 0x2c000
	s_addc_u32 s75, s75, 0
	v_mfma_f32_16x16x32_bf16 v[100:103], v[180:183], v[240:243], v[100:103]
	v_mfma_f32_16x16x32_bf16 v[104:107], v[184:187], v[236:239], v[104:107]
	v_mfma_f32_16x16x32_bf16 v[108:111], v[184:187], v[240:243], v[108:111]
	s_waitcnt lgkmcnt(2)
	v_mfma_f32_16x16x32_bf16 v[64:67], v[188:191], v[244:247], v[64:67]
	ds_read_b128 v[236:239], v128 offset:57344
	v_mfma_f32_16x16x32_bf16 v[68:71], v[188:191], v[248:251], v[68:71]
	ds_read_b128 v[240:243], v128 offset:58368
	v_mfma_f32_16x16x32_bf16 v[72:75], v[192:195], v[244:247], v[72:75]
	v_mfma_f32_16x16x32_bf16 v[76:79], v[192:195], v[248:251], v[76:79]
	v_mfma_f32_16x16x32_bf16 v[48:51], v[220:223], v[244:247], v[48:51]
	v_mfma_f32_16x16x32_bf16 v[52:55], v[220:223], v[248:251], v[52:55]
	v_mfma_f32_16x16x32_bf16 v[56:59], v[224:227], v[244:247], v[56:59]
	v_mfma_f32_16x16x32_bf16 v[60:63], v[224:227], v[248:251], v[60:63]
	s_waitcnt lgkmcnt(2)
	v_mfma_f32_16x16x32_bf16 v[16:19], v[188:191], v[228:231], v[16:19]
	ds_read_b128 v[244:247], v128 offset:61440
	v_mfma_f32_16x16x32_bf16 v[20:23], v[188:191], v[232:235], v[20:23]
	ds_read_b128 v[248:251], v128 offset:62464
	v_mfma_f32_16x16x32_bf16 v[24:27], v[192:195], v[228:231], v[24:27]
	v_mfma_f32_16x16x32_bf16 v[28:31], v[192:195], v[232:235], v[28:31]
	v_mfma_f32_16x16x32_bf16 v[0:3], v[220:223], v[228:231], v[0:3]
	v_mfma_f32_16x16x32_bf16 v[4:7], v[220:223], v[232:235], v[4:7]
	v_mfma_f32_16x16x32_bf16 v[8:11], v[224:227], v[228:231], v[8:11]
	v_mfma_f32_16x16x32_bf16 v[12:15], v[224:227], v[232:235], v[12:15]
	s_waitcnt lgkmcnt(0)
	s_waitcnt vmcnt(6)
	s_barrier
	ds_read_b128 v[172:175], v130
	ds_read_b128 v[176:179], v130 offset:1024
	v_mfma_f32_16x16x32_bf16 v[80:83], v[188:191], v[236:239], v[80:83]
	ds_read_b128 v[180:183], v130 offset:2048
	ds_read_b128 v[184:187], v130 offset:3072
	v_mfma_f32_16x16x32_bf16 v[84:87], v[188:191], v[240:243], v[84:87]
	ds_read_b128 v[228:231], v128
	ds_read_b128 v[232:235], v128 offset:1024
	s_add_u32 m0, s76, 0xc000
	v_mfma_f32_16x16x32_bf16 v[88:91], v[192:195], v[236:239], v[88:91]
	global_load_lds_dwordx4 v132, s[72:73]
	s_add_u32 m0, s76, 0xd000
	v_mfma_f32_16x16x32_bf16 v[92:95], v[192:195], v[240:243], v[92:95]
	global_load_lds_dwordx4 v133, s[72:73]
	s_add_u32 m0, s76, 0xe000
	v_mfma_f32_16x16x32_bf16 v[112:115], v[220:223], v[236:239], v[112:115]
	global_load_lds_dwordx4 v134, s[72:73]
	v_mfma_f32_16x16x32_bf16 v[116:119], v[220:223], v[240:243], v[116:119]
	v_mfma_f32_16x16x32_bf16 v[120:123], v[224:227], v[236:239], v[120:123]
	v_mfma_f32_16x16x32_bf16 v[124:127], v[224:227], v[240:243], v[124:127]
	ds_read_b128 v[236:239], v128 offset:4096
	ds_read_b128 v[240:243], v128 offset:5120
	v_mfma_f32_16x16x32_bf16 v[32:35], v[188:191], v[244:247], v[32:35]
	s_add_u32 m0, s76, 0xf000
	v_mfma_f32_16x16x32_bf16 v[36:39], v[188:191], v[248:251], v[36:39]
	global_load_lds_dwordx4 v135, s[72:73]
	s_add_u32 m0, s76, 0x10000
	v_mfma_f32_16x16x32_bf16 v[40:43], v[192:195], v[244:247], v[40:43]
	global_load_lds_dwordx4 v132, s[74:75]
	s_add_u32 m0, s76, 0x11000
	v_mfma_f32_16x16x32_bf16 v[44:47], v[192:195], v[248:251], v[44:47]
	global_load_lds_dwordx4 v133, s[74:75]
	s_add_u32 s72, s72, 0x202000
	s_addc_u32 s73, s73, 0
	v_mfma_f32_16x16x32_bf16 v[96:99], v[220:223], v[244:247], v[96:99]
	s_add_u32 s74, s74, 0x2c000
	s_addc_u32 s75, s75, 0
	v_mfma_f32_16x16x32_bf16 v[100:103], v[220:223], v[248:251], v[100:103]
	v_mfma_f32_16x16x32_bf16 v[104:107], v[224:227], v[244:247], v[104:107]
	v_mfma_f32_16x16x32_bf16 v[108:111], v[224:227], v[248:251], v[108:111]
	s_sub_i32 s77, s77, 1
	s_cmp_lg_u32 s77, 0
	s_cbranch_scc1 .Lgemm_p1_loop
	s_waitcnt lgkmcnt(2)
	v_mfma_f32_16x16x32_bf16 v[64:67], v[172:175], v[228:231], v[64:67]
	ds_read_b128 v[244:247], v128 offset:8192
	v_mfma_f32_16x16x32_bf16 v[68:71], v[172:175], v[232:235], v[68:71]
	ds_read_b128 v[248:251], v128 offset:9216
	v_mfma_f32_16x16x32_bf16 v[72:75], v[176:179], v[228:231], v[72:75]
	v_mfma_f32_16x16x32_bf16 v[76:79], v[176:179], v[232:235], v[76:79]
	v_mfma_f32_16x16x32_bf16 v[48:51], v[180:183], v[228:231], v[48:51]
	v_mfma_f32_16x16x32_bf16 v[52:55], v[180:183], v[232:235], v[52:55]
	v_mfma_f32_16x16x32_bf16 v[56:59], v[184:187], v[228:231], v[56:59]
	v_mfma_f32_16x16x32_bf16 v[60:63], v[184:187], v[232:235], v[60:63]
	s_waitcnt lgkmcnt(2)
	v_mfma_f32_16x16x32_bf16 v[16:19], v[172:175], v[236:239], v[16:19]
	ds_read_b128 v[228:231], v128 offset:12288
	v_mfma_f32_16x16x32_bf16 v[20:23], v[172:175], v[240:243], v[20:23]
	ds_read_b128 v[232:235], v128 offset:13312
	v_mfma_f32_16x16x32_bf16 v[24:27], v[176:179], v[236:239], v[24:27]
	v_mfma_f32_16x16x32_bf16 v[28:31], v[176:179], v[240:243], v[28:31]
	v_mfma_f32_16x16x32_bf16 v[0:3], v[180:183], v[236:239], v[0:3]
	v_mfma_f32_16x16x32_bf16 v[4:7], v[180:183], v[240:243], v[4:7]
	v_mfma_f32_16x16x32_bf16 v[8:11], v[184:187], v[236:239], v[8:11]
	v_mfma_f32_16x16x32_bf16 v[12:15], v[184:187], v[240:243], v[12:15]
	s_waitcnt lgkmcnt(0)
	s_waitcnt vmcnt(6)
	s_barrier
	ds_read_b128 v[188:191], v130 offset:24576
	ds_read_b128 v[192:195], v130 offset:25600
	v_mfma_f32_16x16x32_bf16 v[80:83], v[172:175], v[244:247], v[80:83]
	ds_read_b128 v[220:223], v130 offset:26624
	ds_read_b128 v[224:227], v130 offset:27648
	v_mfma_f32_16x16x32_bf16 v[84:87], v[172:175], v[248:251], v[84:87]
	ds_read_b128 v[236:239], v128 offset:24576
	ds_read_b128 v[240:243], v128 offset:25600
	s_add_u32 m0, s76, 0x0
	v_mfma_f32_16x16x32_bf16 v[88:91], v[176:179], v[244:247], v[88:91]
	global_load_lds_dwordx4 v132, s[72:73]
	s_add_u32 m0, s76, 0x1000
	v_mfma_f32_16x16x32_bf16 v[92:95], v[176:179], v[248:251], v[92:95]
	global_load_lds_dwordx4 v133, s[72:73]
	s_add_u32 m0, s76, 0x2000
	v_mfma_f32_16x16x32_bf16 v[112:115], v[180:183], v[244:247], v[112:115]
	global_load_lds_dwordx4 v134, s[72:73]
	v_mfma_f32_16x16x32_bf16 v[116:119], v[180:183], v[248:251], v[116:119]
	v_mfma_f32_16x16x32_bf16 v[120:123], v[184:187], v[244:247], v[120:123]
	v_mfma_f32_16x16x32_bf16 v[124:127], v[184:187], v[248:251], v[124:127]
	ds_read_b128 v[244:247], v128 offset:28672
	ds_read_b128 v[248:251], v128 offset:29696
	v_mfma_f32_16x16x32_bf16 v[32:35], v[172:175], v[228:231], v[32:35]
	s_add_u32 m0, s76, 0x3000
	v_mfma_f32_16x16x32_bf16 v[36:39], v[172:175], v[232:235], v[36:39]
	global_load_lds_dwordx4 v135, s[72:73]
	s_add_u32 m0, s76, 0x4000
	v_mfma_f32_16x16x32_bf16 v[40:43], v[176:179], v[228:231], v[40:43]
	global_load_lds_dwordx4 v132, s[74:75]
	s_add_u32 m0, s76, 0x5000
	v_mfma_f32_16x16x32_bf16 v[44:47], v[176:179], v[232:235], v[44:47]
	global_load_lds_dwordx4 v133, s[74:75]
	s_add_u32 s72, s72, 0x202000
	s_addc_u32 s73, s73, 0
	v_mfma_f32_16x16x32_bf16 v[96:99], v[180:183], v[228:231], v[96:99]
	s_add_u32 s74, s74, 0x2c000
	s_addc_u32 s75, s75, 0
	v_mfma_f32_16x16x32_bf16 v[100:103], v[180:183], v[232:235], v[100:103]
	v_mfma_f32_16x16x32_bf16 v[104:107], v[184:187], v[228:231], v[104:107]
	v_mfma_f32_16x16x32_bf16 v[108:111], v[184:187], v[232:235], v[108:111]
	s_waitcnt lgkmcnt(2)
	v_mfma_f32_16x16x32_bf16 v[64:67], v[188:191], v[236:239], v[64:67]
	ds_read_b128 v[228:231], v128 offset:32768
	v_mfma_f32_16x16x32_bf16 v[68:71], v[188:191], v[240:243], v[68:71]
	ds_read_b128 v[232:235], v128 offset:33792
	v_mfma_f32_16x16x32_bf16 v[72:75], v[192:195], v[236:239], v[72:75]
	v_mfma_f32_16x16x32_bf16 v[76:79], v[192:195], v[240:243], v[76:79]
	v_mfma_f32_16x16x32_bf16 v[48:51], v[220:223], v[236:239], v[48:51]
	v_mfma_f32_16x16x32_bf16 v[52:55], v[220:223], v[240:243], v[52:55]
	v_mfma_f32_16x16x32_bf16 v[56:59], v[224:227], v[236:239], v[56:59]
	v_mfma_f32_16x16x32_bf16 v[60:63], v[224:227], v[240:243], v[60:63]
	s_waitcnt lgkmcnt(2)
	v_mfma_f32_16x16x32_bf16 v[16:19], v[188:191], v[244:247], v[16:19]
	ds_read_b128 v[236:239], v128 offset:36864
	v_mfma_f32_16x16x32_bf16 v[20:23], v[188:191], v[248:251], v[20:23]
	ds_read_b128 v[240:243], v128 offset:37888
	v_mfma_f32_16x16x32_bf16 v[24:27], v[192:195], v[244:247], v[24:27]
	v_mfma_f32_16x16x32_bf16 v[28:31], v[192:195], v[248:251], v[28:31]
	v_mfma_f32_16x16x32_bf16 v[0:3], v[220:223], v[244:247], v[0:3]
	v_mfma_f32_16x16x32_bf16 v[4:7], v[220:223], v[248:251], v[4:7]
	v_mfma_f32_16x16x32_bf16 v[8:11], v[224:227], v[244:247], v[8:11]
	v_mfma_f32_16x16x32_bf16 v[12:15], v[224:227], v[248:251], v[12:15]
	s_waitcnt lgkmcnt(0)
	s_waitcnt vmcnt(6)
	s_barrier
	ds_read_b128 v[172:175], v130 offset:49152
	ds_read_b128 v[176:179], v130 offset:50176
	v_mfma_f32_16x16x32_bf16 v[80:83], v[188:191], v[228:231], v[80:83]
	ds_read_b128 v[180:183], v130 offset:51200
	ds_read_b128 v[184:187], v130 offset:52224
	v_mfma_f32_16x16x32_bf16 v[84:87], v[188:191], v[232:235], v[84:87]
	ds_read_b128 v[244:247], v128 offset:49152
	ds_read_b128 v[248:251], v128 offset:50176
	s_add_u32 m0, s76, 0x6000
	v_mfma_f32_16x16x32_bf16 v[88:91], v[192:195], v[228:231], v[88:91]
	global_load_lds_dwordx4 v132, s[72:73]
	s_add_u32 m0, s76, 0x7000
	v_mfma_f32_16x16x32_bf16 v[92:95], v[192:195], v[232:235], v[92:95]
	global_load_lds_dwordx4 v133, s[72:73]
	s_add_u32 m0, s76, 0x8000
	v_mfma_f32_16x16x32_bf16 v[112:115], v[220:223], v[228:231], v[112:115]
	global_load_lds_dwordx4 v134, s[72:73]
	v_mfma_f32_16x16x32_bf16 v[116:119], v[220:223], v[232:235], v[116:119]
	v_mfma_f32_16x16x32_bf16 v[120:123], v[224:227], v[228:231], v[120:123]
	v_mfma_f32_16x16x32_bf16 v[124:127], v[224:227], v[232:235], v[124:127]
	ds_read_b128 v[228:231], v128 offset:53248
	ds_read_b128 v[232:235], v128 offset:54272
	v_mfma_f32_16x16x32_bf16 v[32:35], v[188:191], v[236:239], v[32:35]
	s_add_u32 m0, s76, 0x9000
	v_mfma_f32_16x16x32_bf16 v[36:39], v[188:191], v[240:243], v[36:39]
	global_load_lds_dwordx4 v135, s[72:73]
	s_add_u32 m0, s76, 0xa000
	v_mfma_f32_16x16x32_bf16 v[40:43], v[192:195], v[236:239], v[40:43]
	global_load_lds_dwordx4 v132, s[74:75]
	s_add_u32 m0, s76, 0xb000
	v_mfma_f32_16x16x32_bf16 v[44:47], v[192:195], v[240:243], v[44:47]
	global_load_lds_dwordx4 v133, s[74:75]
	s_add_u32 s72, s72, 0x202000
	s_addc_u32 s73, s73, 0
	v_mfma_f32_16x16x32_bf16 v[96:99], v[220:223], v[236:239], v[96:99]
	s_add_u32 s74, s74, 0x2c000
	s_addc_u32 s75, s75, 0
	v_mfma_f32_16x16x32_bf16 v[100:103], v[220:223], v[240:243], v[100:103]
	v_mfma_f32_16x16x32_bf16 v[104:107], v[224:227], v[236:239], v[104:107]
	v_mfma_f32_16x16x32_bf16 v[108:111], v[224:227], v[240:243], v[108:111]
	s_waitcnt lgkmcnt(2)
	v_mfma_f32_16x16x32_bf16 v[64:67], v[172:175], v[244:247], v[64:67]
	ds_read_b128 v[236:239], v128 offset:57344
	v_mfma_f32_16x16x32_bf16 v[68:71], v[172:175], v[248:251], v[68:71]
	ds_read_b128 v[240:243], v128 offset:58368
	v_mfma_f32_16x16x32_bf16 v[72:75], v[176:179], v[244:247], v[72:75]
	v_mfma_f32_16x16x32_bf16 v[76:79], v[176:179], v[248:251], v[76:79]
	v_mfma_f32_16x16x32_bf16 v[48:51], v[180:183], v[244:247], v[48:51]
	v_mfma_f32_16x16x32_bf16 v[52:55], v[180:183], v[248:251], v[52:55]
	v_mfma_f32_16x16x32_bf16 v[56:59], v[184:187], v[244:247], v[56:59]
	v_mfma_f32_16x16x32_bf16 v[60:63], v[184:187], v[248:251], v[60:63]
	s_waitcnt lgkmcnt(2)
	v_mfma_f32_16x16x32_bf16 v[16:19], v[172:175], v[228:231], v[16:19]
	ds_read_b128 v[244:247], v128 offset:61440
	v_mfma_f32_16x16x32_bf16 v[20:23], v[172:175], v[232:235], v[20:23]
	ds_read_b128 v[248:251], v128 offset:62464
	v_mfma_f32_16x16x32_bf16 v[24:27], v[176:179], v[228:231], v[24:27]
	v_mfma_f32_16x16x32_bf16 v[28:31], v[176:179], v[232:235], v[28:31]
	v_mfma_f32_16x16x32_bf16 v[0:3], v[180:183], v[228:231], v[0:3]
	v_mfma_f32_16x16x32_bf16 v[4:7], v[180:183], v[232:235], v[4:7]
	v_mfma_f32_16x16x32_bf16 v[8:11], v[184:187], v[228:231], v[8:11]
	v_mfma_f32_16x16x32_bf16 v[12:15], v[184:187], v[232:235], v[12:15]
	s_waitcnt lgkmcnt(0)
	s_waitcnt vmcnt(6)
	s_barrier
	ds_read_b128 v[188:191], v130
	ds_read_b128 v[192:195], v130 offset:1024
	v_mfma_f32_16x16x32_bf16 v[80:83], v[172:175], v[236:239], v[80:83]
	ds_read_b128 v[220:223], v130 offset:2048
	ds_read_b128 v[224:227], v130 offset:3072
	v_mfma_f32_16x16x32_bf16 v[84:87], v[172:175], v[240:243], v[84:87]
	ds_read_b128 v[228:231], v128
	ds_read_b128 v[232:235], v128 offset:1024
	s_add_u32 m0, s76, 0xc000
	v_mfma_f32_16x16x32_bf16 v[88:91], v[176:179], v[236:239], v[88:91]
	global_load_lds_dwordx4 v132, s[72:73]
	s_add_u32 m0, s76, 0xd000
	v_mfma_f32_16x16x32_bf16 v[92:95], v[176:179], v[240:243], v[92:95]
	global_load_lds_dwordx4 v133, s[72:73]
	s_add_u32 m0, s76, 0xe000
	v_mfma_f32_16x16x32_bf16 v[112:115], v[180:183], v[236:239], v[112:115]
	global_load_lds_dwordx4 v134, s[72:73]
	v_mfma_f32_16x16x32_bf16 v[116:119], v[180:183], v[240:243], v[116:119]
	v_mfma_f32_16x16x32_bf16 v[120:123], v[184:187], v[236:239], v[120:123]
	v_mfma_f32_16x16x32_bf16 v[124:127], v[184:187], v[240:243], v[124:127]
	ds_read_b128 v[236:239], v128 offset:4096
	ds_read_b128 v[240:243], v128 offset:5120
	v_mfma_f32_16x16x32_bf16 v[32:35], v[172:175], v[244:247], v[32:35]
	s_add_u32 m0, s76, 0xf000
	v_mfma_f32_16x16x32_bf16 v[36:39], v[172:175], v[248:251], v[36:39]
	global_load_lds_dwordx4 v135, s[72:73]
	s_add_u32 m0, s76, 0x10000
	v_mfma_f32_16x16x32_bf16 v[40:43], v[176:179], v[244:247], v[40:43]
	global_load_lds_dwordx4 v132, s[74:75]
	s_add_u32 m0, s76, 0x11000
	v_mfma_f32_16x16x32_bf16 v[44:47], v[176:179], v[248:251], v[44:47]
	global_load_lds_dwordx4 v133, s[74:75]
	s_add_u32 s72, s72, 0x202000
	s_addc_u32 s73, s73, 0
	v_mfma_f32_16x16x32_bf16 v[96:99], v[180:183], v[244:247], v[96:99]
	s_add_u32 s74, s74, 0x2c000
	s_addc_u32 s75, s75, 0
	v_mfma_f32_16x16x32_bf16 v[100:103], v[180:183], v[248:251], v[100:103]
	v_mfma_f32_16x16x32_bf16 v[104:107], v[184:187], v[244:247], v[104:107]
	v_mfma_f32_16x16x32_bf16 v[108:111], v[184:187], v[248:251], v[108:111]
	s_waitcnt lgkmcnt(2)
	v_mfma_f32_16x16x32_bf16 v[64:67], v[188:191], v[228:231], v[64:67]
	ds_read_b128 v[244:247], v128 offset:8192
	v_mfma_f32_16x16x32_bf16 v[68:71], v[188:191], v[232:235], v[68:71]
	ds_read_b128 v[248:251], v128 offset:9216
	v_mfma_f32_16x16x32_bf16 v[72:75], v[192:195], v[228:231], v[72:75]
	v_mfma_f32_16x16x32_bf16 v[76:79], v[192:195], v[232:235], v[76:79]
	v_mfma_f32_16x16x32_bf16 v[48:51], v[220:223], v[228:231], v[48:51]
	v_mfma_f32_16x16x32_bf16 v[52:55], v[220:223], v[232:235], v[52:55]
	v_mfma_f32_16x16x32_bf16 v[56:59], v[224:227], v[228:231], v[56:59]
	v_mfma_f32_16x16x32_bf16 v[60:63], v[224:227], v[232:235], v[60:63]
	s_waitcnt lgkmcnt(2)
	v_mfma_f32_16x16x32_bf16 v[16:19], v[188:191], v[236:239], v[16:19]
	ds_read_b128 v[228:231], v128 offset:12288
	v_mfma_f32_16x16x32_bf16 v[20:23], v[188:191], v[240:243], v[20:23]
	ds_read_b128 v[232:235], v128 offset:13312
	v_mfma_f32_16x16x32_bf16 v[24:27], v[192:195], v[236:239], v[24:27]
	v_mfma_f32_16x16x32_bf16 v[28:31], v[192:195], v[240:243], v[28:31]
	v_mfma_f32_16x16x32_bf16 v[0:3], v[220:223], v[236:239], v[0:3]
	v_mfma_f32_16x16x32_bf16 v[4:7], v[220:223], v[240:243], v[4:7]
	v_mfma_f32_16x16x32_bf16 v[8:11], v[224:227], v[236:239], v[8:11]
	v_mfma_f32_16x16x32_bf16 v[12:15], v[224:227], v[240:243], v[12:15]
	s_waitcnt lgkmcnt(0)
	s_waitcnt vmcnt(6)
	s_barrier
	ds_read_b128 v[172:175], v130 offset:24576
	ds_read_b128 v[176:179], v130 offset:25600
	v_mfma_f32_16x16x32_bf16 v[80:83], v[188:191], v[244:247], v[80:83]
	ds_read_b128 v[180:183], v130 offset:26624
	ds_read_b128 v[184:187], v130 offset:27648
	v_mfma_f32_16x16x32_bf16 v[84:87], v[188:191], v[248:251], v[84:87]
	ds_read_b128 v[236:239], v128 offset:24576
	ds_read_b128 v[240:243], v128 offset:25600
	s_add_u32 m0, s76, 0x0
	v_mfma_f32_16x16x32_bf16 v[88:91], v[192:195], v[244:247], v[88:91]
	global_load_lds_dwordx4 v132, s[72:73]
	s_add_u32 m0, s76, 0x1000
	v_mfma_f32_16x16x32_bf16 v[92:95], v[192:195], v[248:251], v[92:95]
	global_load_lds_dwordx4 v133, s[72:73]
	s_add_u32 m0, s76, 0x2000
	v_mfma_f32_16x16x32_bf16 v[112:115], v[220:223], v[244:247], v[112:115]
	global_load_lds_dwordx4 v134, s[72:73]
	v_mfma_f32_16x16x32_bf16 v[116:119], v[220:223], v[248:251], v[116:119]
	v_mfma_f32_16x16x32_bf16 v[120:123], v[224:227], v[244:247], v[120:123]
	v_mfma_f32_16x16x32_bf16 v[124:127], v[224:227], v[248:251], v[124:127]
	ds_read_b128 v[244:247], v128 offset:28672
	ds_read_b128 v[248:251], v128 offset:29696
	v_mfma_f32_16x16x32_bf16 v[32:35], v[188:191], v[228:231], v[32:35]
	s_add_u32 m0, s76, 0x3000
	v_mfma_f32_16x16x32_bf16 v[36:39], v[188:191], v[232:235], v[36:39]
	global_load_lds_dwordx4 v135, s[72:73]
	s_add_u32 m0, s76, 0x4000
	v_mfma_f32_16x16x32_bf16 v[40:43], v[192:195], v[228:231], v[40:43]
	global_load_lds_dwordx4 v132, s[74:75]
	s_add_u32 m0, s76, 0x5000
	v_mfma_f32_16x16x32_bf16 v[44:47], v[192:195], v[232:235], v[44:47]
	global_load_lds_dwordx4 v133, s[74:75]
	s_add_u32 s72, s72, 0x202000
	s_addc_u32 s73, s73, 0
	v_mfma_f32_16x16x32_bf16 v[96:99], v[220:223], v[228:231], v[96:99]
	s_add_u32 s74, s74, 0x2c000
	s_addc_u32 s75, s75, 0
	v_mfma_f32_16x16x32_bf16 v[100:103], v[220:223], v[232:235], v[100:103]
	v_mfma_f32_16x16x32_bf16 v[104:107], v[224:227], v[228:231], v[104:107]
	v_mfma_f32_16x16x32_bf16 v[108:111], v[224:227], v[232:235], v[108:111]
	s_waitcnt lgkmcnt(2)
	v_mfma_f32_16x16x32_bf16 v[64:67], v[172:175], v[236:239], v[64:67]
	ds_read_b128 v[228:231], v128 offset:32768
	v_mfma_f32_16x16x32_bf16 v[68:71], v[172:175], v[240:243], v[68:71]
	ds_read_b128 v[232:235], v128 offset:33792
	v_mfma_f32_16x16x32_bf16 v[72:75], v[176:179], v[236:239], v[72:75]
	v_mfma_f32_16x16x32_bf16 v[76:79], v[176:179], v[240:243], v[76:79]
	v_mfma_f32_16x16x32_bf16 v[48:51], v[180:183], v[236:239], v[48:51]
	v_mfma_f32_16x16x32_bf16 v[52:55], v[180:183], v[240:243], v[52:55]
	v_mfma_f32_16x16x32_bf16 v[56:59], v[184:187], v[236:239], v[56:59]
	v_mfma_f32_16x16x32_bf16 v[60:63], v[184:187], v[240:243], v[60:63]
	s_waitcnt lgkmcnt(2)
	v_mfma_f32_16x16x32_bf16 v[16:19], v[172:175], v[244:247], v[16:19]
	ds_read_b128 v[236:239], v128 offset:36864
	v_mfma_f32_16x16x32_bf16 v[20:23], v[172:175], v[248:251], v[20:23]
	ds_read_b128 v[240:243], v128 offset:37888
	v_mfma_f32_16x16x32_bf16 v[24:27], v[176:179], v[244:247], v[24:27]
	v_mfma_f32_16x16x32_bf16 v[28:31], v[176:179], v[248:251], v[28:31]
	v_mfma_f32_16x16x32_bf16 v[0:3], v[180:183], v[244:247], v[0:3]
	v_mfma_f32_16x16x32_bf16 v[4:7], v[180:183], v[248:251], v[4:7]
	v_mfma_f32_16x16x32_bf16 v[8:11], v[184:187], v[244:247], v[8:11]
	v_mfma_f32_16x16x32_bf16 v[12:15], v[184:187], v[248:251], v[12:15]
	s_waitcnt lgkmcnt(0)
	s_waitcnt vmcnt(6)
	s_barrier
	ds_read_b128 v[188:191], v130 offset:49152
	ds_read_b128 v[192:195], v130 offset:50176
	v_mfma_f32_16x16x32_bf16 v[80:83], v[172:175], v[228:231], v[80:83]
	ds_read_b128 v[220:223], v130 offset:51200
	ds_read_b128 v[224:227], v130 offset:52224
	v_mfma_f32_16x16x32_bf16 v[84:87], v[172:175], v[232:235], v[84:87]
	ds_read_b128 v[244:247], v128 offset:49152
	ds_read_b128 v[248:251], v128 offset:50176
	s_add_u32 m0, s76, 0x6000
	v_mfma_f32_16x16x32_bf16 v[88:91], v[176:179], v[228:231], v[88:91]
	global_load_lds_dwordx4 v132, s[72:73]
	s_add_u32 m0, s76, 0x7000
	v_mfma_f32_16x16x32_bf16 v[92:95], v[176:179], v[232:235], v[92:95]
	global_load_lds_dwordx4 v133, s[72:73]
	s_add_u32 m0, s76, 0x8000
	v_mfma_f32_16x16x32_bf16 v[112:115], v[180:183], v[228:231], v[112:115]
	global_load_lds_dwordx4 v134, s[72:73]
	v_mfma_f32_16x16x32_bf16 v[116:119], v[180:183], v[232:235], v[116:119]
	v_mfma_f32_16x16x32_bf16 v[120:123], v[184:187], v[228:231], v[120:123]
	v_mfma_f32_16x16x32_bf16 v[124:127], v[184:187], v[232:235], v[124:127]
	ds_read_b128 v[228:231], v128 offset:53248
	ds_read_b128 v[232:235], v128 offset:54272
	v_mfma_f32_16x16x32_bf16 v[32:35], v[172:175], v[236:239], v[32:35]
	s_add_u32 m0, s76, 0x9000
	v_mfma_f32_16x16x32_bf16 v[36:39], v[172:175], v[240:243], v[36:39]
	global_load_lds_dwordx4 v135, s[72:73]
	s_add_u32 m0, s76, 0xa000
	v_mfma_f32_16x16x32_bf16 v[40:43], v[176:179], v[236:239], v[40:43]
	global_load_lds_dwordx4 v132, s[74:75]
	s_add_u32 m0, s76, 0xb000
	v_mfma_f32_16x16x32_bf16 v[44:47], v[176:179], v[240:243], v[44:47]
	global_load_lds_dwordx4 v133, s[74:75]
	s_add_u32 s72, s72, 0x202000
	s_addc_u32 s73, s73, 0
	v_mfma_f32_16x16x32_bf16 v[96:99], v[180:183], v[236:239], v[96:99]
	s_add_u32 s74, s74, 0x2c000
	s_addc_u32 s75, s75, 0
	v_mfma_f32_16x16x32_bf16 v[100:103], v[180:183], v[240:243], v[100:103]
	v_mfma_f32_16x16x32_bf16 v[104:107], v[184:187], v[236:239], v[104:107]
	v_mfma_f32_16x16x32_bf16 v[108:111], v[184:187], v[240:243], v[108:111]
	s_waitcnt lgkmcnt(2)
	v_mfma_f32_16x16x32_bf16 v[64:67], v[188:191], v[244:247], v[64:67]
	ds_read_b128 v[236:239], v128 offset:57344
	v_mfma_f32_16x16x32_bf16 v[68:71], v[188:191], v[248:251], v[68:71]
	ds_read_b128 v[240:243], v128 offset:58368
	v_mfma_f32_16x16x32_bf16 v[72:75], v[192:195], v[244:247], v[72:75]
	v_mfma_f32_16x16x32_bf16 v[76:79], v[192:195], v[248:251], v[76:79]
	v_mfma_f32_16x16x32_bf16 v[48:51], v[220:223], v[244:247], v[48:51]
	v_mfma_f32_16x16x32_bf16 v[52:55], v[220:223], v[248:251], v[52:55]
	v_mfma_f32_16x16x32_bf16 v[56:59], v[224:227], v[244:247], v[56:59]
	v_mfma_f32_16x16x32_bf16 v[60:63], v[224:227], v[248:251], v[60:63]
	s_waitcnt lgkmcnt(2)
	v_mfma_f32_16x16x32_bf16 v[16:19], v[188:191], v[228:231], v[16:19]
	ds_read_b128 v[244:247], v128 offset:61440
	v_mfma_f32_16x16x32_bf16 v[20:23], v[188:191], v[232:235], v[20:23]
	ds_read_b128 v[248:251], v128 offset:62464
	v_mfma_f32_16x16x32_bf16 v[24:27], v[192:195], v[228:231], v[24:27]
	v_mfma_f32_16x16x32_bf16 v[28:31], v[192:195], v[232:235], v[28:31]
	v_mfma_f32_16x16x32_bf16 v[0:3], v[220:223], v[228:231], v[0:3]
	v_mfma_f32_16x16x32_bf16 v[4:7], v[220:223], v[232:235], v[4:7]
	v_mfma_f32_16x16x32_bf16 v[8:11], v[224:227], v[228:231], v[8:11]
	v_mfma_f32_16x16x32_bf16 v[12:15], v[224:227], v[232:235], v[12:15]
	s_waitcnt lgkmcnt(0)
	s_waitcnt vmcnt(6)
	s_barrier
	ds_read_b128 v[172:175], v130
	ds_read_b128 v[176:179], v130 offset:1024
	v_mfma_f32_16x16x32_bf16 v[80:83], v[188:191], v[236:239], v[80:83]
	ds_read_b128 v[180:183], v130 offset:2048
	ds_read_b128 v[184:187], v130 offset:3072
	v_mfma_f32_16x16x32_bf16 v[84:87], v[188:191], v[240:243], v[84:87]
	ds_read_b128 v[228:231], v128
	ds_read_b128 v[232:235], v128 offset:1024
	v_mfma_f32_16x16x32_bf16 v[88:91], v[192:195], v[236:239], v[88:91]
	v_mfma_f32_16x16x32_bf16 v[92:95], v[192:195], v[240:243], v[92:95]
	v_mfma_f32_16x16x32_bf16 v[112:115], v[220:223], v[236:239], v[112:115]
	v_mfma_f32_16x16x32_bf16 v[116:119], v[220:223], v[240:243], v[116:119]
	v_mfma_f32_16x16x32_bf16 v[120:123], v[224:227], v[236:239], v[120:123]
	v_mfma_f32_16x16x32_bf16 v[124:127], v[224:227], v[240:243], v[124:127]
	ds_read_b128 v[236:239], v128 offset:4096
	ds_read_b128 v[240:243], v128 offset:5120
	v_mfma_f32_16x16x32_bf16 v[32:35], v[188:191], v[244:247], v[32:35]
	v_mfma_f32_16x16x32_bf16 v[36:39], v[188:191], v[248:251], v[36:39]
	v_mfma_f32_16x16x32_bf16 v[40:43], v[192:195], v[244:247], v[40:43]
	v_mfma_f32_16x16x32_bf16 v[44:47], v[192:195], v[248:251], v[44:47]
	v_mfma_f32_16x16x32_bf16 v[96:99], v[220:223], v[244:247], v[96:99]
	v_mfma_f32_16x16x32_bf16 v[100:103], v[220:223], v[248:251], v[100:103]
	v_mfma_f32_16x16x32_bf16 v[104:107], v[224:227], v[244:247], v[104:107]
	v_mfma_f32_16x16x32_bf16 v[108:111], v[224:227], v[248:251], v[108:111]
	s_waitcnt lgkmcnt(2)
	v_mfma_f32_16x16x32_bf16 v[64:67], v[172:175], v[228:231], v[64:67]
	ds_read_b128 v[244:247], v128 offset:8192
	v_mfma_f32_16x16x32_bf16 v[68:71], v[172:175], v[232:235], v[68:71]
	ds_read_b128 v[248:251], v128 offset:9216
	v_mfma_f32_16x16x32_bf16 v[72:75], v[176:179], v[228:231], v[72:75]
	v_mfma_f32_16x16x32_bf16 v[76:79], v[176:179], v[232:235], v[76:79]
	v_mfma_f32_16x16x32_bf16 v[48:51], v[180:183], v[228:231], v[48:51]
	v_mfma_f32_16x16x32_bf16 v[52:55], v[180:183], v[232:235], v[52:55]
	v_mfma_f32_16x16x32_bf16 v[56:59], v[184:187], v[228:231], v[56:59]
	v_mfma_f32_16x16x32_bf16 v[60:63], v[184:187], v[232:235], v[60:63]
	s_waitcnt lgkmcnt(2)
	v_mfma_f32_16x16x32_bf16 v[16:19], v[172:175], v[236:239], v[16:19]
	ds_read_b128 v[228:231], v128 offset:12288
	v_mfma_f32_16x16x32_bf16 v[20:23], v[172:175], v[240:243], v[20:23]
	ds_read_b128 v[232:235], v128 offset:13312
	v_mfma_f32_16x16x32_bf16 v[24:27], v[176:179], v[236:239], v[24:27]
	v_mfma_f32_16x16x32_bf16 v[28:31], v[176:179], v[240:243], v[28:31]
	v_mfma_f32_16x16x32_bf16 v[0:3], v[180:183], v[236:239], v[0:3]
	v_mfma_f32_16x16x32_bf16 v[4:7], v[180:183], v[240:243], v[4:7]
	v_mfma_f32_16x16x32_bf16 v[8:11], v[184:187], v[236:239], v[8:11]
	v_mfma_f32_16x16x32_bf16 v[12:15], v[184:187], v[240:243], v[12:15]
	s_waitcnt lgkmcnt(0)
	s_waitcnt vmcnt(0)
	s_barrier
	ds_read_b128 v[188:191], v130 offset:24576
	ds_read_b128 v[192:195], v130 offset:25600
	v_mfma_f32_16x16x32_bf16 v[80:83], v[172:175], v[244:247], v[80:83]
	ds_read_b128 v[220:223], v130 offset:26624
	ds_read_b128 v[224:227], v130 offset:27648
	v_mfma_f32_16x16x32_bf16 v[84:87], v[172:175], v[248:251], v[84:87]
	ds_read_b128 v[236:239], v128 offset:24576
	ds_read_b128 v[240:243], v128 offset:25600
	v_mfma_f32_16x16x32_bf16 v[88:91], v[176:179], v[244:247], v[88:91]
	v_mfma_f32_16x16x32_bf16 v[92:95], v[176:179], v[248:251], v[92:95]
	v_mfma_f32_16x16x32_bf16 v[112:115], v[180:183], v[244:247], v[112:115]
	v_mfma_f32_16x16x32_bf16 v[116:119], v[180:183], v[248:251], v[116:119]
	v_mfma_f32_16x16x32_bf16 v[120:123], v[184:187], v[244:247], v[120:123]
	v_mfma_f32_16x16x32_bf16 v[124:127], v[184:187], v[248:251], v[124:127]
	ds_read_b128 v[244:247], v128 offset:28672
	ds_read_b128 v[248:251], v128 offset:29696
	v_mfma_f32_16x16x32_bf16 v[32:35], v[172:175], v[228:231], v[32:35]
	v_mfma_f32_16x16x32_bf16 v[36:39], v[172:175], v[232:235], v[36:39]
	v_mfma_f32_16x16x32_bf16 v[40:43], v[176:179], v[228:231], v[40:43]
	v_mfma_f32_16x16x32_bf16 v[44:47], v[176:179], v[232:235], v[44:47]
	v_mfma_f32_16x16x32_bf16 v[96:99], v[180:183], v[228:231], v[96:99]
	v_mfma_f32_16x16x32_bf16 v[100:103], v[180:183], v[232:235], v[100:103]
	v_mfma_f32_16x16x32_bf16 v[104:107], v[184:187], v[228:231], v[104:107]
	v_mfma_f32_16x16x32_bf16 v[108:111], v[184:187], v[232:235], v[108:111]
	s_waitcnt lgkmcnt(2)
	v_mfma_f32_16x16x32_bf16 v[64:67], v[188:191], v[236:239], v[64:67]
	ds_read_b128 v[228:231], v128 offset:32768
	v_mfma_f32_16x16x32_bf16 v[68:71], v[188:191], v[240:243], v[68:71]
	ds_read_b128 v[232:235], v128 offset:33792
	v_mfma_f32_16x16x32_bf16 v[72:75], v[192:195], v[236:239], v[72:75]
	v_mfma_f32_16x16x32_bf16 v[76:79], v[192:195], v[240:243], v[76:79]
	v_mfma_f32_16x16x32_bf16 v[48:51], v[220:223], v[236:239], v[48:51]
	v_mfma_f32_16x16x32_bf16 v[52:55], v[220:223], v[240:243], v[52:55]
	v_mfma_f32_16x16x32_bf16 v[56:59], v[224:227], v[236:239], v[56:59]
	v_mfma_f32_16x16x32_bf16 v[60:63], v[224:227], v[240:243], v[60:63]
	s_waitcnt lgkmcnt(2)
	v_mfma_f32_16x16x32_bf16 v[16:19], v[188:191], v[244:247], v[16:19]
	ds_read_b128 v[236:239], v128 offset:36864
	v_mfma_f32_16x16x32_bf16 v[20:23], v[188:191], v[248:251], v[20:23]
	ds_read_b128 v[240:243], v128 offset:37888
	v_mfma_f32_16x16x32_bf16 v[24:27], v[192:195], v[244:247], v[24:27]
	v_mfma_f32_16x16x32_bf16 v[28:31], v[192:195], v[248:251], v[28:31]
	v_mfma_f32_16x16x32_bf16 v[0:3], v[220:223], v[244:247], v[0:3]
	v_mfma_f32_16x16x32_bf16 v[4:7], v[220:223], v[248:251], v[4:7]
	v_mfma_f32_16x16x32_bf16 v[8:11], v[224:227], v[244:247], v[8:11]
	v_mfma_f32_16x16x32_bf16 v[12:15], v[224:227], v[248:251], v[12:15]
	s_waitcnt lgkmcnt(0)
	v_mfma_f32_16x16x32_bf16 v[80:83], v[188:191], v[228:231], v[80:83]
	v_mfma_f32_16x16x32_bf16 v[84:87], v[188:191], v[232:235], v[84:87]
	v_mfma_f32_16x16x32_bf16 v[88:91], v[192:195], v[228:231], v[88:91]
	v_mfma_f32_16x16x32_bf16 v[92:95], v[192:195], v[232:235], v[92:95]
	v_mfma_f32_16x16x32_bf16 v[112:115], v[220:223], v[228:231], v[112:115]
	v_mfma_f32_16x16x32_bf16 v[116:119], v[220:223], v[232:235], v[116:119]
	v_mfma_f32_16x16x32_bf16 v[120:123], v[224:227], v[228:231], v[120:123]
	v_mfma_f32_16x16x32_bf16 v[124:127], v[224:227], v[232:235], v[124:127]
	v_mfma_f32_16x16x32_bf16 v[32:35], v[188:191], v[236:239], v[32:35]
	v_mfma_f32_16x16x32_bf16 v[36:39], v[188:191], v[240:243], v[36:39]
	v_mfma_f32_16x16x32_bf16 v[40:43], v[192:195], v[236:239], v[40:43]
	v_mfma_f32_16x16x32_bf16 v[44:47], v[192:195], v[240:243], v[44:47]
	v_mfma_f32_16x16x32_bf16 v[96:99], v[220:223], v[236:239], v[96:99]
	v_mfma_f32_16x16x32_bf16 v[100:103], v[220:223], v[240:243], v[100:103]
	v_mfma_f32_16x16x32_bf16 v[104:107], v[224:227], v[236:239], v[104:107]
	v_mfma_f32_16x16x32_bf16 v[108:111], v[224:227], v[240:243], v[108:111]
	s_setprio 0
	s_nop 15
	s_nop 15
	v_permlane16_swap_b32_e32 v64, v68
	v_permlane16_swap_b32_e32 v65, v69
	v_permlane16_swap_b32_e32 v66, v70
	v_permlane16_swap_b32_e32 v67, v71
	v_permlane16_swap_b32_e32 v72, v76
	v_permlane16_swap_b32_e32 v73, v77
	v_permlane16_swap_b32_e32 v74, v78
	v_permlane16_swap_b32_e32 v75, v79
	v_permlane16_swap_b32_e32 v16, v20
	v_permlane16_swap_b32_e32 v17, v21
	v_permlane16_swap_b32_e32 v18, v22
	v_permlane16_swap_b32_e32 v19, v23
	v_permlane16_swap_b32_e32 v24, v28
	v_permlane16_swap_b32_e32 v25, v29
	v_permlane16_swap_b32_e32 v26, v30
	v_permlane16_swap_b32_e32 v27, v31
	v_permlane16_swap_b32_e32 v80, v84
	v_permlane16_swap_b32_e32 v81, v85
	v_permlane16_swap_b32_e32 v82, v86
	v_permlane16_swap_b32_e32 v83, v87
	v_permlane16_swap_b32_e32 v88, v92
	v_permlane16_swap_b32_e32 v89, v93
	v_permlane16_swap_b32_e32 v90, v94
	v_permlane16_swap_b32_e32 v91, v95
	v_permlane16_swap_b32_e32 v32, v36
	v_permlane16_swap_b32_e32 v33, v37
	v_permlane16_swap_b32_e32 v34, v38
	v_permlane16_swap_b32_e32 v35, v39
	v_permlane16_swap_b32_e32 v40, v44
	v_permlane16_swap_b32_e32 v41, v45
	v_permlane16_swap_b32_e32 v42, v46
	v_permlane16_swap_b32_e32 v43, v47
	v_permlane16_swap_b32_e32 v48, v52
	v_permlane16_swap_b32_e32 v49, v53
	v_permlane16_swap_b32_e32 v50, v54
	v_permlane16_swap_b32_e32 v51, v55
	v_permlane16_swap_b32_e32 v56, v60
	v_permlane16_swap_b32_e32 v57, v61
	v_permlane16_swap_b32_e32 v58, v62
	v_permlane16_swap_b32_e32 v59, v63
	v_permlane16_swap_b32_e32 v0, v4
	v_permlane16_swap_b32_e32 v1, v5
	v_permlane16_swap_b32_e32 v2, v6
	v_permlane16_swap_b32_e32 v3, v7
	v_permlane16_swap_b32_e32 v8, v12
	v_permlane16_swap_b32_e32 v9, v13
	v_permlane16_swap_b32_e32 v10, v14
	v_permlane16_swap_b32_e32 v11, v15
	v_permlane16_swap_b32_e32 v112, v116
	v_permlane16_swap_b32_e32 v113, v117
	v_permlane16_swap_b32_e32 v114, v118
	v_permlane16_swap_b32_e32 v115, v119
	v_permlane16_swap_b32_e32 v120, v124
	v_permlane16_swap_b32_e32 v121, v125
	v_permlane16_swap_b32_e32 v122, v126
	v_permlane16_swap_b32_e32 v123, v127
	v_permlane16_swap_b32_e32 v96, v100
	v_permlane16_swap_b32_e32 v97, v101
	v_permlane16_swap_b32_e32 v98, v102
	v_permlane16_swap_b32_e32 v99, v103
	v_permlane16_swap_b32_e32 v104, v108
	v_permlane16_swap_b32_e32 v105, v109
	v_permlane16_swap_b32_e32 v106, v110
	v_permlane16_swap_b32_e32 v107, v111
	s_nop 1
	v_mov_b32_e32 v176, v95
	v_mov_b32_e32 v184, v91
	v_mov_b32_e32 v186, v89
	v_mov_b32_e32 v192, v83
	v_mov_b32_e32 v194, v81
	v_mov_b32_e32 v177, v127
	v_mov_b32_e32 v95, v126
	v_mov_b32_e32 v185, v123
	v_mov_b32_e32 v91, v122
	v_mov_b32_e32 v187, v121
	v_mov_b32_e32 v89, v120
	v_mov_b32_e32 v193, v115
	v_mov_b32_e32 v83, v114
	v_mov_b32_e32 v128, v47
	v_mov_b32_e32 v130, v45
	v_mov_b32_e32 v136, v39
	v_mov_b32_e32 v138, v37
	v_mov_b32_e32 v195, v113
	v_mov_b32_e32 v81, v112
	v_mov_b32_e32 v129, v111
	v_mov_b32_e32 v47, v110
	v_mov_b32_e32 v131, v109
	v_mov_b32_e32 v45, v108
	v_mov_b32_e32 v137, v103
	v_mov_b32_e32 v39, v102
	v_mov_b32_e32 v139, v101
	v_mov_b32_e32 v37, v100
	v_mov_b32_e32 v182, v93
	v_mov_b32_e32 v183, v125
	v_mov_b32_e32 v93, v124
	v_mov_b32_e32 v132, v43
	v_mov_b32_e32 v134, v41
	v_mov_b32_e32 v133, v107
	v_mov_b32_e32 v43, v106
	v_mov_b32_e32 v135, v105
	v_mov_b32_e32 v41, v104
	v_mov_b32_e32 v188, v87
	v_mov_b32_e32 v190, v85
	v_mov_b32_e32 v172, v35
	v_mov_b32_e32 v174, v33
	v_mov_b32_e32 v189, v119
	v_mov_b32_e32 v87, v118
	v_mov_b32_e32 v191, v117
	v_mov_b32_e32 v85, v116
	v_mov_b32_e32 v173, v99
	v_mov_b32_e32 v35, v98
	v_mov_b32_e32 v175, v97
	v_mov_b32_e32 v33, v96

.LBB0_535:
	s_or_saveexec_b64 s[0:1], s[0:1]
	v_mov_b32_e32 v127, 0
	v_mov_b64_e32 v[130:131], s[18:19]
	v_mov_b32_e32 v126, 0
	v_mov_b32_e32 v125, 0
	v_mov_b32_e32 v124, 0
	v_mov_b32_e32 v123, 0
	v_mov_b32_e32 v122, 0
	v_mov_b32_e32 v121, 0
	v_mov_b32_e32 v120, 0
	v_mov_b32_e32 v119, 0
	v_mov_b32_e32 v118, 0
	v_mov_b32_e32 v117, 0
	v_mov_b32_e32 v116, 0
	v_mov_b32_e32 v115, 0
	v_mov_b32_e32 v114, 0
	v_mov_b32_e32 v113, 0
	v_mov_b32_e32 v112, 0
	v_mov_b32_e32 v63, 0
	v_mov_b32_e32 v62, 0
	v_mov_b32_e32 v61, 0
	v_mov_b32_e32 v60, 0
	v_mov_b32_e32 v59, 0
	v_mov_b32_e32 v58, 0
	v_mov_b32_e32 v57, 0
	v_mov_b32_e32 v56, 0
	v_mov_b32_e32 v55, 0
	v_mov_b32_e32 v54, 0
	v_mov_b32_e32 v53, 0
	v_mov_b32_e32 v52, 0
	v_mov_b32_e32 v51, 0
	v_mov_b32_e32 v50, 0
	v_mov_b32_e32 v49, 0
	v_mov_b32_e32 v48, 0
	v_mov_b32_e32 v111, 0
	v_mov_b32_e32 v110, 0
	v_mov_b32_e32 v109, 0
	v_mov_b32_e32 v108, 0
	v_mov_b32_e32 v107, 0
	v_mov_b32_e32 v106, 0
	v_mov_b32_e32 v105, 0
	v_mov_b32_e32 v104, 0
	v_mov_b32_e32 v103, 0
	v_mov_b32_e32 v102, 0
	v_mov_b32_e32 v101, 0
	v_mov_b32_e32 v100, 0
	v_mov_b32_e32 v99, 0
	v_mov_b32_e32 v98, 0
	v_mov_b32_e32 v97, 0
	v_mov_b32_e32 v96, 0
	v_mov_b32_e32 v47, 0
	v_mov_b32_e32 v46, 0
	v_mov_b32_e32 v45, 0
	v_mov_b32_e32 v44, 0
	v_mov_b32_e32 v43, 0
	v_mov_b32_e32 v42, 0
	v_mov_b32_e32 v41, 0
	v_mov_b32_e32 v40, 0
	v_mov_b32_e32 v39, 0
	v_mov_b32_e32 v38, 0
	v_mov_b32_e32 v37, 0
	v_mov_b32_e32 v36, 0
	v_mov_b32_e32 v35, 0
	v_mov_b32_e32 v34, 0
	v_mov_b32_e32 v33, 0
	v_mov_b32_e32 v32, 0
	s_xor_b64 exec, exec, s[0:1]
	s_cbranch_execz .LBB0_539
	v_readfirstlane_b32 s78, v166
	v_readfirstlane_b32 s79, v168
	v_readfirstlane_b32 s76, v186
	v_mbcnt_lo_u32_b32 v244, -1, 0
	v_mbcnt_hi_u32_b32 v244, -1, v244
	s_nop 3
	s_lshl_b32 s78, s78, 14
	s_lshl_b32 s79, s79, 13
	s_add_u32 s72, s90, s78
	s_addc_u32 s73, s91, 0
	s_add_u32 s72, s72, 0xf0f0000
	s_addc_u32 s73, s73, 0
	s_add_u32 s74, s90, s79
	s_addc_u32 s75, s91, 0
	s_add_u32 s74, s74, 0x1b108000
	s_addc_u32 s75, s75, 0
	v_lshrrev_b32_e32 v245, 2, v244
	v_lshrrev_b32_e32 v246, 4, v244
	v_xor_b32_e32 v246, v246, v244
	v_and_b32_e32 v246, 3, v246
	v_lshlrev_b32_e32 v246, 4, v246
	v_lshl_or_b32 v245, v245, 6, v246
	v_or_b32_e32 v170, v245, v186
	v_add_u32_e32 v171, 0x1000, v170
	v_add_u32_e32 v180, 0x2000, v170
	v_add_u32_e32 v181, 0x3000, v170
	v_and_b32_e32 v245, 15, v244
	v_lshrrev_b32_e32 v246, 4, v244
	v_bfe_u32 v247, v244, 2, 2
	v_xor_b32_e32 v247, v247, v246
	v_lshlrev_b32_e32 v247, 4, v247
	v_lshl_or_b32 v128, v245, 6, v247
	v_lshrrev_b32_e32 v247, 10, v186
	v_lshrrev_b32_e32 v247, 1, v247
	v_lshl_or_b32 v128, v247, 11, v128
	v_and_b32_e32 v247, 3, v244
	v_bfe_u32 v245, v244, 2, 1
	v_lshl_or_b32 v247, v245, 3, v247
	v_bfe_u32 v245, v244, 3, 1
	v_lshl_or_b32 v247, v245, 2, v247
	v_lshrrev_b32_e32 v245, 2, v247
	v_xor_b32_e32 v245, v245, v246
	v_lshlrev_b32_e32 v245, 4, v245
	v_lshl_or_b32 v167, v247, 6, v245
	v_lshrrev_b32_e32 v247, 10, v186
	v_and_b32_e32 v247, 1, v247
	v_lshl_or_b32 v167, v247, 12, v167
	v_or_b32_e32 v167, 0x4000, v167
	s_cmp_eq_u32 s99, 0x7fffffff
	s_cbranch_scc0 .Lgprio_p3
	s_setprio 1
.Lgprio_p3:
	s_add_u32 m0, s76, 0x2000
	s_nop 0
	global_load_lds_dwordx4 v180, s[72:73]
	s_add_u32 m0, s76, 0x3000
	s_nop 0
	global_load_lds_dwordx4 v181, s[72:73]
	s_add_u32 m0, s76, 0x4000
	s_nop 0
	global_load_lds_dwordx4 v170, s[74:75]
	s_add_u32 m0, s76, 0x5000
	s_nop 0
	global_load_lds_dwordx4 v171, s[74:75]
	s_add_u32 s72, s72, 0x202000
	s_addc_u32 s73, s73, 0
	s_add_u32 s74, s74, 0x10000
	s_addc_u32 s75, s75, 0
	s_add_u32 m0, s76, 0x6000
	s_nop 0
	global_load_lds_dwordx4 v170, s[72:73]
	s_add_u32 m0, s76, 0x7000
	s_nop 0
	global_load_lds_dwordx4 v171, s[72:73]
	s_add_u32 m0, s76, 0x8000
	s_nop 0
	global_load_lds_dwordx4 v180, s[72:73]
	s_add_u32 m0, s76, 0x9000
	s_nop 0
	global_load_lds_dwordx4 v181, s[72:73]
	s_add_u32 m0, s76, 0xa000
	s_nop 0
	global_load_lds_dwordx4 v170, s[74:75]
	s_add_u32 m0, s76, 0xb000
	s_nop 0
	global_load_lds_dwordx4 v171, s[74:75]
	s_add_u32 s72, s72, 0x202000
	s_addc_u32 s73, s73, 0
	s_add_u32 s74, s74, 0x10000
	s_addc_u32 s75, s75, 0
	s_add_u32 m0, s76, 0xc000
	s_nop 0
	global_load_lds_dwordx4 v170, s[72:73]
	s_add_u32 m0, s76, 0xd000
	s_nop 0
	global_load_lds_dwordx4 v171, s[72:73]
	s_add_u32 m0, s76, 0xe000
	s_nop 0
	global_load_lds_dwordx4 v180, s[72:73]
	s_add_u32 m0, s76, 0xf000
	s_nop 0
	global_load_lds_dwordx4 v181, s[72:73]
	s_add_u32 m0, s76, 0x10000
	s_nop 0
	global_load_lds_dwordx4 v170, s[74:75]
	s_add_u32 m0, s76, 0x11000
	s_nop 0
	global_load_lds_dwordx4 v171, s[74:75]
	s_add_u32 s72, s72, 0x202000
	s_addc_u32 s73, s73, 0
	s_add_u32 s74, s74, 0x10000
	s_addc_u32 s75, s75, 0
	s_waitcnt vmcnt(12)
	s_barrier
	ds_read_b128 v[212:215], v167
	ds_read_b128 v[216:219], v167 offset:1024
	ds_read_b128 v[220:223], v167 offset:2048
	ds_read_b128 v[224:227], v167 offset:3072
	ds_read_b128 v[132:135], v128
	ds_read_b128 v[136:139], v128 offset:1024
	ds_read_b128 v[172:175], v128 offset:4096
	ds_read_b128 v[176:179], v128 offset:5120
	s_waitcnt lgkmcnt(0)
	v_mfma_f32_16x16x32_bf16 v[80:83], v[212:215], v[132:135], 0
	ds_read_b128 v[248:251], v128 offset:8192
	v_mfma_f32_16x16x32_bf16 v[84:87], v[212:215], v[136:139], 0
	ds_read_b128 v[244:247], v128 offset:9216
	v_mfma_f32_16x16x32_bf16 v[88:91], v[216:219], v[132:135], 0
	v_mfma_f32_16x16x32_bf16 v[92:95], v[216:219], v[136:139], 0
	v_mfma_f32_16x16x32_bf16 v[64:67], v[220:223], v[132:135], 0
	v_mfma_f32_16x16x32_bf16 v[68:71], v[220:223], v[136:139], 0
	v_mfma_f32_16x16x32_bf16 v[72:75], v[224:227], v[132:135], 0
	v_mfma_f32_16x16x32_bf16 v[76:79], v[224:227], v[136:139], 0
	s_waitcnt lgkmcnt(2)
	v_mfma_f32_16x16x32_bf16 v[16:19], v[212:215], v[172:175], 0
	ds_read_b128 v[132:135], v128 offset:12288
	v_mfma_f32_16x16x32_bf16 v[20:23], v[212:215], v[176:179], 0
	ds_read_b128 v[136:139], v128 offset:13312
	v_mfma_f32_16x16x32_bf16 v[24:27], v[216:219], v[172:175], 0
	v_mfma_f32_16x16x32_bf16 v[28:31], v[216:219], v[176:179], 0
	v_mfma_f32_16x16x32_bf16 v[0:3], v[220:223], v[172:175], 0
	v_mfma_f32_16x16x32_bf16 v[4:7], v[220:223], v[176:179], 0
	v_mfma_f32_16x16x32_bf16 v[8:11], v[224:227], v[172:175], 0
	v_mfma_f32_16x16x32_bf16 v[12:15], v[224:227], v[176:179], 0
	s_waitcnt lgkmcnt(0)
	s_waitcnt vmcnt(6)
	s_barrier
	ds_read_b128 v[228:231], v167 offset:24576
	ds_read_b128 v[232:235], v167 offset:25600
	v_mfma_f32_16x16x32_bf16 v[112:115], v[212:215], v[248:251], 0
	ds_read_b128 v[236:239], v167 offset:26624
	ds_read_b128 v[240:243], v167 offset:27648
	v_mfma_f32_16x16x32_bf16 v[116:119], v[212:215], v[244:247], 0
	ds_read_b128 v[172:175], v128 offset:24576
	ds_read_b128 v[176:179], v128 offset:25600
	s_add_u32 m0, s76, 0x0
	v_mfma_f32_16x16x32_bf16 v[120:123], v[216:219], v[248:251], 0
	global_load_lds_dwordx4 v170, s[72:73]
	s_add_u32 m0, s76, 0x1000
	v_mfma_f32_16x16x32_bf16 v[124:127], v[216:219], v[244:247], 0
	global_load_lds_dwordx4 v171, s[72:73]
	s_add_u32 m0, s76, 0x2000
	v_mfma_f32_16x16x32_bf16 v[96:99], v[220:223], v[248:251], 0
	global_load_lds_dwordx4 v180, s[72:73]
	v_mfma_f32_16x16x32_bf16 v[100:103], v[220:223], v[244:247], 0
	v_mfma_f32_16x16x32_bf16 v[104:107], v[224:227], v[248:251], 0
	v_mfma_f32_16x16x32_bf16 v[108:111], v[224:227], v[244:247], 0
	ds_read_b128 v[248:251], v128 offset:28672
	ds_read_b128 v[244:247], v128 offset:29696
	v_mfma_f32_16x16x32_bf16 v[48:51], v[212:215], v[132:135], 0
	s_add_u32 m0, s76, 0x3000
	v_mfma_f32_16x16x32_bf16 v[52:55], v[212:215], v[136:139], 0
	global_load_lds_dwordx4 v181, s[72:73]
	s_add_u32 m0, s76, 0x4000
	v_mfma_f32_16x16x32_bf16 v[56:59], v[216:219], v[132:135], 0
	global_load_lds_dwordx4 v170, s[74:75]
	s_add_u32 m0, s76, 0x5000
	v_mfma_f32_16x16x32_bf16 v[60:63], v[216:219], v[136:139], 0
	global_load_lds_dwordx4 v171, s[74:75]
	s_add_u32 s72, s72, 0x202000
	s_addc_u32 s73, s73, 0
	v_mfma_f32_16x16x32_bf16 v[32:35], v[220:223], v[132:135], 0
	s_add_u32 s74, s74, 0x10000
	s_addc_u32 s75, s75, 0
	v_mfma_f32_16x16x32_bf16 v[36:39], v[220:223], v[136:139], 0
	v_mfma_f32_16x16x32_bf16 v[40:43], v[224:227], v[132:135], 0
	v_mfma_f32_16x16x32_bf16 v[44:47], v[224:227], v[136:139], 0
	s_waitcnt lgkmcnt(2)
	v_mfma_f32_16x16x32_bf16 v[80:83], v[228:231], v[172:175], v[80:83]
	ds_read_b128 v[132:135], v128 offset:32768
	v_mfma_f32_16x16x32_bf16 v[84:87], v[228:231], v[176:179], v[84:87]
	ds_read_b128 v[136:139], v128 offset:33792
	v_mfma_f32_16x16x32_bf16 v[88:91], v[232:235], v[172:175], v[88:91]
	v_mfma_f32_16x16x32_bf16 v[92:95], v[232:235], v[176:179], v[92:95]
	v_mfma_f32_16x16x32_bf16 v[64:67], v[236:239], v[172:175], v[64:67]
	v_mfma_f32_16x16x32_bf16 v[68:71], v[236:239], v[176:179], v[68:71]
	v_mfma_f32_16x16x32_bf16 v[72:75], v[240:243], v[172:175], v[72:75]
	v_mfma_f32_16x16x32_bf16 v[76:79], v[240:243], v[176:179], v[76:79]
	s_waitcnt lgkmcnt(2)
	v_mfma_f32_16x16x32_bf16 v[16:19], v[228:231], v[248:251], v[16:19]
	ds_read_b128 v[172:175], v128 offset:36864
	v_mfma_f32_16x16x32_bf16 v[20:23], v[228:231], v[244:247], v[20:23]
	ds_read_b128 v[176:179], v128 offset:37888
	v_mfma_f32_16x16x32_bf16 v[24:27], v[232:235], v[248:251], v[24:27]
	v_mfma_f32_16x16x32_bf16 v[28:31], v[232:235], v[244:247], v[28:31]
	v_mfma_f32_16x16x32_bf16 v[0:3], v[236:239], v[248:251], v[0:3]
	v_mfma_f32_16x16x32_bf16 v[4:7], v[236:239], v[244:247], v[4:7]
	v_mfma_f32_16x16x32_bf16 v[8:11], v[240:243], v[248:251], v[8:11]
	v_mfma_f32_16x16x32_bf16 v[12:15], v[240:243], v[244:247], v[12:15]
	s_waitcnt lgkmcnt(0)
	s_waitcnt vmcnt(6)
	s_barrier
	ds_read_b128 v[212:215], v167 offset:49152
	ds_read_b128 v[216:219], v167 offset:50176
	v_mfma_f32_16x16x32_bf16 v[112:115], v[228:231], v[132:135], v[112:115]
	ds_read_b128 v[220:223], v167 offset:51200
	ds_read_b128 v[224:227], v167 offset:52224
	v_mfma_f32_16x16x32_bf16 v[116:119], v[228:231], v[136:139], v[116:119]
	ds_read_b128 v[248:251], v128 offset:49152
	ds_read_b128 v[244:247], v128 offset:50176
	s_add_u32 m0, s76, 0x6000
	v_mfma_f32_16x16x32_bf16 v[120:123], v[232:235], v[132:135], v[120:123]
	global_load_lds_dwordx4 v170, s[72:73]
	s_add_u32 m0, s76, 0x7000
	v_mfma_f32_16x16x32_bf16 v[124:127], v[232:235], v[136:139], v[124:127]
	global_load_lds_dwordx4 v171, s[72:73]
	s_add_u32 m0, s76, 0x8000
	v_mfma_f32_16x16x32_bf16 v[96:99], v[236:239], v[132:135], v[96:99]
	global_load_lds_dwordx4 v180, s[72:73]
	v_mfma_f32_16x16x32_bf16 v[100:103], v[236:239], v[136:139], v[100:103]
	v_mfma_f32_16x16x32_bf16 v[104:107], v[240:243], v[132:135], v[104:107]
	v_mfma_f32_16x16x32_bf16 v[108:111], v[240:243], v[136:139], v[108:111]
	ds_read_b128 v[132:135], v128 offset:53248
	ds_read_b128 v[136:139], v128 offset:54272
	v_mfma_f32_16x16x32_bf16 v[48:51], v[228:231], v[172:175], v[48:51]
	s_add_u32 m0, s76, 0x9000
	v_mfma_f32_16x16x32_bf16 v[52:55], v[228:231], v[176:179], v[52:55]
	global_load_lds_dwordx4 v181, s[72:73]
	s_add_u32 m0, s76, 0xa000
	v_mfma_f32_16x16x32_bf16 v[56:59], v[232:235], v[172:175], v[56:59]
	global_load_lds_dwordx4 v170, s[74:75]
	s_add_u32 m0, s76, 0xb000
	v_mfma_f32_16x16x32_bf16 v[60:63], v[232:235], v[176:179], v[60:63]
	global_load_lds_dwordx4 v171, s[74:75]
	s_add_u32 s72, s72, 0x202000
	s_addc_u32 s73, s73, 0
	v_mfma_f32_16x16x32_bf16 v[32:35], v[236:239], v[172:175], v[32:35]
	s_add_u32 s74, s74, 0x10000
	s_addc_u32 s75, s75, 0
	v_mfma_f32_16x16x32_bf16 v[36:39], v[236:239], v[176:179], v[36:39]
	v_mfma_f32_16x16x32_bf16 v[40:43], v[240:243], v[172:175], v[40:43]
	v_mfma_f32_16x16x32_bf16 v[44:47], v[240:243], v[176:179], v[44:47]
	s_waitcnt lgkmcnt(2)
	v_mfma_f32_16x16x32_bf16 v[80:83], v[212:215], v[248:251], v[80:83]
	ds_read_b128 v[172:175], v128 offset:57344
	v_mfma_f32_16x16x32_bf16 v[84:87], v[212:215], v[244:247], v[84:87]
	ds_read_b128 v[176:179], v128 offset:58368
	v_mfma_f32_16x16x32_bf16 v[88:91], v[216:219], v[248:251], v[88:91]
	v_mfma_f32_16x16x32_bf16 v[92:95], v[216:219], v[244:247], v[92:95]
	v_mfma_f32_16x16x32_bf16 v[64:67], v[220:223], v[248:251], v[64:67]
	v_mfma_f32_16x16x32_bf16 v[68:71], v[220:223], v[244:247], v[68:71]
	v_mfma_f32_16x16x32_bf16 v[72:75], v[224:227], v[248:251], v[72:75]
	v_mfma_f32_16x16x32_bf16 v[76:79], v[224:227], v[244:247], v[76:79]
	s_waitcnt lgkmcnt(2)
	v_mfma_f32_16x16x32_bf16 v[16:19], v[212:215], v[132:135], v[16:19]
	ds_read_b128 v[248:251], v128 offset:61440
	v_mfma_f32_16x16x32_bf16 v[20:23], v[212:215], v[136:139], v[20:23]
	ds_read_b128 v[244:247], v128 offset:62464
	v_mfma_f32_16x16x32_bf16 v[24:27], v[216:219], v[132:135], v[24:27]
	v_mfma_f32_16x16x32_bf16 v[28:31], v[216:219], v[136:139], v[28:31]
	v_mfma_f32_16x16x32_bf16 v[0:3], v[220:223], v[132:135], v[0:3]
	v_mfma_f32_16x16x32_bf16 v[4:7], v[220:223], v[136:139], v[4:7]
	v_mfma_f32_16x16x32_bf16 v[8:11], v[224:227], v[132:135], v[8:11]
	v_mfma_f32_16x16x32_bf16 v[12:15], v[224:227], v[136:139], v[12:15]
	s_waitcnt lgkmcnt(0)
	s_waitcnt vmcnt(6)
	s_barrier
	ds_read_b128 v[228:231], v167
	ds_read_b128 v[232:235], v167 offset:1024
	v_mfma_f32_16x16x32_bf16 v[112:115], v[212:215], v[172:175], v[112:115]
	ds_read_b128 v[236:239], v167 offset:2048
	ds_read_b128 v[240:243], v167 offset:3072
	v_mfma_f32_16x16x32_bf16 v[116:119], v[212:215], v[176:179], v[116:119]
	ds_read_b128 v[132:135], v128
	ds_read_b128 v[136:139], v128 offset:1024
	s_add_u32 m0, s76, 0xc000
	v_mfma_f32_16x16x32_bf16 v[120:123], v[216:219], v[172:175], v[120:123]
	global_load_lds_dwordx4 v170, s[72:73]
	s_add_u32 m0, s76, 0xd000
	v_mfma_f32_16x16x32_bf16 v[124:127], v[216:219], v[176:179], v[124:127]
	global_load_lds_dwordx4 v171, s[72:73]
	s_add_u32 m0, s76, 0xe000
	v_mfma_f32_16x16x32_bf16 v[96:99], v[220:223], v[172:175], v[96:99]
	global_load_lds_dwordx4 v180, s[72:73]
	v_mfma_f32_16x16x32_bf16 v[100:103], v[220:223], v[176:179], v[100:103]
	v_mfma_f32_16x16x32_bf16 v[104:107], v[224:227], v[172:175], v[104:107]
	v_mfma_f32_16x16x32_bf16 v[108:111], v[224:227], v[176:179], v[108:111]
	ds_read_b128 v[172:175], v128 offset:4096
	ds_read_b128 v[176:179], v128 offset:5120
	v_mfma_f32_16x16x32_bf16 v[48:51], v[212:215], v[248:251], v[48:51]
	s_add_u32 m0, s76, 0xf000
	v_mfma_f32_16x16x32_bf16 v[52:55], v[212:215], v[244:247], v[52:55]
	global_load_lds_dwordx4 v181, s[72:73]
	s_add_u32 m0, s76, 0x10000
	v_mfma_f32_16x16x32_bf16 v[56:59], v[216:219], v[248:251], v[56:59]
	global_load_lds_dwordx4 v170, s[74:75]
	s_add_u32 m0, s76, 0x11000
	v_mfma_f32_16x16x32_bf16 v[60:63], v[216:219], v[244:247], v[60:63]
	global_load_lds_dwordx4 v171, s[74:75]
	s_add_u32 s72, s72, 0x202000
	s_addc_u32 s73, s73, 0
	v_mfma_f32_16x16x32_bf16 v[32:35], v[220:223], v[248:251], v[32:35]
	s_add_u32 s74, s74, 0x10000
	s_addc_u32 s75, s75, 0
	v_mfma_f32_16x16x32_bf16 v[36:39], v[220:223], v[244:247], v[36:39]
	v_mfma_f32_16x16x32_bf16 v[40:43], v[224:227], v[248:251], v[40:43]
	v_mfma_f32_16x16x32_bf16 v[44:47], v[224:227], v[244:247], v[44:47]
	s_waitcnt lgkmcnt(2)
	v_mfma_f32_16x16x32_bf16 v[80:83], v[228:231], v[132:135], v[80:83]
	ds_read_b128 v[248:251], v128 offset:8192
	v_mfma_f32_16x16x32_bf16 v[84:87], v[228:231], v[136:139], v[84:87]
	ds_read_b128 v[244:247], v128 offset:9216
	v_mfma_f32_16x16x32_bf16 v[88:91], v[232:235], v[132:135], v[88:91]
	v_mfma_f32_16x16x32_bf16 v[92:95], v[232:235], v[136:139], v[92:95]
	v_mfma_f32_16x16x32_bf16 v[64:67], v[236:239], v[132:135], v[64:67]
	v_mfma_f32_16x16x32_bf16 v[68:71], v[236:239], v[136:139], v[68:71]
	v_mfma_f32_16x16x32_bf16 v[72:75], v[240:243], v[132:135], v[72:75]
	v_mfma_f32_16x16x32_bf16 v[76:79], v[240:243], v[136:139], v[76:79]
	s_waitcnt lgkmcnt(2)
	v_mfma_f32_16x16x32_bf16 v[16:19], v[228:231], v[172:175], v[16:19]
	ds_read_b128 v[132:135], v128 offset:12288
	v_mfma_f32_16x16x32_bf16 v[20:23], v[228:231], v[176:179], v[20:23]
	ds_read_b128 v[136:139], v128 offset:13312
	v_mfma_f32_16x16x32_bf16 v[24:27], v[232:235], v[172:175], v[24:27]
	v_mfma_f32_16x16x32_bf16 v[28:31], v[232:235], v[176:179], v[28:31]
	v_mfma_f32_16x16x32_bf16 v[0:3], v[236:239], v[172:175], v[0:3]
	v_mfma_f32_16x16x32_bf16 v[4:7], v[236:239], v[176:179], v[4:7]
	v_mfma_f32_16x16x32_bf16 v[8:11], v[240:243], v[172:175], v[8:11]
	v_mfma_f32_16x16x32_bf16 v[12:15], v[240:243], v[176:179], v[12:15]
	s_waitcnt lgkmcnt(0)
	s_waitcnt vmcnt(6)
	s_barrier
	ds_read_b128 v[212:215], v167 offset:24576
	ds_read_b128 v[216:219], v167 offset:25600
	v_mfma_f32_16x16x32_bf16 v[112:115], v[228:231], v[248:251], v[112:115]
	ds_read_b128 v[220:223], v167 offset:26624
	ds_read_b128 v[224:227], v167 offset:27648
	v_mfma_f32_16x16x32_bf16 v[116:119], v[228:231], v[244:247], v[116:119]
	ds_read_b128 v[172:175], v128 offset:24576
	ds_read_b128 v[176:179], v128 offset:25600
	s_add_u32 m0, s76, 0x0
	v_mfma_f32_16x16x32_bf16 v[120:123], v[232:235], v[248:251], v[120:123]
	global_load_lds_dwordx4 v170, s[72:73]
	s_add_u32 m0, s76, 0x1000
	v_mfma_f32_16x16x32_bf16 v[124:127], v[232:235], v[244:247], v[124:127]
	global_load_lds_dwordx4 v171, s[72:73]
	s_add_u32 m0, s76, 0x2000
	v_mfma_f32_16x16x32_bf16 v[96:99], v[236:239], v[248:251], v[96:99]
	global_load_lds_dwordx4 v180, s[72:73]
	v_mfma_f32_16x16x32_bf16 v[100:103], v[236:239], v[244:247], v[100:103]
	v_mfma_f32_16x16x32_bf16 v[104:107], v[240:243], v[248:251], v[104:107]
	v_mfma_f32_16x16x32_bf16 v[108:111], v[240:243], v[244:247], v[108:111]
	ds_read_b128 v[248:251], v128 offset:28672
	ds_read_b128 v[244:247], v128 offset:29696
	v_mfma_f32_16x16x32_bf16 v[48:51], v[228:231], v[132:135], v[48:51]
	s_add_u32 m0, s76, 0x3000
	v_mfma_f32_16x16x32_bf16 v[52:55], v[228:231], v[136:139], v[52:55]
	global_load_lds_dwordx4 v181, s[72:73]
	s_add_u32 m0, s76, 0x4000
	v_mfma_f32_16x16x32_bf16 v[56:59], v[232:235], v[132:135], v[56:59]
	global_load_lds_dwordx4 v170, s[74:75]
	s_add_u32 m0, s76, 0x5000
	v_mfma_f32_16x16x32_bf16 v[60:63], v[232:235], v[136:139], v[60:63]
	global_load_lds_dwordx4 v171, s[74:75]
	s_add_u32 s72, s72, 0x202000
	s_addc_u32 s73, s73, 0
	v_mfma_f32_16x16x32_bf16 v[32:35], v[236:239], v[132:135], v[32:35]
	s_add_u32 s74, s74, 0x10000
	s_addc_u32 s75, s75, 0
	v_mfma_f32_16x16x32_bf16 v[36:39], v[236:239], v[136:139], v[36:39]
	v_mfma_f32_16x16x32_bf16 v[40:43], v[240:243], v[132:135], v[40:43]
	v_mfma_f32_16x16x32_bf16 v[44:47], v[240:243], v[136:139], v[44:47]
	s_waitcnt lgkmcnt(2)
	v_mfma_f32_16x16x32_bf16 v[80:83], v[212:215], v[172:175], v[80:83]
	ds_read_b128 v[132:135], v128 offset:32768
	v_mfma_f32_16x16x32_bf16 v[84:87], v[212:215], v[176:179], v[84:87]
	ds_read_b128 v[136:139], v128 offset:33792
	v_mfma_f32_16x16x32_bf16 v[88:91], v[216:219], v[172:175], v[88:91]
	v_mfma_f32_16x16x32_bf16 v[92:95], v[216:219], v[176:179], v[92:95]
	v_mfma_f32_16x16x32_bf16 v[64:67], v[220:223], v[172:175], v[64:67]
	v_mfma_f32_16x16x32_bf16 v[68:71], v[220:223], v[176:179], v[68:71]
	v_mfma_f32_16x16x32_bf16 v[72:75], v[224:227], v[172:175], v[72:75]
	v_mfma_f32_16x16x32_bf16 v[76:79], v[224:227], v[176:179], v[76:79]
	s_waitcnt lgkmcnt(2)
	v_mfma_f32_16x16x32_bf16 v[16:19], v[212:215], v[248:251], v[16:19]
	ds_read_b128 v[172:175], v128 offset:36864
	v_mfma_f32_16x16x32_bf16 v[20:23], v[212:215], v[244:247], v[20:23]
	ds_read_b128 v[176:179], v128 offset:37888
	v_mfma_f32_16x16x32_bf16 v[24:27], v[216:219], v[248:251], v[24:27]
	v_mfma_f32_16x16x32_bf16 v[28:31], v[216:219], v[244:247], v[28:31]
	v_mfma_f32_16x16x32_bf16 v[0:3], v[220:223], v[248:251], v[0:3]
	v_mfma_f32_16x16x32_bf16 v[4:7], v[220:223], v[244:247], v[4:7]
	v_mfma_f32_16x16x32_bf16 v[8:11], v[224:227], v[248:251], v[8:11]
	v_mfma_f32_16x16x32_bf16 v[12:15], v[224:227], v[244:247], v[12:15]
	s_waitcnt lgkmcnt(0)
	s_waitcnt vmcnt(6)
	s_barrier
	ds_read_b128 v[228:231], v167 offset:49152
	ds_read_b128 v[232:235], v167 offset:50176
	v_mfma_f32_16x16x32_bf16 v[112:115], v[212:215], v[132:135], v[112:115]
	ds_read_b128 v[236:239], v167 offset:51200
	ds_read_b128 v[240:243], v167 offset:52224
	v_mfma_f32_16x16x32_bf16 v[116:119], v[212:215], v[136:139], v[116:119]
	ds_read_b128 v[248:251], v128 offset:49152
	ds_read_b128 v[244:247], v128 offset:50176
	s_add_u32 m0, s76, 0x6000
	v_mfma_f32_16x16x32_bf16 v[120:123], v[216:219], v[132:135], v[120:123]
	global_load_lds_dwordx4 v170, s[72:73]
	s_add_u32 m0, s76, 0x7000
	v_mfma_f32_16x16x32_bf16 v[124:127], v[216:219], v[136:139], v[124:127]
	global_load_lds_dwordx4 v171, s[72:73]
	s_add_u32 m0, s76, 0x8000
	v_mfma_f32_16x16x32_bf16 v[96:99], v[220:223], v[132:135], v[96:99]
	global_load_lds_dwordx4 v180, s[72:73]
	v_mfma_f32_16x16x32_bf16 v[100:103], v[220:223], v[136:139], v[100:103]
	v_mfma_f32_16x16x32_bf16 v[104:107], v[224:227], v[132:135], v[104:107]
	v_mfma_f32_16x16x32_bf16 v[108:111], v[224:227], v[136:139], v[108:111]
	ds_read_b128 v[132:135], v128 offset:53248
	ds_read_b128 v[136:139], v128 offset:54272
	v_mfma_f32_16x16x32_bf16 v[48:51], v[212:215], v[172:175], v[48:51]
	s_add_u32 m0, s76, 0x9000
	v_mfma_f32_16x16x32_bf16 v[52:55], v[212:215], v[176:179], v[52:55]
	global_load_lds_dwordx4 v181, s[72:73]
	s_add_u32 m0, s76, 0xa000
	v_mfma_f32_16x16x32_bf16 v[56:59], v[216:219], v[172:175], v[56:59]
	global_load_lds_dwordx4 v170, s[74:75]
	s_add_u32 m0, s76, 0xb000
	v_mfma_f32_16x16x32_bf16 v[60:63], v[216:219], v[176:179], v[60:63]
	global_load_lds_dwordx4 v171, s[74:75]
	s_add_u32 s72, s72, 0x202000
	s_addc_u32 s73, s73, 0
	v_mfma_f32_16x16x32_bf16 v[32:35], v[220:223], v[172:175], v[32:35]
	s_add_u32 s74, s74, 0x10000
	s_addc_u32 s75, s75, 0
	v_mfma_f32_16x16x32_bf16 v[36:39], v[220:223], v[176:179], v[36:39]
	v_mfma_f32_16x16x32_bf16 v[40:43], v[224:227], v[172:175], v[40:43]
	v_mfma_f32_16x16x32_bf16 v[44:47], v[224:227], v[176:179], v[44:47]
	s_waitcnt lgkmcnt(2)
	v_mfma_f32_16x16x32_bf16 v[80:83], v[228:231], v[248:251], v[80:83]
	ds_read_b128 v[172:175], v128 offset:57344
	v_mfma_f32_16x16x32_bf16 v[84:87], v[228:231], v[244:247], v[84:87]
	ds_read_b128 v[176:179], v128 offset:58368
	v_mfma_f32_16x16x32_bf16 v[88:91], v[232:235], v[248:251], v[88:91]
	v_mfma_f32_16x16x32_bf16 v[92:95], v[232:235], v[244:247], v[92:95]
	v_mfma_f32_16x16x32_bf16 v[64:67], v[236:239], v[248:251], v[64:67]
	v_mfma_f32_16x16x32_bf16 v[68:71], v[236:239], v[244:247], v[68:71]
	v_mfma_f32_16x16x32_bf16 v[72:75], v[240:243], v[248:251], v[72:75]
	v_mfma_f32_16x16x32_bf16 v[76:79], v[240:243], v[244:247], v[76:79]
	s_waitcnt lgkmcnt(2)
	v_mfma_f32_16x16x32_bf16 v[16:19], v[228:231], v[132:135], v[16:19]
	ds_read_b128 v[248:251], v128 offset:61440
	v_mfma_f32_16x16x32_bf16 v[20:23], v[228:231], v[136:139], v[20:23]
	ds_read_b128 v[244:247], v128 offset:62464
	v_mfma_f32_16x16x32_bf16 v[24:27], v[232:235], v[132:135], v[24:27]
	v_mfma_f32_16x16x32_bf16 v[28:31], v[232:235], v[136:139], v[28:31]
	v_mfma_f32_16x16x32_bf16 v[0:3], v[236:239], v[132:135], v[0:3]
	v_mfma_f32_16x16x32_bf16 v[4:7], v[236:239], v[136:139], v[4:7]
	v_mfma_f32_16x16x32_bf16 v[8:11], v[240:243], v[132:135], v[8:11]
	v_mfma_f32_16x16x32_bf16 v[12:15], v[240:243], v[136:139], v[12:15]
	s_waitcnt lgkmcnt(0)
	s_waitcnt vmcnt(6)
	s_barrier
	ds_read_b128 v[212:215], v167
	ds_read_b128 v[216:219], v167 offset:1024
	v_mfma_f32_16x16x32_bf16 v[112:115], v[228:231], v[172:175], v[112:115]
	ds_read_b128 v[220:223], v167 offset:2048
	ds_read_b128 v[224:227], v167 offset:3072
	v_mfma_f32_16x16x32_bf16 v[116:119], v[228:231], v[176:179], v[116:119]
	ds_read_b128 v[132:135], v128
	ds_read_b128 v[136:139], v128 offset:1024
	s_add_u32 m0, s76, 0xc000
	v_mfma_f32_16x16x32_bf16 v[120:123], v[232:235], v[172:175], v[120:123]
	global_load_lds_dwordx4 v170, s[72:73]
	s_add_u32 m0, s76, 0xd000
	v_mfma_f32_16x16x32_bf16 v[124:127], v[232:235], v[176:179], v[124:127]
	global_load_lds_dwordx4 v171, s[72:73]
	s_add_u32 m0, s76, 0xe000
	v_mfma_f32_16x16x32_bf16 v[96:99], v[236:239], v[172:175], v[96:99]
	global_load_lds_dwordx4 v180, s[72:73]
	v_mfma_f32_16x16x32_bf16 v[100:103], v[236:239], v[176:179], v[100:103]
	v_mfma_f32_16x16x32_bf16 v[104:107], v[240:243], v[172:175], v[104:107]
	v_mfma_f32_16x16x32_bf16 v[108:111], v[240:243], v[176:179], v[108:111]
	ds_read_b128 v[172:175], v128 offset:4096
	ds_read_b128 v[176:179], v128 offset:5120
	v_mfma_f32_16x16x32_bf16 v[48:51], v[228:231], v[248:251], v[48:51]
	s_add_u32 m0, s76, 0xf000
	v_mfma_f32_16x16x32_bf16 v[52:55], v[228:231], v[244:247], v[52:55]
	global_load_lds_dwordx4 v181, s[72:73]
	s_add_u32 m0, s76, 0x10000
	v_mfma_f32_16x16x32_bf16 v[56:59], v[232:235], v[248:251], v[56:59]
	global_load_lds_dwordx4 v170, s[74:75]
	s_add_u32 m0, s76, 0x11000
	v_mfma_f32_16x16x32_bf16 v[60:63], v[232:235], v[244:247], v[60:63]
	global_load_lds_dwordx4 v171, s[74:75]
	s_add_u32 s72, s72, 0x202000
	s_addc_u32 s73, s73, 0
	v_mfma_f32_16x16x32_bf16 v[32:35], v[236:239], v[248:251], v[32:35]
	s_add_u32 s74, s74, 0x10000
	s_addc_u32 s75, s75, 0
	v_mfma_f32_16x16x32_bf16 v[36:39], v[236:239], v[244:247], v[36:39]
	v_mfma_f32_16x16x32_bf16 v[40:43], v[240:243], v[248:251], v[40:43]
	v_mfma_f32_16x16x32_bf16 v[44:47], v[240:243], v[244:247], v[44:47]
	s_mov_b32 s77, 5
.Lgemm_p3_loop:
	s_waitcnt lgkmcnt(2)
	v_mfma_f32_16x16x32_bf16 v[80:83], v[212:215], v[132:135], v[80:83]
	ds_read_b128 v[248:251], v128 offset:8192
	v_mfma_f32_16x16x32_bf16 v[84:87], v[212:215], v[136:139], v[84:87]
	ds_read_b128 v[244:247], v128 offset:9216
	v_mfma_f32_16x16x32_bf16 v[88:91], v[216:219], v[132:135], v[88:91]
	v_mfma_f32_16x16x32_bf16 v[92:95], v[216:219], v[136:139], v[92:95]
	v_mfma_f32_16x16x32_bf16 v[64:67], v[220:223], v[132:135], v[64:67]
	v_mfma_f32_16x16x32_bf16 v[68:71], v[220:223], v[136:139], v[68:71]
	v_mfma_f32_16x16x32_bf16 v[72:75], v[224:227], v[132:135], v[72:75]
	v_mfma_f32_16x16x32_bf16 v[76:79], v[224:227], v[136:139], v[76:79]
	s_waitcnt lgkmcnt(2)
	v_mfma_f32_16x16x32_bf16 v[16:19], v[212:215], v[172:175], v[16:19]
	ds_read_b128 v[132:135], v128 offset:12288
	v_mfma_f32_16x16x32_bf16 v[20:23], v[212:215], v[176:179], v[20:23]
	ds_read_b128 v[136:139], v128 offset:13312
	v_mfma_f32_16x16x32_bf16 v[24:27], v[216:219], v[172:175], v[24:27]
	v_mfma_f32_16x16x32_bf16 v[28:31], v[216:219], v[176:179], v[28:31]
	v_mfma_f32_16x16x32_bf16 v[0:3], v[220:223], v[172:175], v[0:3]
	v_mfma_f32_16x16x32_bf16 v[4:7], v[220:223], v[176:179], v[4:7]
	v_mfma_f32_16x16x32_bf16 v[8:11], v[224:227], v[172:175], v[8:11]
	v_mfma_f32_16x16x32_bf16 v[12:15], v[224:227], v[176:179], v[12:15]
	s_waitcnt lgkmcnt(0)
	s_waitcnt vmcnt(6)
	s_barrier
	ds_read_b128 v[228:231], v167 offset:24576
	ds_read_b128 v[232:235], v167 offset:25600
	v_mfma_f32_16x16x32_bf16 v[112:115], v[212:215], v[248:251], v[112:115]
	ds_read_b128 v[236:239], v167 offset:26624
	ds_read_b128 v[240:243], v167 offset:27648
	v_mfma_f32_16x16x32_bf16 v[116:119], v[212:215], v[244:247], v[116:119]
	ds_read_b128 v[172:175], v128 offset:24576
	ds_read_b128 v[176:179], v128 offset:25600
	s_add_u32 m0, s76, 0x0
	v_mfma_f32_16x16x32_bf16 v[120:123], v[216:219], v[248:251], v[120:123]
	global_load_lds_dwordx4 v170, s[72:73]
	s_add_u32 m0, s76, 0x1000
	v_mfma_f32_16x16x32_bf16 v[124:127], v[216:219], v[244:247], v[124:127]
	global_load_lds_dwordx4 v171, s[72:73]
	s_add_u32 m0, s76, 0x2000
	v_mfma_f32_16x16x32_bf16 v[96:99], v[220:223], v[248:251], v[96:99]
	global_load_lds_dwordx4 v180, s[72:73]
	v_mfma_f32_16x16x32_bf16 v[100:103], v[220:223], v[244:247], v[100:103]
	v_mfma_f32_16x16x32_bf16 v[104:107], v[224:227], v[248:251], v[104:107]
	v_mfma_f32_16x16x32_bf16 v[108:111], v[224:227], v[244:247], v[108:111]
	ds_read_b128 v[248:251], v128 offset:28672
	ds_read_b128 v[244:247], v128 offset:29696
	v_mfma_f32_16x16x32_bf16 v[48:51], v[212:215], v[132:135], v[48:51]
	s_add_u32 m0, s76, 0x3000
	v_mfma_f32_16x16x32_bf16 v[52:55], v[212:215], v[136:139], v[52:55]
	global_load_lds_dwordx4 v181, s[72:73]
	s_add_u32 m0, s76, 0x4000
	v_mfma_f32_16x16x32_bf16 v[56:59], v[216:219], v[132:135], v[56:59]
	global_load_lds_dwordx4 v170, s[74:75]
	s_add_u32 m0, s76, 0x5000
	v_mfma_f32_16x16x32_bf16 v[60:63], v[216:219], v[136:139], v[60:63]
	global_load_lds_dwordx4 v171, s[74:75]
	s_add_u32 s72, s72, 0x202000
	s_addc_u32 s73, s73, 0
	v_mfma_f32_16x16x32_bf16 v[32:35], v[220:223], v[132:135], v[32:35]
	s_add_u32 s74, s74, 0x10000
	s_addc_u32 s75, s75, 0
	v_mfma_f32_16x16x32_bf16 v[36:39], v[220:223], v[136:139], v[36:39]
	v_mfma_f32_16x16x32_bf16 v[40:43], v[224:227], v[132:135], v[40:43]
	v_mfma_f32_16x16x32_bf16 v[44:47], v[224:227], v[136:139], v[44:47]
	s_waitcnt lgkmcnt(2)
	v_mfma_f32_16x16x32_bf16 v[80:83], v[228:231], v[172:175], v[80:83]
	ds_read_b128 v[132:135], v128 offset:32768
	v_mfma_f32_16x16x32_bf16 v[84:87], v[228:231], v[176:179], v[84:87]
	ds_read_b128 v[136:139], v128 offset:33792
	v_mfma_f32_16x16x32_bf16 v[88:91], v[232:235], v[172:175], v[88:91]
	v_mfma_f32_16x16x32_bf16 v[92:95], v[232:235], v[176:179], v[92:95]
	v_mfma_f32_16x16x32_bf16 v[64:67], v[236:239], v[172:175], v[64:67]
	v_mfma_f32_16x16x32_bf16 v[68:71], v[236:239], v[176:179], v[68:71]
	v_mfma_f32_16x16x32_bf16 v[72:75], v[240:243], v[172:175], v[72:75]
	v_mfma_f32_16x16x32_bf16 v[76:79], v[240:243], v[176:179], v[76:79]
	s_waitcnt lgkmcnt(2)
	v_mfma_f32_16x16x32_bf16 v[16:19], v[228:231], v[248:251], v[16:19]
	ds_read_b128 v[172:175], v128 offset:36864
	v_mfma_f32_16x16x32_bf16 v[20:23], v[228:231], v[244:247], v[20:23]
	ds_read_b128 v[176:179], v128 offset:37888
	v_mfma_f32_16x16x32_bf16 v[24:27], v[232:235], v[248:251], v[24:27]
	v_mfma_f32_16x16x32_bf16 v[28:31], v[232:235], v[244:247], v[28:31]
	v_mfma_f32_16x16x32_bf16 v[0:3], v[236:239], v[248:251], v[0:3]
	v_mfma_f32_16x16x32_bf16 v[4:7], v[236:239], v[244:247], v[4:7]
	v_mfma_f32_16x16x32_bf16 v[8:11], v[240:243], v[248:251], v[8:11]
	v_mfma_f32_16x16x32_bf16 v[12:15], v[240:243], v[244:247], v[12:15]
	s_waitcnt lgkmcnt(0)
	s_waitcnt vmcnt(6)
	s_barrier
	ds_read_b128 v[212:215], v167 offset:49152
	ds_read_b128 v[216:219], v167 offset:50176
	v_mfma_f32_16x16x32_bf16 v[112:115], v[228:231], v[132:135], v[112:115]
	ds_read_b128 v[220:223], v167 offset:51200
	ds_read_b128 v[224:227], v167 offset:52224
	v_mfma_f32_16x16x32_bf16 v[116:119], v[228:231], v[136:139], v[116:119]
	ds_read_b128 v[248:251], v128 offset:49152
	ds_read_b128 v[244:247], v128 offset:50176
	s_add_u32 m0, s76, 0x6000
	v_mfma_f32_16x16x32_bf16 v[120:123], v[232:235], v[132:135], v[120:123]
	global_load_lds_dwordx4 v170, s[72:73]
	s_add_u32 m0, s76, 0x7000
	v_mfma_f32_16x16x32_bf16 v[124:127], v[232:235], v[136:139], v[124:127]
	global_load_lds_dwordx4 v171, s[72:73]
	s_add_u32 m0, s76, 0x8000
	v_mfma_f32_16x16x32_bf16 v[96:99], v[236:239], v[132:135], v[96:99]
	global_load_lds_dwordx4 v180, s[72:73]
	v_mfma_f32_16x16x32_bf16 v[100:103], v[236:239], v[136:139], v[100:103]
	v_mfma_f32_16x16x32_bf16 v[104:107], v[240:243], v[132:135], v[104:107]
	v_mfma_f32_16x16x32_bf16 v[108:111], v[240:243], v[136:139], v[108:111]
	ds_read_b128 v[132:135], v128 offset:53248
	ds_read_b128 v[136:139], v128 offset:54272
	v_mfma_f32_16x16x32_bf16 v[48:51], v[228:231], v[172:175], v[48:51]
	s_add_u32 m0, s76, 0x9000
	v_mfma_f32_16x16x32_bf16 v[52:55], v[228:231], v[176:179], v[52:55]
	global_load_lds_dwordx4 v181, s[72:73]
	s_add_u32 m0, s76, 0xa000
	v_mfma_f32_16x16x32_bf16 v[56:59], v[232:235], v[172:175], v[56:59]
	global_load_lds_dwordx4 v170, s[74:75]
	s_add_u32 m0, s76, 0xb000
	v_mfma_f32_16x16x32_bf16 v[60:63], v[232:235], v[176:179], v[60:63]
	global_load_lds_dwordx4 v171, s[74:75]
	s_add_u32 s72, s72, 0x202000
	s_addc_u32 s73, s73, 0
	v_mfma_f32_16x16x32_bf16 v[32:35], v[236:239], v[172:175], v[32:35]
	s_add_u32 s74, s74, 0x10000
	s_addc_u32 s75, s75, 0
	v_mfma_f32_16x16x32_bf16 v[36:39], v[236:239], v[176:179], v[36:39]
	v_mfma_f32_16x16x32_bf16 v[40:43], v[240:243], v[172:175], v[40:43]
	v_mfma_f32_16x16x32_bf16 v[44:47], v[240:243], v[176:179], v[44:47]
	s_waitcnt lgkmcnt(2)
	v_mfma_f32_16x16x32_bf16 v[80:83], v[212:215], v[248:251], v[80:83]
	ds_read_b128 v[172:175], v128 offset:57344
	v_mfma_f32_16x16x32_bf16 v[84:87], v[212:215], v[244:247], v[84:87]
	ds_read_b128 v[176:179], v128 offset:58368
	v_mfma_f32_16x16x32_bf16 v[88:91], v[216:219], v[248:251], v[88:91]
	v_mfma_f32_16x16x32_bf16 v[92:95], v[216:219], v[244:247], v[92:95]
	v_mfma_f32_16x16x32_bf16 v[64:67], v[220:223], v[248:251], v[64:67]
	v_mfma_f32_16x16x32_bf16 v[68:71], v[220:223], v[244:247], v[68:71]
	v_mfma_f32_16x16x32_bf16 v[72:75], v[224:227], v[248:251], v[72:75]
	v_mfma_f32_16x16x32_bf16 v[76:79], v[224:227], v[244:247], v[76:79]
	s_waitcnt lgkmcnt(2)
	v_mfma_f32_16x16x32_bf16 v[16:19], v[212:215], v[132:135], v[16:19]
	ds_read_b128 v[248:251], v128 offset:61440
	v_mfma_f32_16x16x32_bf16 v[20:23], v[212:215], v[136:139], v[20:23]
	ds_read_b128 v[244:247], v128 offset:62464
	v_mfma_f32_16x16x32_bf16 v[24:27], v[216:219], v[132:135], v[24:27]
	v_mfma_f32_16x16x32_bf16 v[28:31], v[216:219], v[136:139], v[28:31]
	v_mfma_f32_16x16x32_bf16 v[0:3], v[220:223], v[132:135], v[0:3]
	v_mfma_f32_16x16x32_bf16 v[4:7], v[220:223], v[136:139], v[4:7]
	v_mfma_f32_16x16x32_bf16 v[8:11], v[224:227], v[132:135], v[8:11]
	v_mfma_f32_16x16x32_bf16 v[12:15], v[224:227], v[136:139], v[12:15]
	s_waitcnt lgkmcnt(0)
	s_waitcnt vmcnt(6)
	s_barrier
	ds_read_b128 v[228:231], v167
	ds_read_b128 v[232:235], v167 offset:1024
	v_mfma_f32_16x16x32_bf16 v[112:115], v[212:215], v[172:175], v[112:115]
	ds_read_b128 v[236:239], v167 offset:2048
	ds_read_b128 v[240:243], v167 offset:3072
	v_mfma_f32_16x16x32_bf16 v[116:119], v[212:215], v[176:179], v[116:119]
	ds_read_b128 v[132:135], v128
	ds_read_b128 v[136:139], v128 offset:1024
	s_add_u32 m0, s76, 0xc000
	v_mfma_f32_16x16x32_bf16 v[120:123], v[216:219], v[172:175], v[120:123]
	global_load_lds_dwordx4 v170, s[72:73]
	s_add_u32 m0, s76, 0xd000
	v_mfma_f32_16x16x32_bf16 v[124:127], v[216:219], v[176:179], v[124:127]
	global_load_lds_dwordx4 v171, s[72:73]
	s_add_u32 m0, s76, 0xe000
	v_mfma_f32_16x16x32_bf16 v[96:99], v[220:223], v[172:175], v[96:99]
	global_load_lds_dwordx4 v180, s[72:73]
	v_mfma_f32_16x16x32_bf16 v[100:103], v[220:223], v[176:179], v[100:103]
	v_mfma_f32_16x16x32_bf16 v[104:107], v[224:227], v[172:175], v[104:107]
	v_mfma_f32_16x16x32_bf16 v[108:111], v[224:227], v[176:179], v[108:111]
	ds_read_b128 v[172:175], v128 offset:4096
	ds_read_b128 v[176:179], v128 offset:5120
	v_mfma_f32_16x16x32_bf16 v[48:51], v[212:215], v[248:251], v[48:51]
	s_add_u32 m0, s76, 0xf000
	v_mfma_f32_16x16x32_bf16 v[52:55], v[212:215], v[244:247], v[52:55]
	global_load_lds_dwordx4 v181, s[72:73]
	s_add_u32 m0, s76, 0x10000
	v_mfma_f32_16x16x32_bf16 v[56:59], v[216:219], v[248:251], v[56:59]
	global_load_lds_dwordx4 v170, s[74:75]
	s_add_u32 m0, s76, 0x11000
	v_mfma_f32_16x16x32_bf16 v[60:63], v[216:219], v[244:247], v[60:63]
	global_load_lds_dwordx4 v171, s[74:75]
	s_add_u32 s72, s72, 0x202000
	s_addc_u32 s73, s73, 0
	v_mfma_f32_16x16x32_bf16 v[32:35], v[220:223], v[248:251], v[32:35]
	s_add_u32 s74, s74, 0x10000
	s_addc_u32 s75, s75, 0
	v_mfma_f32_16x16x32_bf16 v[36:39], v[220:223], v[244:247], v[36:39]
	v_mfma_f32_16x16x32_bf16 v[40:43], v[224:227], v[248:251], v[40:43]
	v_mfma_f32_16x16x32_bf16 v[44:47], v[224:227], v[244:247], v[44:47]
	s_waitcnt lgkmcnt(2)
	v_mfma_f32_16x16x32_bf16 v[80:83], v[228:231], v[132:135], v[80:83]
	ds_read_b128 v[248:251], v128 offset:8192
	v_mfma_f32_16x16x32_bf16 v[84:87], v[228:231], v[136:139], v[84:87]
	ds_read_b128 v[244:247], v128 offset:9216
	v_mfma_f32_16x16x32_bf16 v[88:91], v[232:235], v[132:135], v[88:91]
	v_mfma_f32_16x16x32_bf16 v[92:95], v[232:235], v[136:139], v[92:95]
	v_mfma_f32_16x16x32_bf16 v[64:67], v[236:239], v[132:135], v[64:67]
	v_mfma_f32_16x16x32_bf16 v[68:71], v[236:239], v[136:139], v[68:71]
	v_mfma_f32_16x16x32_bf16 v[72:75], v[240:243], v[132:135], v[72:75]
	v_mfma_f32_16x16x32_bf16 v[76:79], v[240:243], v[136:139], v[76:79]
	s_waitcnt lgkmcnt(2)
	v_mfma_f32_16x16x32_bf16 v[16:19], v[228:231], v[172:175], v[16:19]
	ds_read_b128 v[132:135], v128 offset:12288
	v_mfma_f32_16x16x32_bf16 v[20:23], v[228:231], v[176:179], v[20:23]
	ds_read_b128 v[136:139], v128 offset:13312
	v_mfma_f32_16x16x32_bf16 v[24:27], v[232:235], v[172:175], v[24:27]
	v_mfma_f32_16x16x32_bf16 v[28:31], v[232:235], v[176:179], v[28:31]
	v_mfma_f32_16x16x32_bf16 v[0:3], v[236:239], v[172:175], v[0:3]
	v_mfma_f32_16x16x32_bf16 v[4:7], v[236:239], v[176:179], v[4:7]
	v_mfma_f32_16x16x32_bf16 v[8:11], v[240:243], v[172:175], v[8:11]
	v_mfma_f32_16x16x32_bf16 v[12:15], v[240:243], v[176:179], v[12:15]
	s_waitcnt lgkmcnt(0)
	s_waitcnt vmcnt(6)
	s_barrier
	ds_read_b128 v[212:215], v167 offset:24576
	ds_read_b128 v[216:219], v167 offset:25600
	v_mfma_f32_16x16x32_bf16 v[112:115], v[228:231], v[248:251], v[112:115]
	ds_read_b128 v[220:223], v167 offset:26624
	ds_read_b128 v[224:227], v167 offset:27648
	v_mfma_f32_16x16x32_bf16 v[116:119], v[228:231], v[244:247], v[116:119]
	ds_read_b128 v[172:175], v128 offset:24576
	ds_read_b128 v[176:179], v128 offset:25600
	s_add_u32 m0, s76, 0x0
	v_mfma_f32_16x16x32_bf16 v[120:123], v[232:235], v[248:251], v[120:123]
	global_load_lds_dwordx4 v170, s[72:73]
	s_add_u32 m0, s76, 0x1000
	v_mfma_f32_16x16x32_bf16 v[124:127], v[232:235], v[244:247], v[124:127]
	global_load_lds_dwordx4 v171, s[72:73]
	s_add_u32 m0, s76, 0x2000
	v_mfma_f32_16x16x32_bf16 v[96:99], v[236:239], v[248:251], v[96:99]
	global_load_lds_dwordx4 v180, s[72:73]
	v_mfma_f32_16x16x32_bf16 v[100:103], v[236:239], v[244:247], v[100:103]
	v_mfma_f32_16x16x32_bf16 v[104:107], v[240:243], v[248:251], v[104:107]
	v_mfma_f32_16x16x32_bf16 v[108:111], v[240:243], v[244:247], v[108:111]
	ds_read_b128 v[248:251], v128 offset:28672
	ds_read_b128 v[244:247], v128 offset:29696
	v_mfma_f32_16x16x32_bf16 v[48:51], v[228:231], v[132:135], v[48:51]
	s_add_u32 m0, s76, 0x3000
	v_mfma_f32_16x16x32_bf16 v[52:55], v[228:231], v[136:139], v[52:55]
	global_load_lds_dwordx4 v181, s[72:73]
	s_add_u32 m0, s76, 0x4000
	v_mfma_f32_16x16x32_bf16 v[56:59], v[232:235], v[132:135], v[56:59]
	global_load_lds_dwordx4 v170, s[74:75]
	s_add_u32 m0, s76, 0x5000
	v_mfma_f32_16x16x32_bf16 v[60:63], v[232:235], v[136:139], v[60:63]
	global_load_lds_dwordx4 v171, s[74:75]
	s_add_u32 s72, s72, 0x202000
	s_addc_u32 s73, s73, 0
	v_mfma_f32_16x16x32_bf16 v[32:35], v[236:239], v[132:135], v[32:35]
	s_add_u32 s74, s74, 0x10000
	s_addc_u32 s75, s75, 0
	v_mfma_f32_16x16x32_bf16 v[36:39], v[236:239], v[136:139], v[36:39]
	v_mfma_f32_16x16x32_bf16 v[40:43], v[240:243], v[132:135], v[40:43]
	v_mfma_f32_16x16x32_bf16 v[44:47], v[240:243], v[136:139], v[44:47]
	s_waitcnt lgkmcnt(2)
	v_mfma_f32_16x16x32_bf16 v[80:83], v[212:215], v[172:175], v[80:83]
	ds_read_b128 v[132:135], v128 offset:32768
	v_mfma_f32_16x16x32_bf16 v[84:87], v[212:215], v[176:179], v[84:87]
	ds_read_b128 v[136:139], v128 offset:33792
	v_mfma_f32_16x16x32_bf16 v[88:91], v[216:219], v[172:175], v[88:91]
	v_mfma_f32_16x16x32_bf16 v[92:95], v[216:219], v[176:179], v[92:95]
	v_mfma_f32_16x16x32_bf16 v[64:67], v[220:223], v[172:175], v[64:67]
	v_mfma_f32_16x16x32_bf16 v[68:71], v[220:223], v[176:179], v[68:71]
	v_mfma_f32_16x16x32_bf16 v[72:75], v[224:227], v[172:175], v[72:75]
	v_mfma_f32_16x16x32_bf16 v[76:79], v[224:227], v[176:179], v[76:79]
	s_waitcnt lgkmcnt(2)
	v_mfma_f32_16x16x32_bf16 v[16:19], v[212:215], v[248:251], v[16:19]
	ds_read_b128 v[172:175], v128 offset:36864
	v_mfma_f32_16x16x32_bf16 v[20:23], v[212:215], v[244:247], v[20:23]
	ds_read_b128 v[176:179], v128 offset:37888
	v_mfma_f32_16x16x32_bf16 v[24:27], v[216:219], v[248:251], v[24:27]
	v_mfma_f32_16x16x32_bf16 v[28:31], v[216:219], v[244:247], v[28:31]
	v_mfma_f32_16x16x32_bf16 v[0:3], v[220:223], v[248:251], v[0:3]
	v_mfma_f32_16x16x32_bf16 v[4:7], v[220:223], v[244:247], v[4:7]
	v_mfma_f32_16x16x32_bf16 v[8:11], v[224:227], v[248:251], v[8:11]
	v_mfma_f32_16x16x32_bf16 v[12:15], v[224:227], v[244:247], v[12:15]
	s_waitcnt lgkmcnt(0)
	s_waitcnt vmcnt(6)
	s_barrier
	ds_read_b128 v[228:231], v167 offset:49152
	ds_read_b128 v[232:235], v167 offset:50176
	v_mfma_f32_16x16x32_bf16 v[112:115], v[212:215], v[132:135], v[112:115]
	ds_read_b128 v[236:239], v167 offset:51200
	ds_read_b128 v[240:243], v167 offset:52224
	v_mfma_f32_16x16x32_bf16 v[116:119], v[212:215], v[136:139], v[116:119]
	ds_read_b128 v[248:251], v128 offset:49152
	ds_read_b128 v[244:247], v128 offset:50176
	s_add_u32 m0, s76, 0x6000
	v_mfma_f32_16x16x32_bf16 v[120:123], v[216:219], v[132:135], v[120:123]
	global_load_lds_dwordx4 v170, s[72:73]
	s_add_u32 m0, s76, 0x7000
	v_mfma_f32_16x16x32_bf16 v[124:127], v[216:219], v[136:139], v[124:127]
	global_load_lds_dwordx4 v171, s[72:73]
	s_add_u32 m0, s76, 0x8000
	v_mfma_f32_16x16x32_bf16 v[96:99], v[220:223], v[132:135], v[96:99]
	global_load_lds_dwordx4 v180, s[72:73]
	v_mfma_f32_16x16x32_bf16 v[100:103], v[220:223], v[136:139], v[100:103]
	v_mfma_f32_16x16x32_bf16 v[104:107], v[224:227], v[132:135], v[104:107]
	v_mfma_f32_16x16x32_bf16 v[108:111], v[224:227], v[136:139], v[108:111]
	ds_read_b128 v[132:135], v128 offset:53248
	ds_read_b128 v[136:139], v128 offset:54272
	v_mfma_f32_16x16x32_bf16 v[48:51], v[212:215], v[172:175], v[48:51]
	s_add_u32 m0, s76, 0x9000
	v_mfma_f32_16x16x32_bf16 v[52:55], v[212:215], v[176:179], v[52:55]
	global_load_lds_dwordx4 v181, s[72:73]
	s_add_u32 m0, s76, 0xa000
	v_mfma_f32_16x16x32_bf16 v[56:59], v[216:219], v[172:175], v[56:59]
	global_load_lds_dwordx4 v170, s[74:75]
	s_add_u32 m0, s76, 0xb000
	v_mfma_f32_16x16x32_bf16 v[60:63], v[216:219], v[176:179], v[60:63]
	global_load_lds_dwordx4 v171, s[74:75]
	s_add_u32 s72, s72, 0x202000
	s_addc_u32 s73, s73, 0
	v_mfma_f32_16x16x32_bf16 v[32:35], v[220:223], v[172:175], v[32:35]
	s_add_u32 s74, s74, 0x10000
	s_addc_u32 s75, s75, 0
	v_mfma_f32_16x16x32_bf16 v[36:39], v[220:223], v[176:179], v[36:39]
	v_mfma_f32_16x16x32_bf16 v[40:43], v[224:227], v[172:175], v[40:43]
	v_mfma_f32_16x16x32_bf16 v[44:47], v[224:227], v[176:179], v[44:47]
	s_waitcnt lgkmcnt(2)
	v_mfma_f32_16x16x32_bf16 v[80:83], v[228:231], v[248:251], v[80:83]
	ds_read_b128 v[172:175], v128 offset:57344
	v_mfma_f32_16x16x32_bf16 v[84:87], v[228:231], v[244:247], v[84:87]
	ds_read_b128 v[176:179], v128 offset:58368
	v_mfma_f32_16x16x32_bf16 v[88:91], v[232:235], v[248:251], v[88:91]
	v_mfma_f32_16x16x32_bf16 v[92:95], v[232:235], v[244:247], v[92:95]
	v_mfma_f32_16x16x32_bf16 v[64:67], v[236:239], v[248:251], v[64:67]
	v_mfma_f32_16x16x32_bf16 v[68:71], v[236:239], v[244:247], v[68:71]
	v_mfma_f32_16x16x32_bf16 v[72:75], v[240:243], v[248:251], v[72:75]
	v_mfma_f32_16x16x32_bf16 v[76:79], v[240:243], v[244:247], v[76:79]
	s_waitcnt lgkmcnt(2)
	v_mfma_f32_16x16x32_bf16 v[16:19], v[228:231], v[132:135], v[16:19]
	ds_read_b128 v[248:251], v128 offset:61440
	v_mfma_f32_16x16x32_bf16 v[20:23], v[228:231], v[136:139], v[20:23]
	ds_read_b128 v[244:247], v128 offset:62464
	v_mfma_f32_16x16x32_bf16 v[24:27], v[232:235], v[132:135], v[24:27]
	v_mfma_f32_16x16x32_bf16 v[28:31], v[232:235], v[136:139], v[28:31]
	v_mfma_f32_16x16x32_bf16 v[0:3], v[236:239], v[132:135], v[0:3]
	v_mfma_f32_16x16x32_bf16 v[4:7], v[236:239], v[136:139], v[4:7]
	v_mfma_f32_16x16x32_bf16 v[8:11], v[240:243], v[132:135], v[8:11]
	v_mfma_f32_16x16x32_bf16 v[12:15], v[240:243], v[136:139], v[12:15]
	s_waitcnt lgkmcnt(0)
	s_waitcnt vmcnt(6)
	s_barrier
	ds_read_b128 v[212:215], v167
	ds_read_b128 v[216:219], v167 offset:1024
	v_mfma_f32_16x16x32_bf16 v[112:115], v[228:231], v[172:175], v[112:115]
	ds_read_b128 v[220:223], v167 offset:2048
	ds_read_b128 v[224:227], v167 offset:3072
	v_mfma_f32_16x16x32_bf16 v[116:119], v[228:231], v[176:179], v[116:119]
	ds_read_b128 v[132:135], v128
	ds_read_b128 v[136:139], v128 offset:1024
	s_add_u32 m0, s76, 0xc000
	v_mfma_f32_16x16x32_bf16 v[120:123], v[232:235], v[172:175], v[120:123]
	global_load_lds_dwordx4 v170, s[72:73]
	s_add_u32 m0, s76, 0xd000
	v_mfma_f32_16x16x32_bf16 v[124:127], v[232:235], v[176:179], v[124:127]
	global_load_lds_dwordx4 v171, s[72:73]
	s_add_u32 m0, s76, 0xe000
	v_mfma_f32_16x16x32_bf16 v[96:99], v[236:239], v[172:175], v[96:99]
	global_load_lds_dwordx4 v180, s[72:73]
	v_mfma_f32_16x16x32_bf16 v[100:103], v[236:239], v[176:179], v[100:103]
	v_mfma_f32_16x16x32_bf16 v[104:107], v[240:243], v[172:175], v[104:107]
	v_mfma_f32_16x16x32_bf16 v[108:111], v[240:243], v[176:179], v[108:111]
	ds_read_b128 v[172:175], v128 offset:4096
	ds_read_b128 v[176:179], v128 offset:5120
	v_mfma_f32_16x16x32_bf16 v[48:51], v[228:231], v[248:251], v[48:51]
	s_add_u32 m0, s76, 0xf000
	v_mfma_f32_16x16x32_bf16 v[52:55], v[228:231], v[244:247], v[52:55]
	global_load_lds_dwordx4 v181, s[72:73]
	s_add_u32 m0, s76, 0x10000
	v_mfma_f32_16x16x32_bf16 v[56:59], v[232:235], v[248:251], v[56:59]
	global_load_lds_dwordx4 v170, s[74:75]
	s_add_u32 m0, s76, 0x11000
	v_mfma_f32_16x16x32_bf16 v[60:63], v[232:235], v[244:247], v[60:63]
	global_load_lds_dwordx4 v171, s[74:75]
	s_add_u32 s72, s72, 0x202000
	s_addc_u32 s73, s73, 0
	v_mfma_f32_16x16x32_bf16 v[32:35], v[236:239], v[248:251], v[32:35]
	s_add_u32 s74, s74, 0x10000
	s_addc_u32 s75, s75, 0
	v_mfma_f32_16x16x32_bf16 v[36:39], v[236:239], v[244:247], v[36:39]
	v_mfma_f32_16x16x32_bf16 v[40:43], v[240:243], v[248:251], v[40:43]
	v_mfma_f32_16x16x32_bf16 v[44:47], v[240:243], v[244:247], v[44:47]
	s_sub_i32 s77, s77, 1
	s_cmp_lg_u32 s77, 0
	s_cbranch_scc1 .Lgemm_p3_loop
	s_waitcnt lgkmcnt(2)
	v_mfma_f32_16x16x32_bf16 v[80:83], v[212:215], v[132:135], v[80:83]
	ds_read_b128 v[248:251], v128 offset:8192
	v_mfma_f32_16x16x32_bf16 v[84:87], v[212:215], v[136:139], v[84:87]
	ds_read_b128 v[244:247], v128 offset:9216
	v_mfma_f32_16x16x32_bf16 v[88:91], v[216:219], v[132:135], v[88:91]
	v_mfma_f32_16x16x32_bf16 v[92:95], v[216:219], v[136:139], v[92:95]
	v_mfma_f32_16x16x32_bf16 v[64:67], v[220:223], v[132:135], v[64:67]
	v_mfma_f32_16x16x32_bf16 v[68:71], v[220:223], v[136:139], v[68:71]
	v_mfma_f32_16x16x32_bf16 v[72:75], v[224:227], v[132:135], v[72:75]
	v_mfma_f32_16x16x32_bf16 v[76:79], v[224:227], v[136:139], v[76:79]
	s_waitcnt lgkmcnt(2)
	v_mfma_f32_16x16x32_bf16 v[16:19], v[212:215], v[172:175], v[16:19]
	ds_read_b128 v[132:135], v128 offset:12288
	v_mfma_f32_16x16x32_bf16 v[20:23], v[212:215], v[176:179], v[20:23]
	ds_read_b128 v[136:139], v128 offset:13312
	v_mfma_f32_16x16x32_bf16 v[24:27], v[216:219], v[172:175], v[24:27]
	v_mfma_f32_16x16x32_bf16 v[28:31], v[216:219], v[176:179], v[28:31]
	v_mfma_f32_16x16x32_bf16 v[0:3], v[220:223], v[172:175], v[0:3]
	v_mfma_f32_16x16x32_bf16 v[4:7], v[220:223], v[176:179], v[4:7]
	v_mfma_f32_16x16x32_bf16 v[8:11], v[224:227], v[172:175], v[8:11]
	v_mfma_f32_16x16x32_bf16 v[12:15], v[224:227], v[176:179], v[12:15]
	s_waitcnt lgkmcnt(0)
	s_waitcnt vmcnt(6)
	s_barrier
	ds_read_b128 v[228:231], v167 offset:24576
	ds_read_b128 v[232:235], v167 offset:25600
	v_mfma_f32_16x16x32_bf16 v[112:115], v[212:215], v[248:251], v[112:115]
	ds_read_b128 v[236:239], v167 offset:26624
	ds_read_b128 v[240:243], v167 offset:27648
	v_mfma_f32_16x16x32_bf16 v[116:119], v[212:215], v[244:247], v[116:119]
	ds_read_b128 v[172:175], v128 offset:24576
	ds_read_b128 v[176:179], v128 offset:25600
	s_add_u32 m0, s76, 0x0
	v_mfma_f32_16x16x32_bf16 v[120:123], v[216:219], v[248:251], v[120:123]
	global_load_lds_dwordx4 v170, s[72:73]
	s_add_u32 m0, s76, 0x1000
	v_mfma_f32_16x16x32_bf16 v[124:127], v[216:219], v[244:247], v[124:127]
	global_load_lds_dwordx4 v171, s[72:73]
	s_add_u32 m0, s76, 0x2000
	v_mfma_f32_16x16x32_bf16 v[96:99], v[220:223], v[248:251], v[96:99]
	global_load_lds_dwordx4 v180, s[72:73]
	v_mfma_f32_16x16x32_bf16 v[100:103], v[220:223], v[244:247], v[100:103]
	v_mfma_f32_16x16x32_bf16 v[104:107], v[224:227], v[248:251], v[104:107]
	v_mfma_f32_16x16x32_bf16 v[108:111], v[224:227], v[244:247], v[108:111]
	ds_read_b128 v[248:251], v128 offset:28672
	ds_read_b128 v[244:247], v128 offset:29696
	v_mfma_f32_16x16x32_bf16 v[48:51], v[212:215], v[132:135], v[48:51]
	s_add_u32 m0, s76, 0x3000
	v_mfma_f32_16x16x32_bf16 v[52:55], v[212:215], v[136:139], v[52:55]
	global_load_lds_dwordx4 v181, s[72:73]
	s_add_u32 m0, s76, 0x4000
	v_mfma_f32_16x16x32_bf16 v[56:59], v[216:219], v[132:135], v[56:59]
	global_load_lds_dwordx4 v170, s[74:75]
	s_add_u32 m0, s76, 0x5000
	v_mfma_f32_16x16x32_bf16 v[60:63], v[216:219], v[136:139], v[60:63]
	global_load_lds_dwordx4 v171, s[74:75]
	s_add_u32 s72, s72, 0x202000
	s_addc_u32 s73, s73, 0
	v_mfma_f32_16x16x32_bf16 v[32:35], v[220:223], v[132:135], v[32:35]
	s_add_u32 s74, s74, 0x10000
	s_addc_u32 s75, s75, 0
	v_mfma_f32_16x16x32_bf16 v[36:39], v[220:223], v[136:139], v[36:39]
	v_mfma_f32_16x16x32_bf16 v[40:43], v[224:227], v[132:135], v[40:43]
	v_mfma_f32_16x16x32_bf16 v[44:47], v[224:227], v[136:139], v[44:47]
	s_waitcnt lgkmcnt(2)
	v_mfma_f32_16x16x32_bf16 v[80:83], v[228:231], v[172:175], v[80:83]
	ds_read_b128 v[132:135], v128 offset:32768
	v_mfma_f32_16x16x32_bf16 v[84:87], v[228:231], v[176:179], v[84:87]
	ds_read_b128 v[136:139], v128 offset:33792
	v_mfma_f32_16x16x32_bf16 v[88:91], v[232:235], v[172:175], v[88:91]
	v_mfma_f32_16x16x32_bf16 v[92:95], v[232:235], v[176:179], v[92:95]
	v_mfma_f32_16x16x32_bf16 v[64:67], v[236:239], v[172:175], v[64:67]
	v_mfma_f32_16x16x32_bf16 v[68:71], v[236:239], v[176:179], v[68:71]
	v_mfma_f32_16x16x32_bf16 v[72:75], v[240:243], v[172:175], v[72:75]
	v_mfma_f32_16x16x32_bf16 v[76:79], v[240:243], v[176:179], v[76:79]
	s_waitcnt lgkmcnt(2)
	v_mfma_f32_16x16x32_bf16 v[16:19], v[228:231], v[248:251], v[16:19]
	ds_read_b128 v[172:175], v128 offset:36864
	v_mfma_f32_16x16x32_bf16 v[20:23], v[228:231], v[244:247], v[20:23]
	ds_read_b128 v[176:179], v128 offset:37888
	v_mfma_f32_16x16x32_bf16 v[24:27], v[232:235], v[248:251], v[24:27]
	v_mfma_f32_16x16x32_bf16 v[28:31], v[232:235], v[244:247], v[28:31]
	v_mfma_f32_16x16x32_bf16 v[0:3], v[236:239], v[248:251], v[0:3]
	v_mfma_f32_16x16x32_bf16 v[4:7], v[236:239], v[244:247], v[4:7]
	v_mfma_f32_16x16x32_bf16 v[8:11], v[240:243], v[248:251], v[8:11]
	v_mfma_f32_16x16x32_bf16 v[12:15], v[240:243], v[244:247], v[12:15]
	s_waitcnt lgkmcnt(0)
	s_waitcnt vmcnt(6)
	s_barrier
	ds_read_b128 v[212:215], v167 offset:49152
	ds_read_b128 v[216:219], v167 offset:50176
	v_mfma_f32_16x16x32_bf16 v[112:115], v[228:231], v[132:135], v[112:115]
	ds_read_b128 v[220:223], v167 offset:51200
	ds_read_b128 v[224:227], v167 offset:52224
	v_mfma_f32_16x16x32_bf16 v[116:119], v[228:231], v[136:139], v[116:119]
	ds_read_b128 v[248:251], v128 offset:49152
	ds_read_b128 v[244:247], v128 offset:50176
	s_add_u32 m0, s76, 0x6000
	v_mfma_f32_16x16x32_bf16 v[120:123], v[232:235], v[132:135], v[120:123]
	global_load_lds_dwordx4 v170, s[72:73]
	s_add_u32 m0, s76, 0x7000
	v_mfma_f32_16x16x32_bf16 v[124:127], v[232:235], v[136:139], v[124:127]
	global_load_lds_dwordx4 v171, s[72:73]
	s_add_u32 m0, s76, 0x8000
	v_mfma_f32_16x16x32_bf16 v[96:99], v[236:239], v[132:135], v[96:99]
	global_load_lds_dwordx4 v180, s[72:73]
	v_mfma_f32_16x16x32_bf16 v[100:103], v[236:239], v[136:139], v[100:103]
	v_mfma_f32_16x16x32_bf16 v[104:107], v[240:243], v[132:135], v[104:107]
	v_mfma_f32_16x16x32_bf16 v[108:111], v[240:243], v[136:139], v[108:111]
	ds_read_b128 v[132:135], v128 offset:53248
	ds_read_b128 v[136:139], v128 offset:54272
	v_mfma_f32_16x16x32_bf16 v[48:51], v[228:231], v[172:175], v[48:51]
	s_add_u32 m0, s76, 0x9000
	v_mfma_f32_16x16x32_bf16 v[52:55], v[228:231], v[176:179], v[52:55]
	global_load_lds_dwordx4 v181, s[72:73]
	s_add_u32 m0, s76, 0xa000
	v_mfma_f32_16x16x32_bf16 v[56:59], v[232:235], v[172:175], v[56:59]
	global_load_lds_dwordx4 v170, s[74:75]
	s_add_u32 m0, s76, 0xb000
	v_mfma_f32_16x16x32_bf16 v[60:63], v[232:235], v[176:179], v[60:63]
	global_load_lds_dwordx4 v171, s[74:75]
	s_add_u32 s72, s72, 0x202000
	s_addc_u32 s73, s73, 0
	v_mfma_f32_16x16x32_bf16 v[32:35], v[236:239], v[172:175], v[32:35]
	s_add_u32 s74, s74, 0x10000
	s_addc_u32 s75, s75, 0
	v_mfma_f32_16x16x32_bf16 v[36:39], v[236:239], v[176:179], v[36:39]
	v_mfma_f32_16x16x32_bf16 v[40:43], v[240:243], v[172:175], v[40:43]
	v_mfma_f32_16x16x32_bf16 v[44:47], v[240:243], v[176:179], v[44:47]
	s_waitcnt lgkmcnt(2)
	v_mfma_f32_16x16x32_bf16 v[80:83], v[212:215], v[248:251], v[80:83]
	ds_read_b128 v[172:175], v128 offset:57344
	v_mfma_f32_16x16x32_bf16 v[84:87], v[212:215], v[244:247], v[84:87]
	ds_read_b128 v[176:179], v128 offset:58368
	v_mfma_f32_16x16x32_bf16 v[88:91], v[216:219], v[248:251], v[88:91]
	v_mfma_f32_16x16x32_bf16 v[92:95], v[216:219], v[244:247], v[92:95]
	v_mfma_f32_16x16x32_bf16 v[64:67], v[220:223], v[248:251], v[64:67]
	v_mfma_f32_16x16x32_bf16 v[68:71], v[220:223], v[244:247], v[68:71]
	v_mfma_f32_16x16x32_bf16 v[72:75], v[224:227], v[248:251], v[72:75]
	v_mfma_f32_16x16x32_bf16 v[76:79], v[224:227], v[244:247], v[76:79]
	s_waitcnt lgkmcnt(2)
	v_mfma_f32_16x16x32_bf16 v[16:19], v[212:215], v[132:135], v[16:19]
	ds_read_b128 v[248:251], v128 offset:61440
	v_mfma_f32_16x16x32_bf16 v[20:23], v[212:215], v[136:139], v[20:23]
	ds_read_b128 v[244:247], v128 offset:62464
	v_mfma_f32_16x16x32_bf16 v[24:27], v[216:219], v[132:135], v[24:27]
	v_mfma_f32_16x16x32_bf16 v[28:31], v[216:219], v[136:139], v[28:31]
	v_mfma_f32_16x16x32_bf16 v[0:3], v[220:223], v[132:135], v[0:3]
	v_mfma_f32_16x16x32_bf16 v[4:7], v[220:223], v[136:139], v[4:7]
	v_mfma_f32_16x16x32_bf16 v[8:11], v[224:227], v[132:135], v[8:11]
	v_mfma_f32_16x16x32_bf16 v[12:15], v[224:227], v[136:139], v[12:15]
	s_waitcnt lgkmcnt(0)
	s_waitcnt vmcnt(6)
	s_barrier
	ds_read_b128 v[228:231], v167
	ds_read_b128 v[232:235], v167 offset:1024
	v_mfma_f32_16x16x32_bf16 v[112:115], v[212:215], v[172:175], v[112:115]
	ds_read_b128 v[236:239], v167 offset:2048
	ds_read_b128 v[240:243], v167 offset:3072
	v_mfma_f32_16x16x32_bf16 v[116:119], v[212:215], v[176:179], v[116:119]
	ds_read_b128 v[132:135], v128
	ds_read_b128 v[136:139], v128 offset:1024
	s_add_u32 m0, s76, 0xc000
	v_mfma_f32_16x16x32_bf16 v[120:123], v[216:219], v[172:175], v[120:123]
	global_load_lds_dwordx4 v170, s[72:73]
	s_add_u32 m0, s76, 0xd000
	v_mfma_f32_16x16x32_bf16 v[124:127], v[216:219], v[176:179], v[124:127]
	global_load_lds_dwordx4 v171, s[72:73]
	s_add_u32 m0, s76, 0xe000
	v_mfma_f32_16x16x32_bf16 v[96:99], v[220:223], v[172:175], v[96:99]
	global_load_lds_dwordx4 v180, s[72:73]
	v_mfma_f32_16x16x32_bf16 v[100:103], v[220:223], v[176:179], v[100:103]
	v_mfma_f32_16x16x32_bf16 v[104:107], v[224:227], v[172:175], v[104:107]
	v_mfma_f32_16x16x32_bf16 v[108:111], v[224:227], v[176:179], v[108:111]
	ds_read_b128 v[172:175], v128 offset:4096
	ds_read_b128 v[176:179], v128 offset:5120
	v_mfma_f32_16x16x32_bf16 v[48:51], v[212:215], v[248:251], v[48:51]
	s_add_u32 m0, s76, 0xf000
	v_mfma_f32_16x16x32_bf16 v[52:55], v[212:215], v[244:247], v[52:55]
	global_load_lds_dwordx4 v181, s[72:73]
	s_add_u32 m0, s76, 0x10000
	v_mfma_f32_16x16x32_bf16 v[56:59], v[216:219], v[248:251], v[56:59]
	global_load_lds_dwordx4 v170, s[74:75]
	s_add_u32 m0, s76, 0x11000
	v_mfma_f32_16x16x32_bf16 v[60:63], v[216:219], v[244:247], v[60:63]
	global_load_lds_dwordx4 v171, s[74:75]
	s_add_u32 s72, s72, 0x202000
	s_addc_u32 s73, s73, 0
	v_mfma_f32_16x16x32_bf16 v[32:35], v[220:223], v[248:251], v[32:35]
	s_add_u32 s74, s74, 0x10000
	s_addc_u32 s75, s75, 0
	v_mfma_f32_16x16x32_bf16 v[36:39], v[220:223], v[244:247], v[36:39]
	v_mfma_f32_16x16x32_bf16 v[40:43], v[224:227], v[248:251], v[40:43]
	v_mfma_f32_16x16x32_bf16 v[44:47], v[224:227], v[244:247], v[44:47]
	s_waitcnt lgkmcnt(2)
	v_mfma_f32_16x16x32_bf16 v[80:83], v[228:231], v[132:135], v[80:83]
	ds_read_b128 v[248:251], v128 offset:8192
	v_mfma_f32_16x16x32_bf16 v[84:87], v[228:231], v[136:139], v[84:87]
	ds_read_b128 v[244:247], v128 offset:9216
	v_mfma_f32_16x16x32_bf16 v[88:91], v[232:235], v[132:135], v[88:91]
	v_mfma_f32_16x16x32_bf16 v[92:95], v[232:235], v[136:139], v[92:95]
	v_mfma_f32_16x16x32_bf16 v[64:67], v[236:239], v[132:135], v[64:67]
	v_mfma_f32_16x16x32_bf16 v[68:71], v[236:239], v[136:139], v[68:71]
	v_mfma_f32_16x16x32_bf16 v[72:75], v[240:243], v[132:135], v[72:75]
	v_mfma_f32_16x16x32_bf16 v[76:79], v[240:243], v[136:139], v[76:79]
	s_waitcnt lgkmcnt(2)
	v_mfma_f32_16x16x32_bf16 v[16:19], v[228:231], v[172:175], v[16:19]
	ds_read_b128 v[132:135], v128 offset:12288
	v_mfma_f32_16x16x32_bf16 v[20:23], v[228:231], v[176:179], v[20:23]
	ds_read_b128 v[136:139], v128 offset:13312
	v_mfma_f32_16x16x32_bf16 v[24:27], v[232:235], v[172:175], v[24:27]
	v_mfma_f32_16x16x32_bf16 v[28:31], v[232:235], v[176:179], v[28:31]
	v_mfma_f32_16x16x32_bf16 v[0:3], v[236:239], v[172:175], v[0:3]
	v_mfma_f32_16x16x32_bf16 v[4:7], v[236:239], v[176:179], v[4:7]
	v_mfma_f32_16x16x32_bf16 v[8:11], v[240:243], v[172:175], v[8:11]
	v_mfma_f32_16x16x32_bf16 v[12:15], v[240:243], v[176:179], v[12:15]
	s_waitcnt lgkmcnt(0)
	s_waitcnt vmcnt(6)
	s_barrier
	ds_read_b128 v[212:215], v167 offset:24576
	ds_read_b128 v[216:219], v167 offset:25600
	v_mfma_f32_16x16x32_bf16 v[112:115], v[228:231], v[248:251], v[112:115]
	ds_read_b128 v[220:223], v167 offset:26624
	ds_read_b128 v[224:227], v167 offset:27648
	v_mfma_f32_16x16x32_bf16 v[116:119], v[228:231], v[244:247], v[116:119]
	ds_read_b128 v[172:175], v128 offset:24576
	ds_read_b128 v[176:179], v128 offset:25600
	s_add_u32 m0, s76, 0x0
	v_mfma_f32_16x16x32_bf16 v[120:123], v[232:235], v[248:251], v[120:123]
	global_load_lds_dwordx4 v170, s[72:73]
	s_add_u32 m0, s76, 0x1000
	v_mfma_f32_16x16x32_bf16 v[124:127], v[232:235], v[244:247], v[124:127]
	global_load_lds_dwordx4 v171, s[72:73]
	s_add_u32 m0, s76, 0x2000
	v_mfma_f32_16x16x32_bf16 v[96:99], v[236:239], v[248:251], v[96:99]
	global_load_lds_dwordx4 v180, s[72:73]
	v_mfma_f32_16x16x32_bf16 v[100:103], v[236:239], v[244:247], v[100:103]
	v_mfma_f32_16x16x32_bf16 v[104:107], v[240:243], v[248:251], v[104:107]
	v_mfma_f32_16x16x32_bf16 v[108:111], v[240:243], v[244:247], v[108:111]
	ds_read_b128 v[248:251], v128 offset:28672
	ds_read_b128 v[244:247], v128 offset:29696
	v_mfma_f32_16x16x32_bf16 v[48:51], v[228:231], v[132:135], v[48:51]
	s_add_u32 m0, s76, 0x3000
	v_mfma_f32_16x16x32_bf16 v[52:55], v[228:231], v[136:139], v[52:55]
	global_load_lds_dwordx4 v181, s[72:73]
	s_add_u32 m0, s76, 0x4000
	v_mfma_f32_16x16x32_bf16 v[56:59], v[232:235], v[132:135], v[56:59]
	global_load_lds_dwordx4 v170, s[74:75]
	s_add_u32 m0, s76, 0x5000
	v_mfma_f32_16x16x32_bf16 v[60:63], v[232:235], v[136:139], v[60:63]
	global_load_lds_dwordx4 v171, s[74:75]
	s_add_u32 s72, s72, 0x202000
	s_addc_u32 s73, s73, 0
	v_mfma_f32_16x16x32_bf16 v[32:35], v[236:239], v[132:135], v[32:35]
	s_add_u32 s74, s74, 0x10000
	s_addc_u32 s75, s75, 0
	v_mfma_f32_16x16x32_bf16 v[36:39], v[236:239], v[136:139], v[36:39]
	v_mfma_f32_16x16x32_bf16 v[40:43], v[240:243], v[132:135], v[40:43]
	v_mfma_f32_16x16x32_bf16 v[44:47], v[240:243], v[136:139], v[44:47]
	s_waitcnt lgkmcnt(2)
	v_mfma_f32_16x16x32_bf16 v[80:83], v[212:215], v[172:175], v[80:83]
	ds_read_b128 v[132:135], v128 offset:32768
	v_mfma_f32_16x16x32_bf16 v[84:87], v[212:215], v[176:179], v[84:87]
	ds_read_b128 v[136:139], v128 offset:33792
	v_mfma_f32_16x16x32_bf16 v[88:91], v[216:219], v[172:175], v[88:91]
	v_mfma_f32_16x16x32_bf16 v[92:95], v[216:219], v[176:179], v[92:95]
	v_mfma_f32_16x16x32_bf16 v[64:67], v[220:223], v[172:175], v[64:67]
	v_mfma_f32_16x16x32_bf16 v[68:71], v[220:223], v[176:179], v[68:71]
	v_mfma_f32_16x16x32_bf16 v[72:75], v[224:227], v[172:175], v[72:75]
	v_mfma_f32_16x16x32_bf16 v[76:79], v[224:227], v[176:179], v[76:79]
	s_waitcnt lgkmcnt(2)
	v_mfma_f32_16x16x32_bf16 v[16:19], v[212:215], v[248:251], v[16:19]
	ds_read_b128 v[172:175], v128 offset:36864
	v_mfma_f32_16x16x32_bf16 v[20:23], v[212:215], v[244:247], v[20:23]
	ds_read_b128 v[176:179], v128 offset:37888
	v_mfma_f32_16x16x32_bf16 v[24:27], v[216:219], v[248:251], v[24:27]
	v_mfma_f32_16x16x32_bf16 v[28:31], v[216:219], v[244:247], v[28:31]
	v_mfma_f32_16x16x32_bf16 v[0:3], v[220:223], v[248:251], v[0:3]
	v_mfma_f32_16x16x32_bf16 v[4:7], v[220:223], v[244:247], v[4:7]
	v_mfma_f32_16x16x32_bf16 v[8:11], v[224:227], v[248:251], v[8:11]
	v_mfma_f32_16x16x32_bf16 v[12:15], v[224:227], v[244:247], v[12:15]
	s_waitcnt lgkmcnt(0)
	s_waitcnt vmcnt(6)
	s_barrier
	ds_read_b128 v[228:231], v167 offset:49152
	ds_read_b128 v[232:235], v167 offset:50176
	v_mfma_f32_16x16x32_bf16 v[112:115], v[212:215], v[132:135], v[112:115]
	ds_read_b128 v[236:239], v167 offset:51200
	ds_read_b128 v[240:243], v167 offset:52224
	v_mfma_f32_16x16x32_bf16 v[116:119], v[212:215], v[136:139], v[116:119]
	ds_read_b128 v[248:251], v128 offset:49152
	ds_read_b128 v[244:247], v128 offset:50176
	s_add_u32 m0, s76, 0x6000
	v_mfma_f32_16x16x32_bf16 v[120:123], v[216:219], v[132:135], v[120:123]
	global_load_lds_dwordx4 v170, s[72:73]
	s_add_u32 m0, s76, 0x7000
	v_mfma_f32_16x16x32_bf16 v[124:127], v[216:219], v[136:139], v[124:127]
	global_load_lds_dwordx4 v171, s[72:73]
	s_add_u32 m0, s76, 0x8000
	v_mfma_f32_16x16x32_bf16 v[96:99], v[220:223], v[132:135], v[96:99]
	global_load_lds_dwordx4 v180, s[72:73]
	v_mfma_f32_16x16x32_bf16 v[100:103], v[220:223], v[136:139], v[100:103]
	v_mfma_f32_16x16x32_bf16 v[104:107], v[224:227], v[132:135], v[104:107]
	v_mfma_f32_16x16x32_bf16 v[108:111], v[224:227], v[136:139], v[108:111]
	ds_read_b128 v[132:135], v128 offset:53248
	ds_read_b128 v[136:139], v128 offset:54272
	v_mfma_f32_16x16x32_bf16 v[48:51], v[212:215], v[172:175], v[48:51]
	s_add_u32 m0, s76, 0x9000
	v_mfma_f32_16x16x32_bf16 v[52:55], v[212:215], v[176:179], v[52:55]
	global_load_lds_dwordx4 v181, s[72:73]
	s_add_u32 m0, s76, 0xa000
	v_mfma_f32_16x16x32_bf16 v[56:59], v[216:219], v[172:175], v[56:59]
	global_load_lds_dwordx4 v170, s[74:75]
	s_add_u32 m0, s76, 0xb000
	v_mfma_f32_16x16x32_bf16 v[60:63], v[216:219], v[176:179], v[60:63]
	global_load_lds_dwordx4 v171, s[74:75]
	s_add_u32 s72, s72, 0x202000
	s_addc_u32 s73, s73, 0
	v_mfma_f32_16x16x32_bf16 v[32:35], v[220:223], v[172:175], v[32:35]
	s_add_u32 s74, s74, 0x10000
	s_addc_u32 s75, s75, 0
	v_mfma_f32_16x16x32_bf16 v[36:39], v[220:223], v[176:179], v[36:39]
	v_mfma_f32_16x16x32_bf16 v[40:43], v[224:227], v[172:175], v[40:43]
	v_mfma_f32_16x16x32_bf16 v[44:47], v[224:227], v[176:179], v[44:47]
	s_waitcnt lgkmcnt(2)
	v_mfma_f32_16x16x32_bf16 v[80:83], v[228:231], v[248:251], v[80:83]
	ds_read_b128 v[172:175], v128 offset:57344
	v_mfma_f32_16x16x32_bf16 v[84:87], v[228:231], v[244:247], v[84:87]
	ds_read_b128 v[176:179], v128 offset:58368
	v_mfma_f32_16x16x32_bf16 v[88:91], v[232:235], v[248:251], v[88:91]
	v_mfma_f32_16x16x32_bf16 v[92:95], v[232:235], v[244:247], v[92:95]
	v_mfma_f32_16x16x32_bf16 v[64:67], v[236:239], v[248:251], v[64:67]
	v_mfma_f32_16x16x32_bf16 v[68:71], v[236:239], v[244:247], v[68:71]
	v_mfma_f32_16x16x32_bf16 v[72:75], v[240:243], v[248:251], v[72:75]
	v_mfma_f32_16x16x32_bf16 v[76:79], v[240:243], v[244:247], v[76:79]
	s_waitcnt lgkmcnt(2)
	v_mfma_f32_16x16x32_bf16 v[16:19], v[228:231], v[132:135], v[16:19]
	ds_read_b128 v[248:251], v128 offset:61440
	v_mfma_f32_16x16x32_bf16 v[20:23], v[228:231], v[136:139], v[20:23]
	ds_read_b128 v[244:247], v128 offset:62464
	v_mfma_f32_16x16x32_bf16 v[24:27], v[232:235], v[132:135], v[24:27]
	v_mfma_f32_16x16x32_bf16 v[28:31], v[232:235], v[136:139], v[28:31]
	v_mfma_f32_16x16x32_bf16 v[0:3], v[236:239], v[132:135], v[0:3]
	v_mfma_f32_16x16x32_bf16 v[4:7], v[236:239], v[136:139], v[4:7]
	v_mfma_f32_16x16x32_bf16 v[8:11], v[240:243], v[132:135], v[8:11]
	v_mfma_f32_16x16x32_bf16 v[12:15], v[240:243], v[136:139], v[12:15]
	s_waitcnt lgkmcnt(0)
	s_waitcnt vmcnt(6)
	s_barrier
	ds_read_b128 v[212:215], v167
	ds_read_b128 v[216:219], v167 offset:1024
	v_mfma_f32_16x16x32_bf16 v[112:115], v[228:231], v[172:175], v[112:115]
	ds_read_b128 v[220:223], v167 offset:2048
	ds_read_b128 v[224:227], v167 offset:3072
	v_mfma_f32_16x16x32_bf16 v[116:119], v[228:231], v[176:179], v[116:119]
	ds_read_b128 v[132:135], v128
	ds_read_b128 v[136:139], v128 offset:1024
	v_mfma_f32_16x16x32_bf16 v[120:123], v[232:235], v[172:175], v[120:123]
	v_mfma_f32_16x16x32_bf16 v[124:127], v[232:235], v[176:179], v[124:127]
	v_mfma_f32_16x16x32_bf16 v[96:99], v[236:239], v[172:175], v[96:99]
	v_mfma_f32_16x16x32_bf16 v[100:103], v[236:239], v[176:179], v[100:103]
	v_mfma_f32_16x16x32_bf16 v[104:107], v[240:243], v[172:175], v[104:107]
	v_mfma_f32_16x16x32_bf16 v[108:111], v[240:243], v[176:179], v[108:111]
	ds_read_b128 v[172:175], v128 offset:4096
	ds_read_b128 v[176:179], v128 offset:5120
	v_mfma_f32_16x16x32_bf16 v[48:51], v[228:231], v[248:251], v[48:51]
	v_mfma_f32_16x16x32_bf16 v[52:55], v[228:231], v[244:247], v[52:55]
	v_mfma_f32_16x16x32_bf16 v[56:59], v[232:235], v[248:251], v[56:59]
	v_mfma_f32_16x16x32_bf16 v[60:63], v[232:235], v[244:247], v[60:63]
	v_mfma_f32_16x16x32_bf16 v[32:35], v[236:239], v[248:251], v[32:35]
	v_mfma_f32_16x16x32_bf16 v[36:39], v[236:239], v[244:247], v[36:39]
	v_mfma_f32_16x16x32_bf16 v[40:43], v[240:243], v[248:251], v[40:43]
	v_mfma_f32_16x16x32_bf16 v[44:47], v[240:243], v[244:247], v[44:47]
	s_waitcnt lgkmcnt(2)
	v_mfma_f32_16x16x32_bf16 v[80:83], v[212:215], v[132:135], v[80:83]
	ds_read_b128 v[248:251], v128 offset:8192
	v_mfma_f32_16x16x32_bf16 v[84:87], v[212:215], v[136:139], v[84:87]
	ds_read_b128 v[244:247], v128 offset:9216
	v_mfma_f32_16x16x32_bf16 v[88:91], v[216:219], v[132:135], v[88:91]
	v_mfma_f32_16x16x32_bf16 v[92:95], v[216:219], v[136:139], v[92:95]
	v_mfma_f32_16x16x32_bf16 v[64:67], v[220:223], v[132:135], v[64:67]
	v_mfma_f32_16x16x32_bf16 v[68:71], v[220:223], v[136:139], v[68:71]
	v_mfma_f32_16x16x32_bf16 v[72:75], v[224:227], v[132:135], v[72:75]
	v_mfma_f32_16x16x32_bf16 v[76:79], v[224:227], v[136:139], v[76:79]
	s_waitcnt lgkmcnt(2)
	v_mfma_f32_16x16x32_bf16 v[16:19], v[212:215], v[172:175], v[16:19]
	ds_read_b128 v[132:135], v128 offset:12288
	v_mfma_f32_16x16x32_bf16 v[20:23], v[212:215], v[176:179], v[20:23]
	ds_read_b128 v[136:139], v128 offset:13312
	v_mfma_f32_16x16x32_bf16 v[24:27], v[216:219], v[172:175], v[24:27]
	v_mfma_f32_16x16x32_bf16 v[28:31], v[216:219], v[176:179], v[28:31]
	v_mfma_f32_16x16x32_bf16 v[0:3], v[220:223], v[172:175], v[0:3]
	v_mfma_f32_16x16x32_bf16 v[4:7], v[220:223], v[176:179], v[4:7]
	v_mfma_f32_16x16x32_bf16 v[8:11], v[224:227], v[172:175], v[8:11]
	v_mfma_f32_16x16x32_bf16 v[12:15], v[224:227], v[176:179], v[12:15]
	s_waitcnt lgkmcnt(0)
	s_waitcnt vmcnt(0)
	s_barrier
	ds_read_b128 v[228:231], v167 offset:24576
	ds_read_b128 v[232:235], v167 offset:25600
	v_mfma_f32_16x16x32_bf16 v[112:115], v[212:215], v[248:251], v[112:115]
	ds_read_b128 v[236:239], v167 offset:26624
	ds_read_b128 v[240:243], v167 offset:27648
	v_mfma_f32_16x16x32_bf16 v[116:119], v[212:215], v[244:247], v[116:119]
	ds_read_b128 v[172:175], v128 offset:24576
	ds_read_b128 v[176:179], v128 offset:25600
	v_mfma_f32_16x16x32_bf16 v[120:123], v[216:219], v[248:251], v[120:123]
	v_mfma_f32_16x16x32_bf16 v[124:127], v[216:219], v[244:247], v[124:127]
	v_mfma_f32_16x16x32_bf16 v[96:99], v[220:223], v[248:251], v[96:99]
	v_mfma_f32_16x16x32_bf16 v[100:103], v[220:223], v[244:247], v[100:103]
	v_mfma_f32_16x16x32_bf16 v[104:107], v[224:227], v[248:251], v[104:107]
	v_mfma_f32_16x16x32_bf16 v[108:111], v[224:227], v[244:247], v[108:111]
	ds_read_b128 v[248:251], v128 offset:28672
	ds_read_b128 v[244:247], v128 offset:29696
	v_mfma_f32_16x16x32_bf16 v[48:51], v[212:215], v[132:135], v[48:51]
	v_mfma_f32_16x16x32_bf16 v[52:55], v[212:215], v[136:139], v[52:55]
	v_mfma_f32_16x16x32_bf16 v[56:59], v[216:219], v[132:135], v[56:59]
	v_mfma_f32_16x16x32_bf16 v[60:63], v[216:219], v[136:139], v[60:63]
	v_mfma_f32_16x16x32_bf16 v[32:35], v[220:223], v[132:135], v[32:35]
	v_mfma_f32_16x16x32_bf16 v[36:39], v[220:223], v[136:139], v[36:39]
	v_mfma_f32_16x16x32_bf16 v[40:43], v[224:227], v[132:135], v[40:43]
	v_mfma_f32_16x16x32_bf16 v[44:47], v[224:227], v[136:139], v[44:47]
	s_waitcnt lgkmcnt(2)
	v_mfma_f32_16x16x32_bf16 v[80:83], v[228:231], v[172:175], v[80:83]
	ds_read_b128 v[132:135], v128 offset:32768
	v_mfma_f32_16x16x32_bf16 v[84:87], v[228:231], v[176:179], v[84:87]
	ds_read_b128 v[136:139], v128 offset:33792
	v_mfma_f32_16x16x32_bf16 v[88:91], v[232:235], v[172:175], v[88:91]
	v_mfma_f32_16x16x32_bf16 v[92:95], v[232:235], v[176:179], v[92:95]
	v_mfma_f32_16x16x32_bf16 v[64:67], v[236:239], v[172:175], v[64:67]
	v_mfma_f32_16x16x32_bf16 v[68:71], v[236:239], v[176:179], v[68:71]
	v_mfma_f32_16x16x32_bf16 v[72:75], v[240:243], v[172:175], v[72:75]
	v_mfma_f32_16x16x32_bf16 v[76:79], v[240:243], v[176:179], v[76:79]
	s_waitcnt lgkmcnt(2)
	v_mfma_f32_16x16x32_bf16 v[16:19], v[228:231], v[248:251], v[16:19]
	ds_read_b128 v[172:175], v128 offset:36864
	v_mfma_f32_16x16x32_bf16 v[20:23], v[228:231], v[244:247], v[20:23]
	ds_read_b128 v[176:179], v128 offset:37888
	v_mfma_f32_16x16x32_bf16 v[24:27], v[232:235], v[248:251], v[24:27]
	v_mfma_f32_16x16x32_bf16 v[28:31], v[232:235], v[244:247], v[28:31]
	v_mfma_f32_16x16x32_bf16 v[0:3], v[236:239], v[248:251], v[0:3]
	v_mfma_f32_16x16x32_bf16 v[4:7], v[236:239], v[244:247], v[4:7]
	v_mfma_f32_16x16x32_bf16 v[8:11], v[240:243], v[248:251], v[8:11]
	v_mfma_f32_16x16x32_bf16 v[12:15], v[240:243], v[244:247], v[12:15]
	s_waitcnt lgkmcnt(0)
	v_mfma_f32_16x16x32_bf16 v[112:115], v[228:231], v[132:135], v[112:115]
	v_mfma_f32_16x16x32_bf16 v[116:119], v[228:231], v[136:139], v[116:119]
	v_mfma_f32_16x16x32_bf16 v[120:123], v[232:235], v[132:135], v[120:123]
	v_mfma_f32_16x16x32_bf16 v[124:127], v[232:235], v[136:139], v[124:127]
	v_mfma_f32_16x16x32_bf16 v[96:99], v[236:239], v[132:135], v[96:99]
	v_mfma_f32_16x16x32_bf16 v[100:103], v[236:239], v[136:139], v[100:103]
	v_mfma_f32_16x16x32_bf16 v[104:107], v[240:243], v[132:135], v[104:107]
	v_mfma_f32_16x16x32_bf16 v[108:111], v[240:243], v[136:139], v[108:111]
	v_mfma_f32_16x16x32_bf16 v[48:51], v[228:231], v[172:175], v[48:51]
	v_mfma_f32_16x16x32_bf16 v[52:55], v[228:231], v[176:179], v[52:55]
	v_mfma_f32_16x16x32_bf16 v[56:59], v[232:235], v[172:175], v[56:59]
	v_mfma_f32_16x16x32_bf16 v[60:63], v[232:235], v[176:179], v[60:63]
	v_mfma_f32_16x16x32_bf16 v[32:35], v[236:239], v[172:175], v[32:35]
	v_mfma_f32_16x16x32_bf16 v[36:39], v[236:239], v[176:179], v[36:39]
	v_mfma_f32_16x16x32_bf16 v[40:43], v[240:243], v[172:175], v[40:43]
	v_mfma_f32_16x16x32_bf16 v[44:47], v[240:243], v[176:179], v[44:47]
	s_setprio 0
	s_nop 15
	s_nop 15
	v_permlane16_swap_b32_e32 v80, v84
	v_permlane16_swap_b32_e32 v81, v85
	v_permlane16_swap_b32_e32 v82, v86
	v_permlane16_swap_b32_e32 v83, v87
	v_permlane16_swap_b32_e32 v88, v92
	v_permlane16_swap_b32_e32 v89, v93
	v_permlane16_swap_b32_e32 v90, v94
	v_permlane16_swap_b32_e32 v91, v95
	v_permlane16_swap_b32_e32 v16, v20
	v_permlane16_swap_b32_e32 v17, v21
	v_permlane16_swap_b32_e32 v18, v22
	v_permlane16_swap_b32_e32 v19, v23
	v_permlane16_swap_b32_e32 v24, v28
	v_permlane16_swap_b32_e32 v25, v29
	v_permlane16_swap_b32_e32 v26, v30
	v_permlane16_swap_b32_e32 v27, v31
	v_permlane16_swap_b32_e32 v112, v116
	v_permlane16_swap_b32_e32 v113, v117
	v_permlane16_swap_b32_e32 v114, v118
	v_permlane16_swap_b32_e32 v115, v119
	v_permlane16_swap_b32_e32 v120, v124
	v_permlane16_swap_b32_e32 v121, v125
	v_permlane16_swap_b32_e32 v122, v126
	v_permlane16_swap_b32_e32 v123, v127
	v_permlane16_swap_b32_e32 v48, v52
	v_permlane16_swap_b32_e32 v49, v53
	v_permlane16_swap_b32_e32 v50, v54
	v_permlane16_swap_b32_e32 v51, v55
	v_permlane16_swap_b32_e32 v56, v60
	v_permlane16_swap_b32_e32 v57, v61
	v_permlane16_swap_b32_e32 v58, v62
	v_permlane16_swap_b32_e32 v59, v63
	v_permlane16_swap_b32_e32 v64, v68
	v_permlane16_swap_b32_e32 v65, v69
	v_permlane16_swap_b32_e32 v66, v70
	v_permlane16_swap_b32_e32 v67, v71
	v_permlane16_swap_b32_e32 v72, v76
	v_permlane16_swap_b32_e32 v73, v77
	v_permlane16_swap_b32_e32 v74, v78
	v_permlane16_swap_b32_e32 v75, v79
	v_permlane16_swap_b32_e32 v0, v4
	v_permlane16_swap_b32_e32 v1, v5
	v_permlane16_swap_b32_e32 v2, v6
	v_permlane16_swap_b32_e32 v3, v7
	v_permlane16_swap_b32_e32 v8, v12
	v_permlane16_swap_b32_e32 v9, v13
	v_permlane16_swap_b32_e32 v10, v14
	v_permlane16_swap_b32_e32 v11, v15
	v_permlane16_swap_b32_e32 v96, v100
	v_permlane16_swap_b32_e32 v97, v101
	v_permlane16_swap_b32_e32 v98, v102
	v_permlane16_swap_b32_e32 v99, v103
	v_permlane16_swap_b32_e32 v104, v108
	v_permlane16_swap_b32_e32 v105, v109
	v_permlane16_swap_b32_e32 v106, v110
	v_permlane16_swap_b32_e32 v107, v111
	v_permlane16_swap_b32_e32 v32, v36
	v_permlane16_swap_b32_e32 v33, v37
	v_permlane16_swap_b32_e32 v34, v38
	v_permlane16_swap_b32_e32 v35, v39
	v_permlane16_swap_b32_e32 v40, v44
	v_permlane16_swap_b32_e32 v41, v45
	v_permlane16_swap_b32_e32 v42, v46
	v_permlane16_swap_b32_e32 v43, v47
	s_nop 1
	v_readlane_b32 s72, v254, 13
	v_readlane_b32 s73, v254, 14
	s_nop 1
	v_mov_b64_e32 v[130:131], s[72:73]

.LBB0_630:
	s_or_saveexec_b64 s[0:1], s[0:1]
	v_mov_b32_e32 v63, 0
	v_mov_b32_e32 v62, 0
	v_mov_b32_e32 v61, 0
	v_mov_b32_e32 v60, 0
	v_mov_b32_e32 v59, 0
	v_mov_b32_e32 v58, 0
	v_mov_b32_e32 v57, 0
	v_mov_b32_e32 v56, 0
	v_mov_b32_e32 v55, 0
	v_mov_b32_e32 v54, 0
	v_mov_b32_e32 v53, 0
	v_mov_b32_e32 v52, 0
	v_mov_b32_e32 v51, 0
	v_mov_b32_e32 v50, 0
	v_mov_b32_e32 v49, 0
	v_mov_b32_e32 v48, v63
	v_mov_b32_e32 v31, 0
	v_mov_b32_e32 v30, 0
	v_mov_b32_e32 v29, 0
	v_mov_b32_e32 v28, 0
	v_mov_b32_e32 v27, 0
	v_mov_b32_e32 v26, 0
	v_mov_b32_e32 v25, 0
	v_mov_b32_e32 v24, 0
	v_mov_b32_e32 v23, 0
	v_mov_b32_e32 v22, 0
	v_mov_b32_e32 v21, 0
	v_mov_b32_e32 v20, 0
	v_mov_b32_e32 v19, 0
	v_mov_b32_e32 v18, 0
	v_mov_b32_e32 v17, 0
	v_mov_b32_e32 v16, v63
	v_mov_b32_e32 v47, 0
	v_mov_b32_e32 v46, v63
	v_mov_b32_e32 v45, 0
	v_mov_b32_e32 v44, v63
	v_mov_b32_e32 v43, 0
	v_mov_b32_e32 v42, v63
	v_mov_b32_e32 v41, 0
	v_mov_b32_e32 v40, v63
	v_mov_b32_e32 v39, 0
	v_mov_b32_e32 v38, v63
	v_mov_b32_e32 v37, 0
	v_mov_b32_e32 v36, 0
	v_mov_b32_e32 v35, 0
	v_mov_b32_e32 v34, 0
	v_mov_b32_e32 v33, 0
	v_mov_b32_e32 v32, v63
	v_mov_b32_e32 v15, 0
	v_mov_b32_e32 v14, v63
	v_mov_b32_e32 v13, 0
	v_mov_b32_e32 v12, v63
	v_mov_b32_e32 v11, 0
	v_mov_b32_e32 v10, v63
	v_mov_b32_e32 v9, 0
	v_mov_b32_e32 v8, v63
	v_mov_b32_e32 v7, 0
	v_mov_b32_e32 v6, v63
	v_mov_b32_e32 v5, 0
	v_mov_b32_e32 v4, 0
	v_mov_b32_e32 v3, 0
	v_mov_b32_e32 v2, 0
	v_mov_b32_e32 v1, 0
	v_mov_b32_e32 v0, v63
	s_xor_b64 exec, exec, s[0:1]
	s_cbranch_execz .LBB0_634
	v_readfirstlane_b32 s10, v128
	v_readfirstlane_b32 s11, v130
	v_readfirstlane_b32 s8, v226
	v_mbcnt_lo_u32_b32 v192, -1, 0
	v_mbcnt_hi_u32_b32 v192, -1, v192
	s_nop 3
	s_lshl_b32 s10, s10, 14
	s_lshl_b32 s11, s11, 13
	s_add_u32 s4, s90, s10
	s_addc_u32 s5, s91, 0
	s_add_u32 s6, s90, s11
	s_addc_u32 s7, s91, 0
	s_add_u32 s6, s6, 0x1b3c8000
	s_addc_u32 s7, s7, 0
	v_lshrrev_b32_e32 v193, 2, v192
	v_lshrrev_b32_e32 v194, 4, v192
	v_xor_b32_e32 v194, v194, v192
	v_and_b32_e32 v194, 3, v194
	v_lshlrev_b32_e32 v194, 4, v194
	v_lshl_or_b32 v193, v193, 6, v194
	v_or_b32_e32 v189, v193, v226
	v_add_u32_e32 v252, 0x1000, v189
	v_add_u32_e32 v190, 0x2000, v189
	v_add_u32_e32 v191, 0x3000, v189
	v_and_b32_e32 v193, 15, v192
	v_lshrrev_b32_e32 v194, 4, v192
	v_bfe_u32 v195, v192, 2, 2
	v_xor_b32_e32 v195, v195, v194
	v_lshlrev_b32_e32 v195, 4, v195
	v_lshl_or_b32 v129, v193, 6, v195
	v_lshrrev_b32_e32 v195, 10, v226
	v_lshrrev_b32_e32 v195, 1, v195
	v_lshl_or_b32 v129, v195, 11, v129
	v_and_b32_e32 v195, 3, v192
	v_bfe_u32 v193, v192, 2, 1
	v_lshl_or_b32 v195, v193, 3, v195
	v_bfe_u32 v193, v192, 3, 1
	v_lshl_or_b32 v195, v193, 2, v195
	v_lshrrev_b32_e32 v193, 2, v195
	v_xor_b32_e32 v193, v193, v194
	v_lshlrev_b32_e32 v193, 4, v193
	v_lshl_or_b32 v156, v195, 6, v193
	v_lshrrev_b32_e32 v195, 10, v226
	v_and_b32_e32 v195, 1, v195
	v_lshl_or_b32 v156, v195, 12, v156
	v_or_b32_e32 v156, 0x4000, v156
	s_cmp_eq_u32 s99, 0x7fffffff
	s_cbranch_scc0 .Lgprio_p4
	s_setprio 1
.Lgprio_p4:
	s_add_u32 m0, s8, 0x2000
	s_nop 0
	global_load_lds_dwordx4 v190, s[4:5]
	s_add_u32 m0, s8, 0x3000
	s_nop 0
	global_load_lds_dwordx4 v191, s[4:5]
	s_add_u32 m0, s8, 0x4000
	s_nop 0
	global_load_lds_dwordx4 v189, s[6:7]
	s_add_u32 m0, s8, 0x5000
	s_nop 0
	global_load_lds_dwordx4 v252, s[6:7]
	s_add_u32 s4, s4, 0x202000
	s_addc_u32 s5, s5, 0
	s_add_u32 s6, s6, 0x40000
	s_addc_u32 s7, s7, 0
	s_add_u32 m0, s8, 0x6000
	s_nop 0
	global_load_lds_dwordx4 v189, s[4:5]
	s_add_u32 m0, s8, 0x7000
	s_nop 0
	global_load_lds_dwordx4 v252, s[4:5]
	s_add_u32 m0, s8, 0x8000
	s_nop 0
	global_load_lds_dwordx4 v190, s[4:5]
	s_add_u32 m0, s8, 0x9000
	s_nop 0
	global_load_lds_dwordx4 v191, s[4:5]
	s_add_u32 m0, s8, 0xa000
	s_nop 0
	global_load_lds_dwordx4 v189, s[6:7]
	s_add_u32 m0, s8, 0xb000
	s_nop 0
	global_load_lds_dwordx4 v252, s[6:7]
	s_add_u32 s4, s4, 0x202000
	s_addc_u32 s5, s5, 0
	s_add_u32 s6, s6, 0x40000
	s_addc_u32 s7, s7, 0
	s_add_u32 m0, s8, 0xc000
	s_nop 0
	global_load_lds_dwordx4 v189, s[4:5]
	s_add_u32 m0, s8, 0xd000
	s_nop 0
	global_load_lds_dwordx4 v252, s[4:5]
	s_add_u32 m0, s8, 0xe000
	s_nop 0
	global_load_lds_dwordx4 v190, s[4:5]
	s_add_u32 m0, s8, 0xf000
	s_nop 0
	global_load_lds_dwordx4 v191, s[4:5]
	s_add_u32 m0, s8, 0x10000
	s_nop 0
	global_load_lds_dwordx4 v189, s[6:7]
	s_add_u32 m0, s8, 0x11000
	s_nop 0
	global_load_lds_dwordx4 v252, s[6:7]
	s_add_u32 s4, s4, 0x202000
	s_addc_u32 s5, s5, 0
	s_add_u32 s6, s6, 0x40000
	s_addc_u32 s7, s7, 0
	s_waitcnt vmcnt(12)
	s_barrier
	ds_read_b128 v[132:135], v156
	ds_read_b128 v[136:139], v156 offset:1024
	ds_read_b128 v[140:143], v156 offset:2048
	ds_read_b128 v[180:183], v156 offset:3072
	ds_read_b128 v[248:251], v129
	ds_read_b128 v[200:203], v129 offset:1024
	ds_read_b128 v[204:207], v129 offset:4096
	ds_read_b128 v[208:211], v129 offset:5120
	s_waitcnt lgkmcnt(0)
	v_mfma_f32_16x16x32_bf16 v[112:115], v[132:135], v[248:251], 0
	ds_read_b128 v[212:215], v129 offset:8192
	v_mfma_f32_16x16x32_bf16 v[116:119], v[132:135], v[200:203], 0
	ds_read_b128 v[216:219], v129 offset:9216
	v_mfma_f32_16x16x32_bf16 v[120:123], v[136:139], v[248:251], 0
	v_mfma_f32_16x16x32_bf16 v[124:127], v[136:139], v[200:203], 0
	v_mfma_f32_16x16x32_bf16 v[96:99], v[140:143], v[248:251], 0
	v_mfma_f32_16x16x32_bf16 v[100:103], v[140:143], v[200:203], 0
	v_mfma_f32_16x16x32_bf16 v[104:107], v[180:183], v[248:251], 0
	v_mfma_f32_16x16x32_bf16 v[108:111], v[180:183], v[200:203], 0
	s_waitcnt lgkmcnt(2)
	v_mfma_f32_16x16x32_bf16 v[80:83], v[132:135], v[204:207], 0
	ds_read_b128 v[248:251], v129 offset:12288
	v_mfma_f32_16x16x32_bf16 v[84:87], v[132:135], v[208:211], 0
	ds_read_b128 v[200:203], v129 offset:13312
	v_mfma_f32_16x16x32_bf16 v[88:91], v[136:139], v[204:207], 0
	v_mfma_f32_16x16x32_bf16 v[92:95], v[136:139], v[208:211], 0
	v_mfma_f32_16x16x32_bf16 v[64:67], v[140:143], v[204:207], 0
	v_mfma_f32_16x16x32_bf16 v[68:71], v[140:143], v[208:211], 0
	v_mfma_f32_16x16x32_bf16 v[72:75], v[180:183], v[204:207], 0
	v_mfma_f32_16x16x32_bf16 v[76:79], v[180:183], v[208:211], 0
	s_waitcnt lgkmcnt(0)
	s_waitcnt vmcnt(6)
	s_barrier
	ds_read_b128 v[184:187], v156 offset:24576
	ds_read_b128 v[236:239], v156 offset:25600
	v_mfma_f32_16x16x32_bf16 v[48:51], v[132:135], v[212:215], 0
	ds_read_b128 v[240:243], v156 offset:26624
	ds_read_b128 v[244:247], v156 offset:27648
	v_mfma_f32_16x16x32_bf16 v[52:55], v[132:135], v[216:219], 0
	ds_read_b128 v[204:207], v129 offset:24576
	ds_read_b128 v[208:211], v129 offset:25600
	s_add_u32 m0, s8, 0x0
	v_mfma_f32_16x16x32_bf16 v[56:59], v[136:139], v[212:215], 0
	global_load_lds_dwordx4 v189, s[4:5]
	s_add_u32 m0, s8, 0x1000
	v_mfma_f32_16x16x32_bf16 v[60:63], v[136:139], v[216:219], 0
	global_load_lds_dwordx4 v252, s[4:5]
	s_add_u32 m0, s8, 0x2000
	v_mfma_f32_16x16x32_bf16 v[32:35], v[140:143], v[212:215], 0
	global_load_lds_dwordx4 v190, s[4:5]
	v_mfma_f32_16x16x32_bf16 v[36:39], v[140:143], v[216:219], 0
	v_mfma_f32_16x16x32_bf16 v[40:43], v[180:183], v[212:215], 0
	v_mfma_f32_16x16x32_bf16 v[44:47], v[180:183], v[216:219], 0
	ds_read_b128 v[212:215], v129 offset:28672
	ds_read_b128 v[216:219], v129 offset:29696
	v_mfma_f32_16x16x32_bf16 v[16:19], v[132:135], v[248:251], 0
	s_add_u32 m0, s8, 0x3000
	v_mfma_f32_16x16x32_bf16 v[20:23], v[132:135], v[200:203], 0
	global_load_lds_dwordx4 v191, s[4:5]
	s_add_u32 m0, s8, 0x4000
	v_mfma_f32_16x16x32_bf16 v[24:27], v[136:139], v[248:251], 0
	global_load_lds_dwordx4 v189, s[6:7]
	s_add_u32 m0, s8, 0x5000
	v_mfma_f32_16x16x32_bf16 v[28:31], v[136:139], v[200:203], 0
	global_load_lds_dwordx4 v252, s[6:7]
	s_add_u32 s4, s4, 0x202000
	s_addc_u32 s5, s5, 0
	v_mfma_f32_16x16x32_bf16 v[0:3], v[140:143], v[248:251], 0
	s_add_u32 s6, s6, 0x40000
	s_addc_u32 s7, s7, 0
	v_mfma_f32_16x16x32_bf16 v[4:7], v[140:143], v[200:203], 0
	v_mfma_f32_16x16x32_bf16 v[8:11], v[180:183], v[248:251], 0
	v_mfma_f32_16x16x32_bf16 v[12:15], v[180:183], v[200:203], 0
	s_waitcnt lgkmcnt(2)
	v_mfma_f32_16x16x32_bf16 v[112:115], v[184:187], v[204:207], v[112:115]
	ds_read_b128 v[248:251], v129 offset:32768
	v_mfma_f32_16x16x32_bf16 v[116:119], v[184:187], v[208:211], v[116:119]
	ds_read_b128 v[200:203], v129 offset:33792
	v_mfma_f32_16x16x32_bf16 v[120:123], v[236:239], v[204:207], v[120:123]
	v_mfma_f32_16x16x32_bf16 v[124:127], v[236:239], v[208:211], v[124:127]
	v_mfma_f32_16x16x32_bf16 v[96:99], v[240:243], v[204:207], v[96:99]
	v_mfma_f32_16x16x32_bf16 v[100:103], v[240:243], v[208:211], v[100:103]
	v_mfma_f32_16x16x32_bf16 v[104:107], v[244:247], v[204:207], v[104:107]
	v_mfma_f32_16x16x32_bf16 v[108:111], v[244:247], v[208:211], v[108:111]
	s_waitcnt lgkmcnt(2)
	v_mfma_f32_16x16x32_bf16 v[80:83], v[184:187], v[212:215], v[80:83]
	ds_read_b128 v[204:207], v129 offset:36864
	v_mfma_f32_16x16x32_bf16 v[84:87], v[184:187], v[216:219], v[84:87]
	ds_read_b128 v[208:211], v129 offset:37888
	v_mfma_f32_16x16x32_bf16 v[88:91], v[236:239], v[212:215], v[88:91]
	v_mfma_f32_16x16x32_bf16 v[92:95], v[236:239], v[216:219], v[92:95]
	v_mfma_f32_16x16x32_bf16 v[64:67], v[240:243], v[212:215], v[64:67]
	v_mfma_f32_16x16x32_bf16 v[68:71], v[240:243], v[216:219], v[68:71]
	v_mfma_f32_16x16x32_bf16 v[72:75], v[244:247], v[212:215], v[72:75]
	v_mfma_f32_16x16x32_bf16 v[76:79], v[244:247], v[216:219], v[76:79]
	s_waitcnt lgkmcnt(0)
	s_waitcnt vmcnt(6)
	s_barrier
	ds_read_b128 v[132:135], v156 offset:49152
	ds_read_b128 v[136:139], v156 offset:50176
	v_mfma_f32_16x16x32_bf16 v[48:51], v[184:187], v[248:251], v[48:51]
	ds_read_b128 v[140:143], v156 offset:51200
	ds_read_b128 v[180:183], v156 offset:52224
	v_mfma_f32_16x16x32_bf16 v[52:55], v[184:187], v[200:203], v[52:55]
	ds_read_b128 v[212:215], v129 offset:49152
	ds_read_b128 v[216:219], v129 offset:50176
	s_add_u32 m0, s8, 0x6000
	v_mfma_f32_16x16x32_bf16 v[56:59], v[236:239], v[248:251], v[56:59]
	global_load_lds_dwordx4 v189, s[4:5]
	s_add_u32 m0, s8, 0x7000
	v_mfma_f32_16x16x32_bf16 v[60:63], v[236:239], v[200:203], v[60:63]
	global_load_lds_dwordx4 v252, s[4:5]
	s_add_u32 m0, s8, 0x8000
	v_mfma_f32_16x16x32_bf16 v[32:35], v[240:243], v[248:251], v[32:35]
	global_load_lds_dwordx4 v190, s[4:5]
	v_mfma_f32_16x16x32_bf16 v[36:39], v[240:243], v[200:203], v[36:39]
	v_mfma_f32_16x16x32_bf16 v[40:43], v[244:247], v[248:251], v[40:43]
	v_mfma_f32_16x16x32_bf16 v[44:47], v[244:247], v[200:203], v[44:47]
	ds_read_b128 v[248:251], v129 offset:53248
	ds_read_b128 v[200:203], v129 offset:54272
	v_mfma_f32_16x16x32_bf16 v[16:19], v[184:187], v[204:207], v[16:19]
	s_add_u32 m0, s8, 0x9000
	v_mfma_f32_16x16x32_bf16 v[20:23], v[184:187], v[208:211], v[20:23]
	global_load_lds_dwordx4 v191, s[4:5]
	s_add_u32 m0, s8, 0xa000
	v_mfma_f32_16x16x32_bf16 v[24:27], v[236:239], v[204:207], v[24:27]
	global_load_lds_dwordx4 v189, s[6:7]
	s_add_u32 m0, s8, 0xb000
	v_mfma_f32_16x16x32_bf16 v[28:31], v[236:239], v[208:211], v[28:31]
	global_load_lds_dwordx4 v252, s[6:7]
	s_add_u32 s4, s4, 0x202000
	s_addc_u32 s5, s5, 0
	v_mfma_f32_16x16x32_bf16 v[0:3], v[240:243], v[204:207], v[0:3]
	s_add_u32 s6, s6, 0x40000
	s_addc_u32 s7, s7, 0
	v_mfma_f32_16x16x32_bf16 v[4:7], v[240:243], v[208:211], v[4:7]
	v_mfma_f32_16x16x32_bf16 v[8:11], v[244:247], v[204:207], v[8:11]
	v_mfma_f32_16x16x32_bf16 v[12:15], v[244:247], v[208:211], v[12:15]
	s_waitcnt lgkmcnt(2)
	v_mfma_f32_16x16x32_bf16 v[112:115], v[132:135], v[212:215], v[112:115]
	ds_read_b128 v[204:207], v129 offset:57344
	v_mfma_f32_16x16x32_bf16 v[116:119], v[132:135], v[216:219], v[116:119]
	ds_read_b128 v[208:211], v129 offset:58368
	v_mfma_f32_16x16x32_bf16 v[120:123], v[136:139], v[212:215], v[120:123]
	v_mfma_f32_16x16x32_bf16 v[124:127], v[136:139], v[216:219], v[124:127]
	v_mfma_f32_16x16x32_bf16 v[96:99], v[140:143], v[212:215], v[96:99]
	v_mfma_f32_16x16x32_bf16 v[100:103], v[140:143], v[216:219], v[100:103]
	v_mfma_f32_16x16x32_bf16 v[104:107], v[180:183], v[212:215], v[104:107]
	v_mfma_f32_16x16x32_bf16 v[108:111], v[180:183], v[216:219], v[108:111]
	s_waitcnt lgkmcnt(2)
	v_mfma_f32_16x16x32_bf16 v[80:83], v[132:135], v[248:251], v[80:83]
	ds_read_b128 v[212:215], v129 offset:61440
	v_mfma_f32_16x16x32_bf16 v[84:87], v[132:135], v[200:203], v[84:87]
	ds_read_b128 v[216:219], v129 offset:62464
	v_mfma_f32_16x16x32_bf16 v[88:91], v[136:139], v[248:251], v[88:91]
	v_mfma_f32_16x16x32_bf16 v[92:95], v[136:139], v[200:203], v[92:95]
	v_mfma_f32_16x16x32_bf16 v[64:67], v[140:143], v[248:251], v[64:67]
	v_mfma_f32_16x16x32_bf16 v[68:71], v[140:143], v[200:203], v[68:71]
	v_mfma_f32_16x16x32_bf16 v[72:75], v[180:183], v[248:251], v[72:75]
	v_mfma_f32_16x16x32_bf16 v[76:79], v[180:183], v[200:203], v[76:79]
	s_waitcnt lgkmcnt(0)
	s_waitcnt vmcnt(6)
	s_barrier
	ds_read_b128 v[184:187], v156
	ds_read_b128 v[236:239], v156 offset:1024
	v_mfma_f32_16x16x32_bf16 v[48:51], v[132:135], v[204:207], v[48:51]
	ds_read_b128 v[240:243], v156 offset:2048
	ds_read_b128 v[244:247], v156 offset:3072
	v_mfma_f32_16x16x32_bf16 v[52:55], v[132:135], v[208:211], v[52:55]
	ds_read_b128 v[248:251], v129
	ds_read_b128 v[200:203], v129 offset:1024
	s_add_u32 m0, s8, 0xc000
	v_mfma_f32_16x16x32_bf16 v[56:59], v[136:139], v[204:207], v[56:59]
	global_load_lds_dwordx4 v189, s[4:5]
	s_add_u32 m0, s8, 0xd000
	v_mfma_f32_16x16x32_bf16 v[60:63], v[136:139], v[208:211], v[60:63]
	global_load_lds_dwordx4 v252, s[4:5]
	s_add_u32 m0, s8, 0xe000
	v_mfma_f32_16x16x32_bf16 v[32:35], v[140:143], v[204:207], v[32:35]
	global_load_lds_dwordx4 v190, s[4:5]
	v_mfma_f32_16x16x32_bf16 v[36:39], v[140:143], v[208:211], v[36:39]
	v_mfma_f32_16x16x32_bf16 v[40:43], v[180:183], v[204:207], v[40:43]
	v_mfma_f32_16x16x32_bf16 v[44:47], v[180:183], v[208:211], v[44:47]
	ds_read_b128 v[204:207], v129 offset:4096
	ds_read_b128 v[208:211], v129 offset:5120
	v_mfma_f32_16x16x32_bf16 v[16:19], v[132:135], v[212:215], v[16:19]
	s_add_u32 m0, s8, 0xf000
	v_mfma_f32_16x16x32_bf16 v[20:23], v[132:135], v[216:219], v[20:23]
	global_load_lds_dwordx4 v191, s[4:5]
	s_add_u32 m0, s8, 0x10000
	v_mfma_f32_16x16x32_bf16 v[24:27], v[136:139], v[212:215], v[24:27]
	global_load_lds_dwordx4 v189, s[6:7]
	s_add_u32 m0, s8, 0x11000
	v_mfma_f32_16x16x32_bf16 v[28:31], v[136:139], v[216:219], v[28:31]
	global_load_lds_dwordx4 v252, s[6:7]
	s_add_u32 s4, s4, 0x202000
	s_addc_u32 s5, s5, 0
	v_mfma_f32_16x16x32_bf16 v[0:3], v[140:143], v[212:215], v[0:3]
	s_add_u32 s6, s6, 0x40000
	s_addc_u32 s7, s7, 0
	v_mfma_f32_16x16x32_bf16 v[4:7], v[140:143], v[216:219], v[4:7]
	v_mfma_f32_16x16x32_bf16 v[8:11], v[180:183], v[212:215], v[8:11]
	v_mfma_f32_16x16x32_bf16 v[12:15], v[180:183], v[216:219], v[12:15]
	s_waitcnt lgkmcnt(2)
	v_mfma_f32_16x16x32_bf16 v[112:115], v[184:187], v[248:251], v[112:115]
	ds_read_b128 v[212:215], v129 offset:8192
	v_mfma_f32_16x16x32_bf16 v[116:119], v[184:187], v[200:203], v[116:119]
	ds_read_b128 v[216:219], v129 offset:9216
	v_mfma_f32_16x16x32_bf16 v[120:123], v[236:239], v[248:251], v[120:123]
	v_mfma_f32_16x16x32_bf16 v[124:127], v[236:239], v[200:203], v[124:127]
	v_mfma_f32_16x16x32_bf16 v[96:99], v[240:243], v[248:251], v[96:99]
	v_mfma_f32_16x16x32_bf16 v[100:103], v[240:243], v[200:203], v[100:103]
	v_mfma_f32_16x16x32_bf16 v[104:107], v[244:247], v[248:251], v[104:107]
	v_mfma_f32_16x16x32_bf16 v[108:111], v[244:247], v[200:203], v[108:111]
	s_waitcnt lgkmcnt(2)
	v_mfma_f32_16x16x32_bf16 v[80:83], v[184:187], v[204:207], v[80:83]
	ds_read_b128 v[248:251], v129 offset:12288
	v_mfma_f32_16x16x32_bf16 v[84:87], v[184:187], v[208:211], v[84:87]
	ds_read_b128 v[200:203], v129 offset:13312
	v_mfma_f32_16x16x32_bf16 v[88:91], v[236:239], v[204:207], v[88:91]
	v_mfma_f32_16x16x32_bf16 v[92:95], v[236:239], v[208:211], v[92:95]
	v_mfma_f32_16x16x32_bf16 v[64:67], v[240:243], v[204:207], v[64:67]
	v_mfma_f32_16x16x32_bf16 v[68:71], v[240:243], v[208:211], v[68:71]
	v_mfma_f32_16x16x32_bf16 v[72:75], v[244:247], v[204:207], v[72:75]
	v_mfma_f32_16x16x32_bf16 v[76:79], v[244:247], v[208:211], v[76:79]
	s_waitcnt lgkmcnt(0)
	s_waitcnt vmcnt(6)
	s_barrier
	ds_read_b128 v[132:135], v156 offset:24576
	ds_read_b128 v[136:139], v156 offset:25600
	v_mfma_f32_16x16x32_bf16 v[48:51], v[184:187], v[212:215], v[48:51]
	ds_read_b128 v[140:143], v156 offset:26624
	ds_read_b128 v[180:183], v156 offset:27648
	v_mfma_f32_16x16x32_bf16 v[52:55], v[184:187], v[216:219], v[52:55]
	ds_read_b128 v[204:207], v129 offset:24576
	ds_read_b128 v[208:211], v129 offset:25600
	s_add_u32 m0, s8, 0x0
	v_mfma_f32_16x16x32_bf16 v[56:59], v[236:239], v[212:215], v[56:59]
	global_load_lds_dwordx4 v189, s[4:5]
	s_add_u32 m0, s8, 0x1000
	v_mfma_f32_16x16x32_bf16 v[60:63], v[236:239], v[216:219], v[60:63]
	global_load_lds_dwordx4 v252, s[4:5]
	s_add_u32 m0, s8, 0x2000
	v_mfma_f32_16x16x32_bf16 v[32:35], v[240:243], v[212:215], v[32:35]
	global_load_lds_dwordx4 v190, s[4:5]
	v_mfma_f32_16x16x32_bf16 v[36:39], v[240:243], v[216:219], v[36:39]
	v_mfma_f32_16x16x32_bf16 v[40:43], v[244:247], v[212:215], v[40:43]
	v_mfma_f32_16x16x32_bf16 v[44:47], v[244:247], v[216:219], v[44:47]
	ds_read_b128 v[212:215], v129 offset:28672
	ds_read_b128 v[216:219], v129 offset:29696
	v_mfma_f32_16x16x32_bf16 v[16:19], v[184:187], v[248:251], v[16:19]
	s_add_u32 m0, s8, 0x3000
	v_mfma_f32_16x16x32_bf16 v[20:23], v[184:187], v[200:203], v[20:23]
	global_load_lds_dwordx4 v191, s[4:5]
	s_add_u32 m0, s8, 0x4000
	v_mfma_f32_16x16x32_bf16 v[24:27], v[236:239], v[248:251], v[24:27]
	global_load_lds_dwordx4 v189, s[6:7]
	s_add_u32 m0, s8, 0x5000
	v_mfma_f32_16x16x32_bf16 v[28:31], v[236:239], v[200:203], v[28:31]
	global_load_lds_dwordx4 v252, s[6:7]
	s_add_u32 s4, s4, 0x202000
	s_addc_u32 s5, s5, 0
	v_mfma_f32_16x16x32_bf16 v[0:3], v[240:243], v[248:251], v[0:3]
	s_add_u32 s6, s6, 0x40000
	s_addc_u32 s7, s7, 0
	v_mfma_f32_16x16x32_bf16 v[4:7], v[240:243], v[200:203], v[4:7]
	v_mfma_f32_16x16x32_bf16 v[8:11], v[244:247], v[248:251], v[8:11]
	v_mfma_f32_16x16x32_bf16 v[12:15], v[244:247], v[200:203], v[12:15]
	s_waitcnt lgkmcnt(2)
	v_mfma_f32_16x16x32_bf16 v[112:115], v[132:135], v[204:207], v[112:115]
	ds_read_b128 v[248:251], v129 offset:32768
	v_mfma_f32_16x16x32_bf16 v[116:119], v[132:135], v[208:211], v[116:119]
	ds_read_b128 v[200:203], v129 offset:33792
	v_mfma_f32_16x16x32_bf16 v[120:123], v[136:139], v[204:207], v[120:123]
	v_mfma_f32_16x16x32_bf16 v[124:127], v[136:139], v[208:211], v[124:127]
	v_mfma_f32_16x16x32_bf16 v[96:99], v[140:143], v[204:207], v[96:99]
	v_mfma_f32_16x16x32_bf16 v[100:103], v[140:143], v[208:211], v[100:103]
	v_mfma_f32_16x16x32_bf16 v[104:107], v[180:183], v[204:207], v[104:107]
	v_mfma_f32_16x16x32_bf16 v[108:111], v[180:183], v[208:211], v[108:111]
	s_waitcnt lgkmcnt(2)
	v_mfma_f32_16x16x32_bf16 v[80:83], v[132:135], v[212:215], v[80:83]
	ds_read_b128 v[204:207], v129 offset:36864
	v_mfma_f32_16x16x32_bf16 v[84:87], v[132:135], v[216:219], v[84:87]
	ds_read_b128 v[208:211], v129 offset:37888
	v_mfma_f32_16x16x32_bf16 v[88:91], v[136:139], v[212:215], v[88:91]
	v_mfma_f32_16x16x32_bf16 v[92:95], v[136:139], v[216:219], v[92:95]
	v_mfma_f32_16x16x32_bf16 v[64:67], v[140:143], v[212:215], v[64:67]
	v_mfma_f32_16x16x32_bf16 v[68:71], v[140:143], v[216:219], v[68:71]
	v_mfma_f32_16x16x32_bf16 v[72:75], v[180:183], v[212:215], v[72:75]
	v_mfma_f32_16x16x32_bf16 v[76:79], v[180:183], v[216:219], v[76:79]
	s_waitcnt lgkmcnt(0)
	s_waitcnt vmcnt(6)
	s_barrier
	ds_read_b128 v[184:187], v156 offset:49152
	ds_read_b128 v[236:239], v156 offset:50176
	v_mfma_f32_16x16x32_bf16 v[48:51], v[132:135], v[248:251], v[48:51]
	ds_read_b128 v[240:243], v156 offset:51200
	ds_read_b128 v[244:247], v156 offset:52224
	v_mfma_f32_16x16x32_bf16 v[52:55], v[132:135], v[200:203], v[52:55]
	ds_read_b128 v[212:215], v129 offset:49152
	ds_read_b128 v[216:219], v129 offset:50176
	s_add_u32 m0, s8, 0x6000
	v_mfma_f32_16x16x32_bf16 v[56:59], v[136:139], v[248:251], v[56:59]
	global_load_lds_dwordx4 v189, s[4:5]
	s_add_u32 m0, s8, 0x7000
	v_mfma_f32_16x16x32_bf16 v[60:63], v[136:139], v[200:203], v[60:63]
	global_load_lds_dwordx4 v252, s[4:5]
	s_add_u32 m0, s8, 0x8000
	v_mfma_f32_16x16x32_bf16 v[32:35], v[140:143], v[248:251], v[32:35]
	global_load_lds_dwordx4 v190, s[4:5]
	v_mfma_f32_16x16x32_bf16 v[36:39], v[140:143], v[200:203], v[36:39]
	v_mfma_f32_16x16x32_bf16 v[40:43], v[180:183], v[248:251], v[40:43]
	v_mfma_f32_16x16x32_bf16 v[44:47], v[180:183], v[200:203], v[44:47]
	ds_read_b128 v[248:251], v129 offset:53248
	ds_read_b128 v[200:203], v129 offset:54272
	v_mfma_f32_16x16x32_bf16 v[16:19], v[132:135], v[204:207], v[16:19]
	s_add_u32 m0, s8, 0x9000
	v_mfma_f32_16x16x32_bf16 v[20:23], v[132:135], v[208:211], v[20:23]
	global_load_lds_dwordx4 v191, s[4:5]
	s_add_u32 m0, s8, 0xa000
	v_mfma_f32_16x16x32_bf16 v[24:27], v[136:139], v[204:207], v[24:27]
	global_load_lds_dwordx4 v189, s[6:7]
	s_add_u32 m0, s8, 0xb000
	v_mfma_f32_16x16x32_bf16 v[28:31], v[136:139], v[208:211], v[28:31]
	global_load_lds_dwordx4 v252, s[6:7]
	s_add_u32 s4, s4, 0x202000
	s_addc_u32 s5, s5, 0
	v_mfma_f32_16x16x32_bf16 v[0:3], v[140:143], v[204:207], v[0:3]
	s_add_u32 s6, s6, 0x40000
	s_addc_u32 s7, s7, 0
	v_mfma_f32_16x16x32_bf16 v[4:7], v[140:143], v[208:211], v[4:7]
	v_mfma_f32_16x16x32_bf16 v[8:11], v[180:183], v[204:207], v[8:11]
	v_mfma_f32_16x16x32_bf16 v[12:15], v[180:183], v[208:211], v[12:15]
	s_waitcnt lgkmcnt(2)
	v_mfma_f32_16x16x32_bf16 v[112:115], v[184:187], v[212:215], v[112:115]
	ds_read_b128 v[204:207], v129 offset:57344
	v_mfma_f32_16x16x32_bf16 v[116:119], v[184:187], v[216:219], v[116:119]
	ds_read_b128 v[208:211], v129 offset:58368
	v_mfma_f32_16x16x32_bf16 v[120:123], v[236:239], v[212:215], v[120:123]
	v_mfma_f32_16x16x32_bf16 v[124:127], v[236:239], v[216:219], v[124:127]
	v_mfma_f32_16x16x32_bf16 v[96:99], v[240:243], v[212:215], v[96:99]
	v_mfma_f32_16x16x32_bf16 v[100:103], v[240:243], v[216:219], v[100:103]
	v_mfma_f32_16x16x32_bf16 v[104:107], v[244:247], v[212:215], v[104:107]
	v_mfma_f32_16x16x32_bf16 v[108:111], v[244:247], v[216:219], v[108:111]
	s_waitcnt lgkmcnt(2)
	v_mfma_f32_16x16x32_bf16 v[80:83], v[184:187], v[248:251], v[80:83]
	ds_read_b128 v[212:215], v129 offset:61440
	v_mfma_f32_16x16x32_bf16 v[84:87], v[184:187], v[200:203], v[84:87]
	ds_read_b128 v[216:219], v129 offset:62464
	v_mfma_f32_16x16x32_bf16 v[88:91], v[236:239], v[248:251], v[88:91]
	v_mfma_f32_16x16x32_bf16 v[92:95], v[236:239], v[200:203], v[92:95]
	v_mfma_f32_16x16x32_bf16 v[64:67], v[240:243], v[248:251], v[64:67]
	v_mfma_f32_16x16x32_bf16 v[68:71], v[240:243], v[200:203], v[68:71]
	v_mfma_f32_16x16x32_bf16 v[72:75], v[244:247], v[248:251], v[72:75]
	v_mfma_f32_16x16x32_bf16 v[76:79], v[244:247], v[200:203], v[76:79]
	s_waitcnt lgkmcnt(0)
	s_waitcnt vmcnt(6)
	s_barrier
	ds_read_b128 v[132:135], v156
	ds_read_b128 v[136:139], v156 offset:1024
	v_mfma_f32_16x16x32_bf16 v[48:51], v[184:187], v[204:207], v[48:51]
	ds_read_b128 v[140:143], v156 offset:2048
	ds_read_b128 v[180:183], v156 offset:3072
	v_mfma_f32_16x16x32_bf16 v[52:55], v[184:187], v[208:211], v[52:55]
	ds_read_b128 v[248:251], v129
	ds_read_b128 v[200:203], v129 offset:1024
	s_add_u32 m0, s8, 0xc000
	v_mfma_f32_16x16x32_bf16 v[56:59], v[236:239], v[204:207], v[56:59]
	global_load_lds_dwordx4 v189, s[4:5]
	s_add_u32 m0, s8, 0xd000
	v_mfma_f32_16x16x32_bf16 v[60:63], v[236:239], v[208:211], v[60:63]
	global_load_lds_dwordx4 v252, s[4:5]
	s_add_u32 m0, s8, 0xe000
	v_mfma_f32_16x16x32_bf16 v[32:35], v[240:243], v[204:207], v[32:35]
	global_load_lds_dwordx4 v190, s[4:5]
	v_mfma_f32_16x16x32_bf16 v[36:39], v[240:243], v[208:211], v[36:39]
	v_mfma_f32_16x16x32_bf16 v[40:43], v[244:247], v[204:207], v[40:43]
	v_mfma_f32_16x16x32_bf16 v[44:47], v[244:247], v[208:211], v[44:47]
	ds_read_b128 v[204:207], v129 offset:4096
	ds_read_b128 v[208:211], v129 offset:5120
	v_mfma_f32_16x16x32_bf16 v[16:19], v[184:187], v[212:215], v[16:19]
	s_add_u32 m0, s8, 0xf000
	v_mfma_f32_16x16x32_bf16 v[20:23], v[184:187], v[216:219], v[20:23]
	global_load_lds_dwordx4 v191, s[4:5]
	s_add_u32 m0, s8, 0x10000
	v_mfma_f32_16x16x32_bf16 v[24:27], v[236:239], v[212:215], v[24:27]
	global_load_lds_dwordx4 v189, s[6:7]
	s_add_u32 m0, s8, 0x11000
	v_mfma_f32_16x16x32_bf16 v[28:31], v[236:239], v[216:219], v[28:31]
	global_load_lds_dwordx4 v252, s[6:7]
	s_add_u32 s4, s4, 0x202000
	s_addc_u32 s5, s5, 0
	v_mfma_f32_16x16x32_bf16 v[0:3], v[240:243], v[212:215], v[0:3]
	s_add_u32 s6, s6, 0x40000
	s_addc_u32 s7, s7, 0
	v_mfma_f32_16x16x32_bf16 v[4:7], v[240:243], v[216:219], v[4:7]
	v_mfma_f32_16x16x32_bf16 v[8:11], v[244:247], v[212:215], v[8:11]
	v_mfma_f32_16x16x32_bf16 v[12:15], v[244:247], v[216:219], v[12:15]
	s_mov_b32 s9, 3
.Lgemm_p4_loop:
	s_waitcnt lgkmcnt(2)
	v_mfma_f32_16x16x32_bf16 v[112:115], v[132:135], v[248:251], v[112:115]
	ds_read_b128 v[212:215], v129 offset:8192
	v_mfma_f32_16x16x32_bf16 v[116:119], v[132:135], v[200:203], v[116:119]
	ds_read_b128 v[216:219], v129 offset:9216
	v_mfma_f32_16x16x32_bf16 v[120:123], v[136:139], v[248:251], v[120:123]
	v_mfma_f32_16x16x32_bf16 v[124:127], v[136:139], v[200:203], v[124:127]
	v_mfma_f32_16x16x32_bf16 v[96:99], v[140:143], v[248:251], v[96:99]
	v_mfma_f32_16x16x32_bf16 v[100:103], v[140:143], v[200:203], v[100:103]
	v_mfma_f32_16x16x32_bf16 v[104:107], v[180:183], v[248:251], v[104:107]
	v_mfma_f32_16x16x32_bf16 v[108:111], v[180:183], v[200:203], v[108:111]
	s_waitcnt lgkmcnt(2)
	v_mfma_f32_16x16x32_bf16 v[80:83], v[132:135], v[204:207], v[80:83]
	ds_read_b128 v[248:251], v129 offset:12288
	v_mfma_f32_16x16x32_bf16 v[84:87], v[132:135], v[208:211], v[84:87]
	ds_read_b128 v[200:203], v129 offset:13312
	v_mfma_f32_16x16x32_bf16 v[88:91], v[136:139], v[204:207], v[88:91]
	v_mfma_f32_16x16x32_bf16 v[92:95], v[136:139], v[208:211], v[92:95]
	v_mfma_f32_16x16x32_bf16 v[64:67], v[140:143], v[204:207], v[64:67]
	v_mfma_f32_16x16x32_bf16 v[68:71], v[140:143], v[208:211], v[68:71]
	v_mfma_f32_16x16x32_bf16 v[72:75], v[180:183], v[204:207], v[72:75]
	v_mfma_f32_16x16x32_bf16 v[76:79], v[180:183], v[208:211], v[76:79]
	s_waitcnt lgkmcnt(0)
	s_waitcnt vmcnt(6)
	s_barrier
	ds_read_b128 v[184:187], v156 offset:24576
	ds_read_b128 v[236:239], v156 offset:25600
	v_mfma_f32_16x16x32_bf16 v[48:51], v[132:135], v[212:215], v[48:51]
	ds_read_b128 v[240:243], v156 offset:26624
	ds_read_b128 v[244:247], v156 offset:27648
	v_mfma_f32_16x16x32_bf16 v[52:55], v[132:135], v[216:219], v[52:55]
	ds_read_b128 v[204:207], v129 offset:24576
	ds_read_b128 v[208:211], v129 offset:25600
	s_add_u32 m0, s8, 0x0
	v_mfma_f32_16x16x32_bf16 v[56:59], v[136:139], v[212:215], v[56:59]
	global_load_lds_dwordx4 v189, s[4:5]
	s_add_u32 m0, s8, 0x1000
	v_mfma_f32_16x16x32_bf16 v[60:63], v[136:139], v[216:219], v[60:63]
	global_load_lds_dwordx4 v252, s[4:5]
	s_add_u32 m0, s8, 0x2000
	v_mfma_f32_16x16x32_bf16 v[32:35], v[140:143], v[212:215], v[32:35]
	global_load_lds_dwordx4 v190, s[4:5]
	v_mfma_f32_16x16x32_bf16 v[36:39], v[140:143], v[216:219], v[36:39]
	v_mfma_f32_16x16x32_bf16 v[40:43], v[180:183], v[212:215], v[40:43]
	v_mfma_f32_16x16x32_bf16 v[44:47], v[180:183], v[216:219], v[44:47]
	ds_read_b128 v[212:215], v129 offset:28672
	ds_read_b128 v[216:219], v129 offset:29696
	v_mfma_f32_16x16x32_bf16 v[16:19], v[132:135], v[248:251], v[16:19]
	s_add_u32 m0, s8, 0x3000
	v_mfma_f32_16x16x32_bf16 v[20:23], v[132:135], v[200:203], v[20:23]
	global_load_lds_dwordx4 v191, s[4:5]
	s_add_u32 m0, s8, 0x4000
	v_mfma_f32_16x16x32_bf16 v[24:27], v[136:139], v[248:251], v[24:27]
	global_load_lds_dwordx4 v189, s[6:7]
	s_add_u32 m0, s8, 0x5000
	v_mfma_f32_16x16x32_bf16 v[28:31], v[136:139], v[200:203], v[28:31]
	global_load_lds_dwordx4 v252, s[6:7]
	s_add_u32 s4, s4, 0x202000
	s_addc_u32 s5, s5, 0
	v_mfma_f32_16x16x32_bf16 v[0:3], v[140:143], v[248:251], v[0:3]
	s_add_u32 s6, s6, 0x40000
	s_addc_u32 s7, s7, 0
	v_mfma_f32_16x16x32_bf16 v[4:7], v[140:143], v[200:203], v[4:7]
	v_mfma_f32_16x16x32_bf16 v[8:11], v[180:183], v[248:251], v[8:11]
	v_mfma_f32_16x16x32_bf16 v[12:15], v[180:183], v[200:203], v[12:15]
	s_waitcnt lgkmcnt(2)
	v_mfma_f32_16x16x32_bf16 v[112:115], v[184:187], v[204:207], v[112:115]
	ds_read_b128 v[248:251], v129 offset:32768
	v_mfma_f32_16x16x32_bf16 v[116:119], v[184:187], v[208:211], v[116:119]
	ds_read_b128 v[200:203], v129 offset:33792
	v_mfma_f32_16x16x32_bf16 v[120:123], v[236:239], v[204:207], v[120:123]
	v_mfma_f32_16x16x32_bf16 v[124:127], v[236:239], v[208:211], v[124:127]
	v_mfma_f32_16x16x32_bf16 v[96:99], v[240:243], v[204:207], v[96:99]
	v_mfma_f32_16x16x32_bf16 v[100:103], v[240:243], v[208:211], v[100:103]
	v_mfma_f32_16x16x32_bf16 v[104:107], v[244:247], v[204:207], v[104:107]
	v_mfma_f32_16x16x32_bf16 v[108:111], v[244:247], v[208:211], v[108:111]
	s_waitcnt lgkmcnt(2)
	v_mfma_f32_16x16x32_bf16 v[80:83], v[184:187], v[212:215], v[80:83]
	ds_read_b128 v[204:207], v129 offset:36864
	v_mfma_f32_16x16x32_bf16 v[84:87], v[184:187], v[216:219], v[84:87]
	ds_read_b128 v[208:211], v129 offset:37888
	v_mfma_f32_16x16x32_bf16 v[88:91], v[236:239], v[212:215], v[88:91]
	v_mfma_f32_16x16x32_bf16 v[92:95], v[236:239], v[216:219], v[92:95]
	v_mfma_f32_16x16x32_bf16 v[64:67], v[240:243], v[212:215], v[64:67]
	v_mfma_f32_16x16x32_bf16 v[68:71], v[240:243], v[216:219], v[68:71]
	v_mfma_f32_16x16x32_bf16 v[72:75], v[244:247], v[212:215], v[72:75]
	v_mfma_f32_16x16x32_bf16 v[76:79], v[244:247], v[216:219], v[76:79]
	s_waitcnt lgkmcnt(0)
	s_waitcnt vmcnt(6)
	s_barrier
	ds_read_b128 v[132:135], v156 offset:49152
	ds_read_b128 v[136:139], v156 offset:50176
	v_mfma_f32_16x16x32_bf16 v[48:51], v[184:187], v[248:251], v[48:51]
	ds_read_b128 v[140:143], v156 offset:51200
	ds_read_b128 v[180:183], v156 offset:52224
	v_mfma_f32_16x16x32_bf16 v[52:55], v[184:187], v[200:203], v[52:55]
	ds_read_b128 v[212:215], v129 offset:49152
	ds_read_b128 v[216:219], v129 offset:50176
	s_add_u32 m0, s8, 0x6000
	v_mfma_f32_16x16x32_bf16 v[56:59], v[236:239], v[248:251], v[56:59]
	global_load_lds_dwordx4 v189, s[4:5]
	s_add_u32 m0, s8, 0x7000
	v_mfma_f32_16x16x32_bf16 v[60:63], v[236:239], v[200:203], v[60:63]
	global_load_lds_dwordx4 v252, s[4:5]
	s_add_u32 m0, s8, 0x8000
	v_mfma_f32_16x16x32_bf16 v[32:35], v[240:243], v[248:251], v[32:35]
	global_load_lds_dwordx4 v190, s[4:5]
	v_mfma_f32_16x16x32_bf16 v[36:39], v[240:243], v[200:203], v[36:39]
	v_mfma_f32_16x16x32_bf16 v[40:43], v[244:247], v[248:251], v[40:43]
	v_mfma_f32_16x16x32_bf16 v[44:47], v[244:247], v[200:203], v[44:47]
	ds_read_b128 v[248:251], v129 offset:53248
	ds_read_b128 v[200:203], v129 offset:54272
	v_mfma_f32_16x16x32_bf16 v[16:19], v[184:187], v[204:207], v[16:19]
	s_add_u32 m0, s8, 0x9000
	v_mfma_f32_16x16x32_bf16 v[20:23], v[184:187], v[208:211], v[20:23]
	global_load_lds_dwordx4 v191, s[4:5]
	s_add_u32 m0, s8, 0xa000
	v_mfma_f32_16x16x32_bf16 v[24:27], v[236:239], v[204:207], v[24:27]
	global_load_lds_dwordx4 v189, s[6:7]
	s_add_u32 m0, s8, 0xb000
	v_mfma_f32_16x16x32_bf16 v[28:31], v[236:239], v[208:211], v[28:31]
	global_load_lds_dwordx4 v252, s[6:7]
	s_add_u32 s4, s4, 0x202000
	s_addc_u32 s5, s5, 0
	v_mfma_f32_16x16x32_bf16 v[0:3], v[240:243], v[204:207], v[0:3]
	s_add_u32 s6, s6, 0x40000
	s_addc_u32 s7, s7, 0
	v_mfma_f32_16x16x32_bf16 v[4:7], v[240:243], v[208:211], v[4:7]
	v_mfma_f32_16x16x32_bf16 v[8:11], v[244:247], v[204:207], v[8:11]
	v_mfma_f32_16x16x32_bf16 v[12:15], v[244:247], v[208:211], v[12:15]
	s_waitcnt lgkmcnt(2)
	v_mfma_f32_16x16x32_bf16 v[112:115], v[132:135], v[212:215], v[112:115]
	ds_read_b128 v[204:207], v129 offset:57344
	v_mfma_f32_16x16x32_bf16 v[116:119], v[132:135], v[216:219], v[116:119]
	ds_read_b128 v[208:211], v129 offset:58368
	v_mfma_f32_16x16x32_bf16 v[120:123], v[136:139], v[212:215], v[120:123]
	v_mfma_f32_16x16x32_bf16 v[124:127], v[136:139], v[216:219], v[124:127]
	v_mfma_f32_16x16x32_bf16 v[96:99], v[140:143], v[212:215], v[96:99]
	v_mfma_f32_16x16x32_bf16 v[100:103], v[140:143], v[216:219], v[100:103]
	v_mfma_f32_16x16x32_bf16 v[104:107], v[180:183], v[212:215], v[104:107]
	v_mfma_f32_16x16x32_bf16 v[108:111], v[180:183], v[216:219], v[108:111]
	s_waitcnt lgkmcnt(2)
	v_mfma_f32_16x16x32_bf16 v[80:83], v[132:135], v[248:251], v[80:83]
	ds_read_b128 v[212:215], v129 offset:61440
	v_mfma_f32_16x16x32_bf16 v[84:87], v[132:135], v[200:203], v[84:87]
	ds_read_b128 v[216:219], v129 offset:62464
	v_mfma_f32_16x16x32_bf16 v[88:91], v[136:139], v[248:251], v[88:91]
	v_mfma_f32_16x16x32_bf16 v[92:95], v[136:139], v[200:203], v[92:95]
	v_mfma_f32_16x16x32_bf16 v[64:67], v[140:143], v[248:251], v[64:67]
	v_mfma_f32_16x16x32_bf16 v[68:71], v[140:143], v[200:203], v[68:71]
	v_mfma_f32_16x16x32_bf16 v[72:75], v[180:183], v[248:251], v[72:75]
	v_mfma_f32_16x16x32_bf16 v[76:79], v[180:183], v[200:203], v[76:79]
	s_waitcnt lgkmcnt(0)
	s_waitcnt vmcnt(6)
	s_barrier
	ds_read_b128 v[184:187], v156
	ds_read_b128 v[236:239], v156 offset:1024
	v_mfma_f32_16x16x32_bf16 v[48:51], v[132:135], v[204:207], v[48:51]
	ds_read_b128 v[240:243], v156 offset:2048
	ds_read_b128 v[244:247], v156 offset:3072
	v_mfma_f32_16x16x32_bf16 v[52:55], v[132:135], v[208:211], v[52:55]
	ds_read_b128 v[248:251], v129
	ds_read_b128 v[200:203], v129 offset:1024
	s_add_u32 m0, s8, 0xc000
	v_mfma_f32_16x16x32_bf16 v[56:59], v[136:139], v[204:207], v[56:59]
	global_load_lds_dwordx4 v189, s[4:5]
	s_add_u32 m0, s8, 0xd000
	v_mfma_f32_16x16x32_bf16 v[60:63], v[136:139], v[208:211], v[60:63]
	global_load_lds_dwordx4 v252, s[4:5]
	s_add_u32 m0, s8, 0xe000
	v_mfma_f32_16x16x32_bf16 v[32:35], v[140:143], v[204:207], v[32:35]
	global_load_lds_dwordx4 v190, s[4:5]
	v_mfma_f32_16x16x32_bf16 v[36:39], v[140:143], v[208:211], v[36:39]
	v_mfma_f32_16x16x32_bf16 v[40:43], v[180:183], v[204:207], v[40:43]
	v_mfma_f32_16x16x32_bf16 v[44:47], v[180:183], v[208:211], v[44:47]
	ds_read_b128 v[204:207], v129 offset:4096
	ds_read_b128 v[208:211], v129 offset:5120
	v_mfma_f32_16x16x32_bf16 v[16:19], v[132:135], v[212:215], v[16:19]
	s_add_u32 m0, s8, 0xf000
	v_mfma_f32_16x16x32_bf16 v[20:23], v[132:135], v[216:219], v[20:23]
	global_load_lds_dwordx4 v191, s[4:5]
	s_add_u32 m0, s8, 0x10000
	v_mfma_f32_16x16x32_bf16 v[24:27], v[136:139], v[212:215], v[24:27]
	global_load_lds_dwordx4 v189, s[6:7]
	s_add_u32 m0, s8, 0x11000
	v_mfma_f32_16x16x32_bf16 v[28:31], v[136:139], v[216:219], v[28:31]
	global_load_lds_dwordx4 v252, s[6:7]
	s_add_u32 s4, s4, 0x202000
	s_addc_u32 s5, s5, 0
	v_mfma_f32_16x16x32_bf16 v[0:3], v[140:143], v[212:215], v[0:3]
	s_add_u32 s6, s6, 0x40000
	s_addc_u32 s7, s7, 0
	v_mfma_f32_16x16x32_bf16 v[4:7], v[140:143], v[216:219], v[4:7]
	v_mfma_f32_16x16x32_bf16 v[8:11], v[180:183], v[212:215], v[8:11]
	v_mfma_f32_16x16x32_bf16 v[12:15], v[180:183], v[216:219], v[12:15]
	s_waitcnt lgkmcnt(2)
	v_mfma_f32_16x16x32_bf16 v[112:115], v[184:187], v[248:251], v[112:115]
	ds_read_b128 v[212:215], v129 offset:8192
	v_mfma_f32_16x16x32_bf16 v[116:119], v[184:187], v[200:203], v[116:119]
	ds_read_b128 v[216:219], v129 offset:9216
	v_mfma_f32_16x16x32_bf16 v[120:123], v[236:239], v[248:251], v[120:123]
	v_mfma_f32_16x16x32_bf16 v[124:127], v[236:239], v[200:203], v[124:127]
	v_mfma_f32_16x16x32_bf16 v[96:99], v[240:243], v[248:251], v[96:99]
	v_mfma_f32_16x16x32_bf16 v[100:103], v[240:243], v[200:203], v[100:103]
	v_mfma_f32_16x16x32_bf16 v[104:107], v[244:247], v[248:251], v[104:107]
	v_mfma_f32_16x16x32_bf16 v[108:111], v[244:247], v[200:203], v[108:111]
	s_waitcnt lgkmcnt(2)
	v_mfma_f32_16x16x32_bf16 v[80:83], v[184:187], v[204:207], v[80:83]
	ds_read_b128 v[248:251], v129 offset:12288
	v_mfma_f32_16x16x32_bf16 v[84:87], v[184:187], v[208:211], v[84:87]
	ds_read_b128 v[200:203], v129 offset:13312
	v_mfma_f32_16x16x32_bf16 v[88:91], v[236:239], v[204:207], v[88:91]
	v_mfma_f32_16x16x32_bf16 v[92:95], v[236:239], v[208:211], v[92:95]
	v_mfma_f32_16x16x32_bf16 v[64:67], v[240:243], v[204:207], v[64:67]
	v_mfma_f32_16x16x32_bf16 v[68:71], v[240:243], v[208:211], v[68:71]
	v_mfma_f32_16x16x32_bf16 v[72:75], v[244:247], v[204:207], v[72:75]
	v_mfma_f32_16x16x32_bf16 v[76:79], v[244:247], v[208:211], v[76:79]
	s_waitcnt lgkmcnt(0)
	s_waitcnt vmcnt(6)
	s_barrier
	ds_read_b128 v[132:135], v156 offset:24576
	ds_read_b128 v[136:139], v156 offset:25600
	v_mfma_f32_16x16x32_bf16 v[48:51], v[184:187], v[212:215], v[48:51]
	ds_read_b128 v[140:143], v156 offset:26624
	ds_read_b128 v[180:183], v156 offset:27648
	v_mfma_f32_16x16x32_bf16 v[52:55], v[184:187], v[216:219], v[52:55]
	ds_read_b128 v[204:207], v129 offset:24576
	ds_read_b128 v[208:211], v129 offset:25600
	s_add_u32 m0, s8, 0x0
	v_mfma_f32_16x16x32_bf16 v[56:59], v[236:239], v[212:215], v[56:59]
	global_load_lds_dwordx4 v189, s[4:5]
	s_add_u32 m0, s8, 0x1000
	v_mfma_f32_16x16x32_bf16 v[60:63], v[236:239], v[216:219], v[60:63]
	global_load_lds_dwordx4 v252, s[4:5]
	s_add_u32 m0, s8, 0x2000
	v_mfma_f32_16x16x32_bf16 v[32:35], v[240:243], v[212:215], v[32:35]
	global_load_lds_dwordx4 v190, s[4:5]
	v_mfma_f32_16x16x32_bf16 v[36:39], v[240:243], v[216:219], v[36:39]
	v_mfma_f32_16x16x32_bf16 v[40:43], v[244:247], v[212:215], v[40:43]
	v_mfma_f32_16x16x32_bf16 v[44:47], v[244:247], v[216:219], v[44:47]
	ds_read_b128 v[212:215], v129 offset:28672
	ds_read_b128 v[216:219], v129 offset:29696
	v_mfma_f32_16x16x32_bf16 v[16:19], v[184:187], v[248:251], v[16:19]
	s_add_u32 m0, s8, 0x3000
	v_mfma_f32_16x16x32_bf16 v[20:23], v[184:187], v[200:203], v[20:23]
	global_load_lds_dwordx4 v191, s[4:5]
	s_add_u32 m0, s8, 0x4000
	v_mfma_f32_16x16x32_bf16 v[24:27], v[236:239], v[248:251], v[24:27]
	global_load_lds_dwordx4 v189, s[6:7]
	s_add_u32 m0, s8, 0x5000
	v_mfma_f32_16x16x32_bf16 v[28:31], v[236:239], v[200:203], v[28:31]
	global_load_lds_dwordx4 v252, s[6:7]
	s_add_u32 s4, s4, 0x202000
	s_addc_u32 s5, s5, 0
	v_mfma_f32_16x16x32_bf16 v[0:3], v[240:243], v[248:251], v[0:3]
	s_add_u32 s6, s6, 0x40000
	s_addc_u32 s7, s7, 0
	v_mfma_f32_16x16x32_bf16 v[4:7], v[240:243], v[200:203], v[4:7]
	v_mfma_f32_16x16x32_bf16 v[8:11], v[244:247], v[248:251], v[8:11]
	v_mfma_f32_16x16x32_bf16 v[12:15], v[244:247], v[200:203], v[12:15]
	s_waitcnt lgkmcnt(2)
	v_mfma_f32_16x16x32_bf16 v[112:115], v[132:135], v[204:207], v[112:115]
	ds_read_b128 v[248:251], v129 offset:32768
	v_mfma_f32_16x16x32_bf16 v[116:119], v[132:135], v[208:211], v[116:119]
	ds_read_b128 v[200:203], v129 offset:33792
	v_mfma_f32_16x16x32_bf16 v[120:123], v[136:139], v[204:207], v[120:123]
	v_mfma_f32_16x16x32_bf16 v[124:127], v[136:139], v[208:211], v[124:127]
	v_mfma_f32_16x16x32_bf16 v[96:99], v[140:143], v[204:207], v[96:99]
	v_mfma_f32_16x16x32_bf16 v[100:103], v[140:143], v[208:211], v[100:103]
	v_mfma_f32_16x16x32_bf16 v[104:107], v[180:183], v[204:207], v[104:107]
	v_mfma_f32_16x16x32_bf16 v[108:111], v[180:183], v[208:211], v[108:111]
	s_waitcnt lgkmcnt(2)
	v_mfma_f32_16x16x32_bf16 v[80:83], v[132:135], v[212:215], v[80:83]
	ds_read_b128 v[204:207], v129 offset:36864
	v_mfma_f32_16x16x32_bf16 v[84:87], v[132:135], v[216:219], v[84:87]
	ds_read_b128 v[208:211], v129 offset:37888
	v_mfma_f32_16x16x32_bf16 v[88:91], v[136:139], v[212:215], v[88:91]
	v_mfma_f32_16x16x32_bf16 v[92:95], v[136:139], v[216:219], v[92:95]
	v_mfma_f32_16x16x32_bf16 v[64:67], v[140:143], v[212:215], v[64:67]
	v_mfma_f32_16x16x32_bf16 v[68:71], v[140:143], v[216:219], v[68:71]
	v_mfma_f32_16x16x32_bf16 v[72:75], v[180:183], v[212:215], v[72:75]
	v_mfma_f32_16x16x32_bf16 v[76:79], v[180:183], v[216:219], v[76:79]
	s_waitcnt lgkmcnt(0)
	s_waitcnt vmcnt(6)
	s_barrier
	ds_read_b128 v[184:187], v156 offset:49152
	ds_read_b128 v[236:239], v156 offset:50176
	v_mfma_f32_16x16x32_bf16 v[48:51], v[132:135], v[248:251], v[48:51]
	ds_read_b128 v[240:243], v156 offset:51200
	ds_read_b128 v[244:247], v156 offset:52224
	v_mfma_f32_16x16x32_bf16 v[52:55], v[132:135], v[200:203], v[52:55]
	ds_read_b128 v[212:215], v129 offset:49152
	ds_read_b128 v[216:219], v129 offset:50176
	s_add_u32 m0, s8, 0x6000
	v_mfma_f32_16x16x32_bf16 v[56:59], v[136:139], v[248:251], v[56:59]
	global_load_lds_dwordx4 v189, s[4:5]
	s_add_u32 m0, s8, 0x7000
	v_mfma_f32_16x16x32_bf16 v[60:63], v[136:139], v[200:203], v[60:63]
	global_load_lds_dwordx4 v252, s[4:5]
	s_add_u32 m0, s8, 0x8000
	v_mfma_f32_16x16x32_bf16 v[32:35], v[140:143], v[248:251], v[32:35]
	global_load_lds_dwordx4 v190, s[4:5]
	v_mfma_f32_16x16x32_bf16 v[36:39], v[140:143], v[200:203], v[36:39]
	v_mfma_f32_16x16x32_bf16 v[40:43], v[180:183], v[248:251], v[40:43]
	v_mfma_f32_16x16x32_bf16 v[44:47], v[180:183], v[200:203], v[44:47]
	ds_read_b128 v[248:251], v129 offset:53248
	ds_read_b128 v[200:203], v129 offset:54272
	v_mfma_f32_16x16x32_bf16 v[16:19], v[132:135], v[204:207], v[16:19]
	s_add_u32 m0, s8, 0x9000
	v_mfma_f32_16x16x32_bf16 v[20:23], v[132:135], v[208:211], v[20:23]
	global_load_lds_dwordx4 v191, s[4:5]
	s_add_u32 m0, s8, 0xa000
	v_mfma_f32_16x16x32_bf16 v[24:27], v[136:139], v[204:207], v[24:27]
	global_load_lds_dwordx4 v189, s[6:7]
	s_add_u32 m0, s8, 0xb000
	v_mfma_f32_16x16x32_bf16 v[28:31], v[136:139], v[208:211], v[28:31]
	global_load_lds_dwordx4 v252, s[6:7]
	s_add_u32 s4, s4, 0x202000
	s_addc_u32 s5, s5, 0
	v_mfma_f32_16x16x32_bf16 v[0:3], v[140:143], v[204:207], v[0:3]
	s_add_u32 s6, s6, 0x40000
	s_addc_u32 s7, s7, 0
	v_mfma_f32_16x16x32_bf16 v[4:7], v[140:143], v[208:211], v[4:7]
	v_mfma_f32_16x16x32_bf16 v[8:11], v[180:183], v[204:207], v[8:11]
	v_mfma_f32_16x16x32_bf16 v[12:15], v[180:183], v[208:211], v[12:15]
	s_waitcnt lgkmcnt(2)
	v_mfma_f32_16x16x32_bf16 v[112:115], v[184:187], v[212:215], v[112:115]
	ds_read_b128 v[204:207], v129 offset:57344
	v_mfma_f32_16x16x32_bf16 v[116:119], v[184:187], v[216:219], v[116:119]
	ds_read_b128 v[208:211], v129 offset:58368
	v_mfma_f32_16x16x32_bf16 v[120:123], v[236:239], v[212:215], v[120:123]
	v_mfma_f32_16x16x32_bf16 v[124:127], v[236:239], v[216:219], v[124:127]
	v_mfma_f32_16x16x32_bf16 v[96:99], v[240:243], v[212:215], v[96:99]
	v_mfma_f32_16x16x32_bf16 v[100:103], v[240:243], v[216:219], v[100:103]
	v_mfma_f32_16x16x32_bf16 v[104:107], v[244:247], v[212:215], v[104:107]
	v_mfma_f32_16x16x32_bf16 v[108:111], v[244:247], v[216:219], v[108:111]
	s_waitcnt lgkmcnt(2)
	v_mfma_f32_16x16x32_bf16 v[80:83], v[184:187], v[248:251], v[80:83]
	ds_read_b128 v[212:215], v129 offset:61440
	v_mfma_f32_16x16x32_bf16 v[84:87], v[184:187], v[200:203], v[84:87]
	ds_read_b128 v[216:219], v129 offset:62464
	v_mfma_f32_16x16x32_bf16 v[88:91], v[236:239], v[248:251], v[88:91]
	v_mfma_f32_16x16x32_bf16 v[92:95], v[236:239], v[200:203], v[92:95]
	v_mfma_f32_16x16x32_bf16 v[64:67], v[240:243], v[248:251], v[64:67]
	v_mfma_f32_16x16x32_bf16 v[68:71], v[240:243], v[200:203], v[68:71]
	v_mfma_f32_16x16x32_bf16 v[72:75], v[244:247], v[248:251], v[72:75]
	v_mfma_f32_16x16x32_bf16 v[76:79], v[244:247], v[200:203], v[76:79]
	s_waitcnt lgkmcnt(0)
	s_waitcnt vmcnt(6)
	s_barrier
	ds_read_b128 v[132:135], v156
	ds_read_b128 v[136:139], v156 offset:1024
	v_mfma_f32_16x16x32_bf16 v[48:51], v[184:187], v[204:207], v[48:51]
	ds_read_b128 v[140:143], v156 offset:2048
	ds_read_b128 v[180:183], v156 offset:3072
	v_mfma_f32_16x16x32_bf16 v[52:55], v[184:187], v[208:211], v[52:55]
	ds_read_b128 v[248:251], v129
	ds_read_b128 v[200:203], v129 offset:1024
	s_add_u32 m0, s8, 0xc000
	v_mfma_f32_16x16x32_bf16 v[56:59], v[236:239], v[204:207], v[56:59]
	global_load_lds_dwordx4 v189, s[4:5]
	s_add_u32 m0, s8, 0xd000
	v_mfma_f32_16x16x32_bf16 v[60:63], v[236:239], v[208:211], v[60:63]
	global_load_lds_dwordx4 v252, s[4:5]
	s_add_u32 m0, s8, 0xe000
	v_mfma_f32_16x16x32_bf16 v[32:35], v[240:243], v[204:207], v[32:35]
	global_load_lds_dwordx4 v190, s[4:5]
	v_mfma_f32_16x16x32_bf16 v[36:39], v[240:243], v[208:211], v[36:39]
	v_mfma_f32_16x16x32_bf16 v[40:43], v[244:247], v[204:207], v[40:43]
	v_mfma_f32_16x16x32_bf16 v[44:47], v[244:247], v[208:211], v[44:47]
	ds_read_b128 v[204:207], v129 offset:4096
	ds_read_b128 v[208:211], v129 offset:5120
	v_mfma_f32_16x16x32_bf16 v[16:19], v[184:187], v[212:215], v[16:19]
	s_add_u32 m0, s8, 0xf000
	v_mfma_f32_16x16x32_bf16 v[20:23], v[184:187], v[216:219], v[20:23]
	global_load_lds_dwordx4 v191, s[4:5]
	s_add_u32 m0, s8, 0x10000
	v_mfma_f32_16x16x32_bf16 v[24:27], v[236:239], v[212:215], v[24:27]
	global_load_lds_dwordx4 v189, s[6:7]
	s_add_u32 m0, s8, 0x11000
	v_mfma_f32_16x16x32_bf16 v[28:31], v[236:239], v[216:219], v[28:31]
	global_load_lds_dwordx4 v252, s[6:7]
	s_add_u32 s4, s4, 0x202000
	s_addc_u32 s5, s5, 0
	v_mfma_f32_16x16x32_bf16 v[0:3], v[240:243], v[212:215], v[0:3]
	s_add_u32 s6, s6, 0x40000
	s_addc_u32 s7, s7, 0
	v_mfma_f32_16x16x32_bf16 v[4:7], v[240:243], v[216:219], v[4:7]
	v_mfma_f32_16x16x32_bf16 v[8:11], v[244:247], v[212:215], v[8:11]
	v_mfma_f32_16x16x32_bf16 v[12:15], v[244:247], v[216:219], v[12:15]
	s_sub_i32 s9, s9, 1
	s_cmp_lg_u32 s9, 0
	s_cbranch_scc1 .Lgemm_p4_loop
	s_waitcnt lgkmcnt(2)
	v_mfma_f32_16x16x32_bf16 v[112:115], v[132:135], v[248:251], v[112:115]
	ds_read_b128 v[212:215], v129 offset:8192
	v_mfma_f32_16x16x32_bf16 v[116:119], v[132:135], v[200:203], v[116:119]
	ds_read_b128 v[216:219], v129 offset:9216
	v_mfma_f32_16x16x32_bf16 v[120:123], v[136:139], v[248:251], v[120:123]
	v_mfma_f32_16x16x32_bf16 v[124:127], v[136:139], v[200:203], v[124:127]
	v_mfma_f32_16x16x32_bf16 v[96:99], v[140:143], v[248:251], v[96:99]
	v_mfma_f32_16x16x32_bf16 v[100:103], v[140:143], v[200:203], v[100:103]
	v_mfma_f32_16x16x32_bf16 v[104:107], v[180:183], v[248:251], v[104:107]
	v_mfma_f32_16x16x32_bf16 v[108:111], v[180:183], v[200:203], v[108:111]
	s_waitcnt lgkmcnt(2)
	v_mfma_f32_16x16x32_bf16 v[80:83], v[132:135], v[204:207], v[80:83]
	ds_read_b128 v[248:251], v129 offset:12288
	v_mfma_f32_16x16x32_bf16 v[84:87], v[132:135], v[208:211], v[84:87]
	ds_read_b128 v[200:203], v129 offset:13312
	v_mfma_f32_16x16x32_bf16 v[88:91], v[136:139], v[204:207], v[88:91]
	v_mfma_f32_16x16x32_bf16 v[92:95], v[136:139], v[208:211], v[92:95]
	v_mfma_f32_16x16x32_bf16 v[64:67], v[140:143], v[204:207], v[64:67]
	v_mfma_f32_16x16x32_bf16 v[68:71], v[140:143], v[208:211], v[68:71]
	v_mfma_f32_16x16x32_bf16 v[72:75], v[180:183], v[204:207], v[72:75]
	v_mfma_f32_16x16x32_bf16 v[76:79], v[180:183], v[208:211], v[76:79]
	s_waitcnt lgkmcnt(0)
	s_waitcnt vmcnt(6)
	s_barrier
	ds_read_b128 v[184:187], v156 offset:24576
	ds_read_b128 v[236:239], v156 offset:25600
	v_mfma_f32_16x16x32_bf16 v[48:51], v[132:135], v[212:215], v[48:51]
	ds_read_b128 v[240:243], v156 offset:26624
	ds_read_b128 v[244:247], v156 offset:27648
	v_mfma_f32_16x16x32_bf16 v[52:55], v[132:135], v[216:219], v[52:55]
	ds_read_b128 v[204:207], v129 offset:24576
	ds_read_b128 v[208:211], v129 offset:25600
	s_add_u32 m0, s8, 0x0
	v_mfma_f32_16x16x32_bf16 v[56:59], v[136:139], v[212:215], v[56:59]
	global_load_lds_dwordx4 v189, s[4:5]
	s_add_u32 m0, s8, 0x1000
	v_mfma_f32_16x16x32_bf16 v[60:63], v[136:139], v[216:219], v[60:63]
	global_load_lds_dwordx4 v252, s[4:5]
	s_add_u32 m0, s8, 0x2000
	v_mfma_f32_16x16x32_bf16 v[32:35], v[140:143], v[212:215], v[32:35]
	global_load_lds_dwordx4 v190, s[4:5]
	v_mfma_f32_16x16x32_bf16 v[36:39], v[140:143], v[216:219], v[36:39]
	v_mfma_f32_16x16x32_bf16 v[40:43], v[180:183], v[212:215], v[40:43]
	v_mfma_f32_16x16x32_bf16 v[44:47], v[180:183], v[216:219], v[44:47]
	ds_read_b128 v[212:215], v129 offset:28672
	ds_read_b128 v[216:219], v129 offset:29696
	v_mfma_f32_16x16x32_bf16 v[16:19], v[132:135], v[248:251], v[16:19]
	s_add_u32 m0, s8, 0x3000
	v_mfma_f32_16x16x32_bf16 v[20:23], v[132:135], v[200:203], v[20:23]
	global_load_lds_dwordx4 v191, s[4:5]
	s_add_u32 m0, s8, 0x4000
	v_mfma_f32_16x16x32_bf16 v[24:27], v[136:139], v[248:251], v[24:27]
	global_load_lds_dwordx4 v189, s[6:7]
	s_add_u32 m0, s8, 0x5000
	v_mfma_f32_16x16x32_bf16 v[28:31], v[136:139], v[200:203], v[28:31]
	global_load_lds_dwordx4 v252, s[6:7]
	s_add_u32 s4, s4, 0x202000
	s_addc_u32 s5, s5, 0
	v_mfma_f32_16x16x32_bf16 v[0:3], v[140:143], v[248:251], v[0:3]
	s_add_u32 s6, s6, 0x40000
	s_addc_u32 s7, s7, 0
	v_mfma_f32_16x16x32_bf16 v[4:7], v[140:143], v[200:203], v[4:7]
	v_mfma_f32_16x16x32_bf16 v[8:11], v[180:183], v[248:251], v[8:11]
	v_mfma_f32_16x16x32_bf16 v[12:15], v[180:183], v[200:203], v[12:15]
	s_waitcnt lgkmcnt(2)
	v_mfma_f32_16x16x32_bf16 v[112:115], v[184:187], v[204:207], v[112:115]
	ds_read_b128 v[248:251], v129 offset:32768
	v_mfma_f32_16x16x32_bf16 v[116:119], v[184:187], v[208:211], v[116:119]
	ds_read_b128 v[200:203], v129 offset:33792
	v_mfma_f32_16x16x32_bf16 v[120:123], v[236:239], v[204:207], v[120:123]
	v_mfma_f32_16x16x32_bf16 v[124:127], v[236:239], v[208:211], v[124:127]
	v_mfma_f32_16x16x32_bf16 v[96:99], v[240:243], v[204:207], v[96:99]
	v_mfma_f32_16x16x32_bf16 v[100:103], v[240:243], v[208:211], v[100:103]
	v_mfma_f32_16x16x32_bf16 v[104:107], v[244:247], v[204:207], v[104:107]
	v_mfma_f32_16x16x32_bf16 v[108:111], v[244:247], v[208:211], v[108:111]
	s_waitcnt lgkmcnt(2)
	v_mfma_f32_16x16x32_bf16 v[80:83], v[184:187], v[212:215], v[80:83]
	ds_read_b128 v[204:207], v129 offset:36864
	v_mfma_f32_16x16x32_bf16 v[84:87], v[184:187], v[216:219], v[84:87]
	ds_read_b128 v[208:211], v129 offset:37888
	v_mfma_f32_16x16x32_bf16 v[88:91], v[236:239], v[212:215], v[88:91]
	v_mfma_f32_16x16x32_bf16 v[92:95], v[236:239], v[216:219], v[92:95]
	v_mfma_f32_16x16x32_bf16 v[64:67], v[240:243], v[212:215], v[64:67]
	v_mfma_f32_16x16x32_bf16 v[68:71], v[240:243], v[216:219], v[68:71]
	v_mfma_f32_16x16x32_bf16 v[72:75], v[244:247], v[212:215], v[72:75]
	v_mfma_f32_16x16x32_bf16 v[76:79], v[244:247], v[216:219], v[76:79]
	s_waitcnt lgkmcnt(0)
	s_waitcnt vmcnt(6)
	s_barrier
	ds_read_b128 v[132:135], v156 offset:49152
	ds_read_b128 v[136:139], v156 offset:50176
	v_mfma_f32_16x16x32_bf16 v[48:51], v[184:187], v[248:251], v[48:51]
	ds_read_b128 v[140:143], v156 offset:51200
	ds_read_b128 v[180:183], v156 offset:52224
	v_mfma_f32_16x16x32_bf16 v[52:55], v[184:187], v[200:203], v[52:55]
	ds_read_b128 v[212:215], v129 offset:49152
	ds_read_b128 v[216:219], v129 offset:50176
	s_add_u32 m0, s8, 0x6000
	v_mfma_f32_16x16x32_bf16 v[56:59], v[236:239], v[248:251], v[56:59]
	global_load_lds_dwordx4 v189, s[4:5]
	s_add_u32 m0, s8, 0x7000
	v_mfma_f32_16x16x32_bf16 v[60:63], v[236:239], v[200:203], v[60:63]
	global_load_lds_dwordx4 v252, s[4:5]
	s_add_u32 m0, s8, 0x8000
	v_mfma_f32_16x16x32_bf16 v[32:35], v[240:243], v[248:251], v[32:35]
	global_load_lds_dwordx4 v190, s[4:5]
	v_mfma_f32_16x16x32_bf16 v[36:39], v[240:243], v[200:203], v[36:39]
	v_mfma_f32_16x16x32_bf16 v[40:43], v[244:247], v[248:251], v[40:43]
	v_mfma_f32_16x16x32_bf16 v[44:47], v[244:247], v[200:203], v[44:47]
	ds_read_b128 v[248:251], v129 offset:53248
	ds_read_b128 v[200:203], v129 offset:54272
	v_mfma_f32_16x16x32_bf16 v[16:19], v[184:187], v[204:207], v[16:19]
	s_add_u32 m0, s8, 0x9000
	v_mfma_f32_16x16x32_bf16 v[20:23], v[184:187], v[208:211], v[20:23]
	global_load_lds_dwordx4 v191, s[4:5]
	s_add_u32 m0, s8, 0xa000
	v_mfma_f32_16x16x32_bf16 v[24:27], v[236:239], v[204:207], v[24:27]
	global_load_lds_dwordx4 v189, s[6:7]
	s_add_u32 m0, s8, 0xb000
	v_mfma_f32_16x16x32_bf16 v[28:31], v[236:239], v[208:211], v[28:31]
	global_load_lds_dwordx4 v252, s[6:7]
	s_add_u32 s4, s4, 0x202000
	s_addc_u32 s5, s5, 0
	v_mfma_f32_16x16x32_bf16 v[0:3], v[240:243], v[204:207], v[0:3]
	s_add_u32 s6, s6, 0x40000
	s_addc_u32 s7, s7, 0
	v_mfma_f32_16x16x32_bf16 v[4:7], v[240:243], v[208:211], v[4:7]
	v_mfma_f32_16x16x32_bf16 v[8:11], v[244:247], v[204:207], v[8:11]
	v_mfma_f32_16x16x32_bf16 v[12:15], v[244:247], v[208:211], v[12:15]
	s_waitcnt lgkmcnt(2)
	v_mfma_f32_16x16x32_bf16 v[112:115], v[132:135], v[212:215], v[112:115]
	ds_read_b128 v[204:207], v129 offset:57344
	v_mfma_f32_16x16x32_bf16 v[116:119], v[132:135], v[216:219], v[116:119]
	ds_read_b128 v[208:211], v129 offset:58368
	v_mfma_f32_16x16x32_bf16 v[120:123], v[136:139], v[212:215], v[120:123]
	v_mfma_f32_16x16x32_bf16 v[124:127], v[136:139], v[216:219], v[124:127]
	v_mfma_f32_16x16x32_bf16 v[96:99], v[140:143], v[212:215], v[96:99]
	v_mfma_f32_16x16x32_bf16 v[100:103], v[140:143], v[216:219], v[100:103]
	v_mfma_f32_16x16x32_bf16 v[104:107], v[180:183], v[212:215], v[104:107]
	v_mfma_f32_16x16x32_bf16 v[108:111], v[180:183], v[216:219], v[108:111]
	s_waitcnt lgkmcnt(2)
	v_mfma_f32_16x16x32_bf16 v[80:83], v[132:135], v[248:251], v[80:83]
	ds_read_b128 v[212:215], v129 offset:61440
	v_mfma_f32_16x16x32_bf16 v[84:87], v[132:135], v[200:203], v[84:87]
	ds_read_b128 v[216:219], v129 offset:62464
	v_mfma_f32_16x16x32_bf16 v[88:91], v[136:139], v[248:251], v[88:91]
	v_mfma_f32_16x16x32_bf16 v[92:95], v[136:139], v[200:203], v[92:95]
	v_mfma_f32_16x16x32_bf16 v[64:67], v[140:143], v[248:251], v[64:67]
	v_mfma_f32_16x16x32_bf16 v[68:71], v[140:143], v[200:203], v[68:71]
	v_mfma_f32_16x16x32_bf16 v[72:75], v[180:183], v[248:251], v[72:75]
	v_mfma_f32_16x16x32_bf16 v[76:79], v[180:183], v[200:203], v[76:79]
	s_waitcnt lgkmcnt(0)
	s_waitcnt vmcnt(6)
	s_barrier
	ds_read_b128 v[184:187], v156
	ds_read_b128 v[236:239], v156 offset:1024
	v_mfma_f32_16x16x32_bf16 v[48:51], v[132:135], v[204:207], v[48:51]
	ds_read_b128 v[240:243], v156 offset:2048
	ds_read_b128 v[244:247], v156 offset:3072
	v_mfma_f32_16x16x32_bf16 v[52:55], v[132:135], v[208:211], v[52:55]
	ds_read_b128 v[248:251], v129
	ds_read_b128 v[200:203], v129 offset:1024
	s_add_u32 m0, s8, 0xc000
	v_mfma_f32_16x16x32_bf16 v[56:59], v[136:139], v[204:207], v[56:59]
	global_load_lds_dwordx4 v189, s[4:5]
	s_add_u32 m0, s8, 0xd000
	v_mfma_f32_16x16x32_bf16 v[60:63], v[136:139], v[208:211], v[60:63]
	global_load_lds_dwordx4 v252, s[4:5]
	s_add_u32 m0, s8, 0xe000
	v_mfma_f32_16x16x32_bf16 v[32:35], v[140:143], v[204:207], v[32:35]
	global_load_lds_dwordx4 v190, s[4:5]
	v_mfma_f32_16x16x32_bf16 v[36:39], v[140:143], v[208:211], v[36:39]
	v_mfma_f32_16x16x32_bf16 v[40:43], v[180:183], v[204:207], v[40:43]
	v_mfma_f32_16x16x32_bf16 v[44:47], v[180:183], v[208:211], v[44:47]
	ds_read_b128 v[204:207], v129 offset:4096
	ds_read_b128 v[208:211], v129 offset:5120
	v_mfma_f32_16x16x32_bf16 v[16:19], v[132:135], v[212:215], v[16:19]
	s_add_u32 m0, s8, 0xf000
	v_mfma_f32_16x16x32_bf16 v[20:23], v[132:135], v[216:219], v[20:23]
	global_load_lds_dwordx4 v191, s[4:5]
	s_add_u32 m0, s8, 0x10000
	v_mfma_f32_16x16x32_bf16 v[24:27], v[136:139], v[212:215], v[24:27]
	global_load_lds_dwordx4 v189, s[6:7]
	s_add_u32 m0, s8, 0x11000
	v_mfma_f32_16x16x32_bf16 v[28:31], v[136:139], v[216:219], v[28:31]
	global_load_lds_dwordx4 v252, s[6:7]
	s_add_u32 s4, s4, 0x202000
	s_addc_u32 s5, s5, 0
	v_mfma_f32_16x16x32_bf16 v[0:3], v[140:143], v[212:215], v[0:3]
	s_add_u32 s6, s6, 0x40000
	s_addc_u32 s7, s7, 0
	v_mfma_f32_16x16x32_bf16 v[4:7], v[140:143], v[216:219], v[4:7]
	v_mfma_f32_16x16x32_bf16 v[8:11], v[180:183], v[212:215], v[8:11]
	v_mfma_f32_16x16x32_bf16 v[12:15], v[180:183], v[216:219], v[12:15]
	s_waitcnt lgkmcnt(2)
	v_mfma_f32_16x16x32_bf16 v[112:115], v[184:187], v[248:251], v[112:115]
	ds_read_b128 v[212:215], v129 offset:8192
	v_mfma_f32_16x16x32_bf16 v[116:119], v[184:187], v[200:203], v[116:119]
	ds_read_b128 v[216:219], v129 offset:9216
	v_mfma_f32_16x16x32_bf16 v[120:123], v[236:239], v[248:251], v[120:123]
	v_mfma_f32_16x16x32_bf16 v[124:127], v[236:239], v[200:203], v[124:127]
	v_mfma_f32_16x16x32_bf16 v[96:99], v[240:243], v[248:251], v[96:99]
	v_mfma_f32_16x16x32_bf16 v[100:103], v[240:243], v[200:203], v[100:103]
	v_mfma_f32_16x16x32_bf16 v[104:107], v[244:247], v[248:251], v[104:107]
	v_mfma_f32_16x16x32_bf16 v[108:111], v[244:247], v[200:203], v[108:111]
	s_waitcnt lgkmcnt(2)
	v_mfma_f32_16x16x32_bf16 v[80:83], v[184:187], v[204:207], v[80:83]
	ds_read_b128 v[248:251], v129 offset:12288
	v_mfma_f32_16x16x32_bf16 v[84:87], v[184:187], v[208:211], v[84:87]
	ds_read_b128 v[200:203], v129 offset:13312
	v_mfma_f32_16x16x32_bf16 v[88:91], v[236:239], v[204:207], v[88:91]
	v_mfma_f32_16x16x32_bf16 v[92:95], v[236:239], v[208:211], v[92:95]
	v_mfma_f32_16x16x32_bf16 v[64:67], v[240:243], v[204:207], v[64:67]
	v_mfma_f32_16x16x32_bf16 v[68:71], v[240:243], v[208:211], v[68:71]
	v_mfma_f32_16x16x32_bf16 v[72:75], v[244:247], v[204:207], v[72:75]
	v_mfma_f32_16x16x32_bf16 v[76:79], v[244:247], v[208:211], v[76:79]
	s_waitcnt lgkmcnt(0)
	s_waitcnt vmcnt(6)
	s_barrier
	ds_read_b128 v[132:135], v156 offset:24576
	ds_read_b128 v[136:139], v156 offset:25600
	v_mfma_f32_16x16x32_bf16 v[48:51], v[184:187], v[212:215], v[48:51]
	ds_read_b128 v[140:143], v156 offset:26624
	ds_read_b128 v[180:183], v156 offset:27648
	v_mfma_f32_16x16x32_bf16 v[52:55], v[184:187], v[216:219], v[52:55]
	ds_read_b128 v[204:207], v129 offset:24576
	ds_read_b128 v[208:211], v129 offset:25600
	s_add_u32 m0, s8, 0x0
	v_mfma_f32_16x16x32_bf16 v[56:59], v[236:239], v[212:215], v[56:59]
	global_load_lds_dwordx4 v189, s[4:5]
	s_add_u32 m0, s8, 0x1000
	v_mfma_f32_16x16x32_bf16 v[60:63], v[236:239], v[216:219], v[60:63]
	global_load_lds_dwordx4 v252, s[4:5]
	s_add_u32 m0, s8, 0x2000
	v_mfma_f32_16x16x32_bf16 v[32:35], v[240:243], v[212:215], v[32:35]
	global_load_lds_dwordx4 v190, s[4:5]
	v_mfma_f32_16x16x32_bf16 v[36:39], v[240:243], v[216:219], v[36:39]
	v_mfma_f32_16x16x32_bf16 v[40:43], v[244:247], v[212:215], v[40:43]
	v_mfma_f32_16x16x32_bf16 v[44:47], v[244:247], v[216:219], v[44:47]
	ds_read_b128 v[212:215], v129 offset:28672
	ds_read_b128 v[216:219], v129 offset:29696
	v_mfma_f32_16x16x32_bf16 v[16:19], v[184:187], v[248:251], v[16:19]
	s_add_u32 m0, s8, 0x3000
	v_mfma_f32_16x16x32_bf16 v[20:23], v[184:187], v[200:203], v[20:23]
	global_load_lds_dwordx4 v191, s[4:5]
	s_add_u32 m0, s8, 0x4000
	v_mfma_f32_16x16x32_bf16 v[24:27], v[236:239], v[248:251], v[24:27]
	global_load_lds_dwordx4 v189, s[6:7]
	s_add_u32 m0, s8, 0x5000
	v_mfma_f32_16x16x32_bf16 v[28:31], v[236:239], v[200:203], v[28:31]
	global_load_lds_dwordx4 v252, s[6:7]
	s_add_u32 s4, s4, 0x202000
	s_addc_u32 s5, s5, 0
	v_mfma_f32_16x16x32_bf16 v[0:3], v[240:243], v[248:251], v[0:3]
	s_add_u32 s6, s6, 0x40000
	s_addc_u32 s7, s7, 0
	v_mfma_f32_16x16x32_bf16 v[4:7], v[240:243], v[200:203], v[4:7]
	v_mfma_f32_16x16x32_bf16 v[8:11], v[244:247], v[248:251], v[8:11]
	v_mfma_f32_16x16x32_bf16 v[12:15], v[244:247], v[200:203], v[12:15]
	s_waitcnt lgkmcnt(2)
	v_mfma_f32_16x16x32_bf16 v[112:115], v[132:135], v[204:207], v[112:115]
	ds_read_b128 v[248:251], v129 offset:32768
	v_mfma_f32_16x16x32_bf16 v[116:119], v[132:135], v[208:211], v[116:119]
	ds_read_b128 v[200:203], v129 offset:33792
	v_mfma_f32_16x16x32_bf16 v[120:123], v[136:139], v[204:207], v[120:123]
	v_mfma_f32_16x16x32_bf16 v[124:127], v[136:139], v[208:211], v[124:127]
	v_mfma_f32_16x16x32_bf16 v[96:99], v[140:143], v[204:207], v[96:99]
	v_mfma_f32_16x16x32_bf16 v[100:103], v[140:143], v[208:211], v[100:103]
	v_mfma_f32_16x16x32_bf16 v[104:107], v[180:183], v[204:207], v[104:107]
	v_mfma_f32_16x16x32_bf16 v[108:111], v[180:183], v[208:211], v[108:111]
	s_waitcnt lgkmcnt(2)
	v_mfma_f32_16x16x32_bf16 v[80:83], v[132:135], v[212:215], v[80:83]
	ds_read_b128 v[204:207], v129 offset:36864
	v_mfma_f32_16x16x32_bf16 v[84:87], v[132:135], v[216:219], v[84:87]
	ds_read_b128 v[208:211], v129 offset:37888
	v_mfma_f32_16x16x32_bf16 v[88:91], v[136:139], v[212:215], v[88:91]
	v_mfma_f32_16x16x32_bf16 v[92:95], v[136:139], v[216:219], v[92:95]
	v_mfma_f32_16x16x32_bf16 v[64:67], v[140:143], v[212:215], v[64:67]
	v_mfma_f32_16x16x32_bf16 v[68:71], v[140:143], v[216:219], v[68:71]
	v_mfma_f32_16x16x32_bf16 v[72:75], v[180:183], v[212:215], v[72:75]
	v_mfma_f32_16x16x32_bf16 v[76:79], v[180:183], v[216:219], v[76:79]
	s_waitcnt lgkmcnt(0)
	s_waitcnt vmcnt(6)
	s_barrier
	ds_read_b128 v[184:187], v156 offset:49152
	ds_read_b128 v[236:239], v156 offset:50176
	v_mfma_f32_16x16x32_bf16 v[48:51], v[132:135], v[248:251], v[48:51]
	ds_read_b128 v[240:243], v156 offset:51200
	ds_read_b128 v[244:247], v156 offset:52224
	v_mfma_f32_16x16x32_bf16 v[52:55], v[132:135], v[200:203], v[52:55]
	ds_read_b128 v[212:215], v129 offset:49152
	ds_read_b128 v[216:219], v129 offset:50176
	s_add_u32 m0, s8, 0x6000
	v_mfma_f32_16x16x32_bf16 v[56:59], v[136:139], v[248:251], v[56:59]
	global_load_lds_dwordx4 v189, s[4:5]
	s_add_u32 m0, s8, 0x7000
	v_mfma_f32_16x16x32_bf16 v[60:63], v[136:139], v[200:203], v[60:63]
	global_load_lds_dwordx4 v252, s[4:5]
	s_add_u32 m0, s8, 0x8000
	v_mfma_f32_16x16x32_bf16 v[32:35], v[140:143], v[248:251], v[32:35]
	global_load_lds_dwordx4 v190, s[4:5]
	v_mfma_f32_16x16x32_bf16 v[36:39], v[140:143], v[200:203], v[36:39]
	v_mfma_f32_16x16x32_bf16 v[40:43], v[180:183], v[248:251], v[40:43]
	v_mfma_f32_16x16x32_bf16 v[44:47], v[180:183], v[200:203], v[44:47]
	ds_read_b128 v[248:251], v129 offset:53248
	ds_read_b128 v[200:203], v129 offset:54272
	v_mfma_f32_16x16x32_bf16 v[16:19], v[132:135], v[204:207], v[16:19]
	s_add_u32 m0, s8, 0x9000
	v_mfma_f32_16x16x32_bf16 v[20:23], v[132:135], v[208:211], v[20:23]
	global_load_lds_dwordx4 v191, s[4:5]
	s_add_u32 m0, s8, 0xa000
	v_mfma_f32_16x16x32_bf16 v[24:27], v[136:139], v[204:207], v[24:27]
	global_load_lds_dwordx4 v189, s[6:7]
	s_add_u32 m0, s8, 0xb000
	v_mfma_f32_16x16x32_bf16 v[28:31], v[136:139], v[208:211], v[28:31]
	global_load_lds_dwordx4 v252, s[6:7]
	s_add_u32 s4, s4, 0x202000
	s_addc_u32 s5, s5, 0
	v_mfma_f32_16x16x32_bf16 v[0:3], v[140:143], v[204:207], v[0:3]
	s_add_u32 s6, s6, 0x40000
	s_addc_u32 s7, s7, 0
	v_mfma_f32_16x16x32_bf16 v[4:7], v[140:143], v[208:211], v[4:7]
	v_mfma_f32_16x16x32_bf16 v[8:11], v[180:183], v[204:207], v[8:11]
	v_mfma_f32_16x16x32_bf16 v[12:15], v[180:183], v[208:211], v[12:15]
	s_waitcnt lgkmcnt(2)
	v_mfma_f32_16x16x32_bf16 v[112:115], v[184:187], v[212:215], v[112:115]
	ds_read_b128 v[204:207], v129 offset:57344
	v_mfma_f32_16x16x32_bf16 v[116:119], v[184:187], v[216:219], v[116:119]
	ds_read_b128 v[208:211], v129 offset:58368
	v_mfma_f32_16x16x32_bf16 v[120:123], v[236:239], v[212:215], v[120:123]
	v_mfma_f32_16x16x32_bf16 v[124:127], v[236:239], v[216:219], v[124:127]
	v_mfma_f32_16x16x32_bf16 v[96:99], v[240:243], v[212:215], v[96:99]
	v_mfma_f32_16x16x32_bf16 v[100:103], v[240:243], v[216:219], v[100:103]
	v_mfma_f32_16x16x32_bf16 v[104:107], v[244:247], v[212:215], v[104:107]
	v_mfma_f32_16x16x32_bf16 v[108:111], v[244:247], v[216:219], v[108:111]
	s_waitcnt lgkmcnt(2)
	v_mfma_f32_16x16x32_bf16 v[80:83], v[184:187], v[248:251], v[80:83]
	ds_read_b128 v[212:215], v129 offset:61440
	v_mfma_f32_16x16x32_bf16 v[84:87], v[184:187], v[200:203], v[84:87]
	ds_read_b128 v[216:219], v129 offset:62464
	v_mfma_f32_16x16x32_bf16 v[88:91], v[236:239], v[248:251], v[88:91]
	v_mfma_f32_16x16x32_bf16 v[92:95], v[236:239], v[200:203], v[92:95]
	v_mfma_f32_16x16x32_bf16 v[64:67], v[240:243], v[248:251], v[64:67]
	v_mfma_f32_16x16x32_bf16 v[68:71], v[240:243], v[200:203], v[68:71]
	v_mfma_f32_16x16x32_bf16 v[72:75], v[244:247], v[248:251], v[72:75]
	v_mfma_f32_16x16x32_bf16 v[76:79], v[244:247], v[200:203], v[76:79]
	s_waitcnt lgkmcnt(0)
	s_waitcnt vmcnt(6)
	s_barrier
	ds_read_b128 v[132:135], v156
	ds_read_b128 v[136:139], v156 offset:1024
	v_mfma_f32_16x16x32_bf16 v[48:51], v[184:187], v[204:207], v[48:51]
	ds_read_b128 v[140:143], v156 offset:2048
	ds_read_b128 v[180:183], v156 offset:3072
	v_mfma_f32_16x16x32_bf16 v[52:55], v[184:187], v[208:211], v[52:55]
	ds_read_b128 v[248:251], v129
	ds_read_b128 v[200:203], v129 offset:1024
	v_mfma_f32_16x16x32_bf16 v[56:59], v[236:239], v[204:207], v[56:59]
	v_mfma_f32_16x16x32_bf16 v[60:63], v[236:239], v[208:211], v[60:63]
	v_mfma_f32_16x16x32_bf16 v[32:35], v[240:243], v[204:207], v[32:35]
	v_mfma_f32_16x16x32_bf16 v[36:39], v[240:243], v[208:211], v[36:39]
	v_mfma_f32_16x16x32_bf16 v[40:43], v[244:247], v[204:207], v[40:43]
	v_mfma_f32_16x16x32_bf16 v[44:47], v[244:247], v[208:211], v[44:47]
	ds_read_b128 v[204:207], v129 offset:4096
	ds_read_b128 v[208:211], v129 offset:5120
	v_mfma_f32_16x16x32_bf16 v[16:19], v[184:187], v[212:215], v[16:19]
	v_mfma_f32_16x16x32_bf16 v[20:23], v[184:187], v[216:219], v[20:23]
	v_mfma_f32_16x16x32_bf16 v[24:27], v[236:239], v[212:215], v[24:27]
	v_mfma_f32_16x16x32_bf16 v[28:31], v[236:239], v[216:219], v[28:31]
	v_mfma_f32_16x16x32_bf16 v[0:3], v[240:243], v[212:215], v[0:3]
	v_mfma_f32_16x16x32_bf16 v[4:7], v[240:243], v[216:219], v[4:7]
	v_mfma_f32_16x16x32_bf16 v[8:11], v[244:247], v[212:215], v[8:11]
	v_mfma_f32_16x16x32_bf16 v[12:15], v[244:247], v[216:219], v[12:15]
	s_waitcnt lgkmcnt(2)
	v_mfma_f32_16x16x32_bf16 v[112:115], v[132:135], v[248:251], v[112:115]
	ds_read_b128 v[212:215], v129 offset:8192
	v_mfma_f32_16x16x32_bf16 v[116:119], v[132:135], v[200:203], v[116:119]
	ds_read_b128 v[216:219], v129 offset:9216
	v_mfma_f32_16x16x32_bf16 v[120:123], v[136:139], v[248:251], v[120:123]
	v_mfma_f32_16x16x32_bf16 v[124:127], v[136:139], v[200:203], v[124:127]
	v_mfma_f32_16x16x32_bf16 v[96:99], v[140:143], v[248:251], v[96:99]
	v_mfma_f32_16x16x32_bf16 v[100:103], v[140:143], v[200:203], v[100:103]
	v_mfma_f32_16x16x32_bf16 v[104:107], v[180:183], v[248:251], v[104:107]
	v_mfma_f32_16x16x32_bf16 v[108:111], v[180:183], v[200:203], v[108:111]
	s_waitcnt lgkmcnt(2)
	v_mfma_f32_16x16x32_bf16 v[80:83], v[132:135], v[204:207], v[80:83]
	ds_read_b128 v[248:251], v129 offset:12288
	v_mfma_f32_16x16x32_bf16 v[84:87], v[132:135], v[208:211], v[84:87]
	ds_read_b128 v[200:203], v129 offset:13312
	v_mfma_f32_16x16x32_bf16 v[88:91], v[136:139], v[204:207], v[88:91]
	v_mfma_f32_16x16x32_bf16 v[92:95], v[136:139], v[208:211], v[92:95]
	v_mfma_f32_16x16x32_bf16 v[64:67], v[140:143], v[204:207], v[64:67]
	v_mfma_f32_16x16x32_bf16 v[68:71], v[140:143], v[208:211], v[68:71]
	v_mfma_f32_16x16x32_bf16 v[72:75], v[180:183], v[204:207], v[72:75]
	v_mfma_f32_16x16x32_bf16 v[76:79], v[180:183], v[208:211], v[76:79]
	s_waitcnt lgkmcnt(0)
	s_waitcnt vmcnt(0)
	s_barrier
	ds_read_b128 v[184:187], v156 offset:24576
	ds_read_b128 v[236:239], v156 offset:25600
	v_mfma_f32_16x16x32_bf16 v[48:51], v[132:135], v[212:215], v[48:51]
	ds_read_b128 v[240:243], v156 offset:26624
	ds_read_b128 v[244:247], v156 offset:27648
	v_mfma_f32_16x16x32_bf16 v[52:55], v[132:135], v[216:219], v[52:55]
	ds_read_b128 v[204:207], v129 offset:24576
	ds_read_b128 v[208:211], v129 offset:25600
	v_mfma_f32_16x16x32_bf16 v[56:59], v[136:139], v[212:215], v[56:59]
	v_mfma_f32_16x16x32_bf16 v[60:63], v[136:139], v[216:219], v[60:63]
	v_mfma_f32_16x16x32_bf16 v[32:35], v[140:143], v[212:215], v[32:35]
	v_mfma_f32_16x16x32_bf16 v[36:39], v[140:143], v[216:219], v[36:39]
	v_mfma_f32_16x16x32_bf16 v[40:43], v[180:183], v[212:215], v[40:43]
	v_mfma_f32_16x16x32_bf16 v[44:47], v[180:183], v[216:219], v[44:47]
	ds_read_b128 v[212:215], v129 offset:28672
	ds_read_b128 v[216:219], v129 offset:29696
	v_mfma_f32_16x16x32_bf16 v[16:19], v[132:135], v[248:251], v[16:19]
	v_mfma_f32_16x16x32_bf16 v[20:23], v[132:135], v[200:203], v[20:23]
	v_mfma_f32_16x16x32_bf16 v[24:27], v[136:139], v[248:251], v[24:27]
	v_mfma_f32_16x16x32_bf16 v[28:31], v[136:139], v[200:203], v[28:31]
	v_mfma_f32_16x16x32_bf16 v[0:3], v[140:143], v[248:251], v[0:3]
	v_mfma_f32_16x16x32_bf16 v[4:7], v[140:143], v[200:203], v[4:7]
	v_mfma_f32_16x16x32_bf16 v[8:11], v[180:183], v[248:251], v[8:11]
	v_mfma_f32_16x16x32_bf16 v[12:15], v[180:183], v[200:203], v[12:15]
	s_waitcnt lgkmcnt(2)
	v_mfma_f32_16x16x32_bf16 v[112:115], v[184:187], v[204:207], v[112:115]
	ds_read_b128 v[248:251], v129 offset:32768
	v_mfma_f32_16x16x32_bf16 v[116:119], v[184:187], v[208:211], v[116:119]
	ds_read_b128 v[200:203], v129 offset:33792
	v_mfma_f32_16x16x32_bf16 v[120:123], v[236:239], v[204:207], v[120:123]
	v_mfma_f32_16x16x32_bf16 v[124:127], v[236:239], v[208:211], v[124:127]
	v_mfma_f32_16x16x32_bf16 v[96:99], v[240:243], v[204:207], v[96:99]
	v_mfma_f32_16x16x32_bf16 v[100:103], v[240:243], v[208:211], v[100:103]
	v_mfma_f32_16x16x32_bf16 v[104:107], v[244:247], v[204:207], v[104:107]
	v_mfma_f32_16x16x32_bf16 v[108:111], v[244:247], v[208:211], v[108:111]
	s_waitcnt lgkmcnt(2)
	v_mfma_f32_16x16x32_bf16 v[80:83], v[184:187], v[212:215], v[80:83]
	ds_read_b128 v[204:207], v129 offset:36864
	v_mfma_f32_16x16x32_bf16 v[84:87], v[184:187], v[216:219], v[84:87]
	ds_read_b128 v[208:211], v129 offset:37888
	v_mfma_f32_16x16x32_bf16 v[88:91], v[236:239], v[212:215], v[88:91]
	v_mfma_f32_16x16x32_bf16 v[92:95], v[236:239], v[216:219], v[92:95]
	v_mfma_f32_16x16x32_bf16 v[64:67], v[240:243], v[212:215], v[64:67]
	v_mfma_f32_16x16x32_bf16 v[68:71], v[240:243], v[216:219], v[68:71]
	v_mfma_f32_16x16x32_bf16 v[72:75], v[244:247], v[212:215], v[72:75]
	v_mfma_f32_16x16x32_bf16 v[76:79], v[244:247], v[216:219], v[76:79]
	s_waitcnt lgkmcnt(0)
	v_mfma_f32_16x16x32_bf16 v[48:51], v[184:187], v[248:251], v[48:51]
	v_mfma_f32_16x16x32_bf16 v[52:55], v[184:187], v[200:203], v[52:55]
	v_mfma_f32_16x16x32_bf16 v[56:59], v[236:239], v[248:251], v[56:59]
	v_mfma_f32_16x16x32_bf16 v[60:63], v[236:239], v[200:203], v[60:63]
	v_mfma_f32_16x16x32_bf16 v[32:35], v[240:243], v[248:251], v[32:35]
	v_mfma_f32_16x16x32_bf16 v[36:39], v[240:243], v[200:203], v[36:39]
	v_mfma_f32_16x16x32_bf16 v[40:43], v[244:247], v[248:251], v[40:43]
	v_mfma_f32_16x16x32_bf16 v[44:47], v[244:247], v[200:203], v[44:47]
	v_mfma_f32_16x16x32_bf16 v[16:19], v[184:187], v[204:207], v[16:19]
	v_mfma_f32_16x16x32_bf16 v[20:23], v[184:187], v[208:211], v[20:23]
	v_mfma_f32_16x16x32_bf16 v[24:27], v[236:239], v[204:207], v[24:27]
	v_mfma_f32_16x16x32_bf16 v[28:31], v[236:239], v[208:211], v[28:31]
	v_mfma_f32_16x16x32_bf16 v[0:3], v[240:243], v[204:207], v[0:3]
	v_mfma_f32_16x16x32_bf16 v[4:7], v[240:243], v[208:211], v[4:7]
	v_mfma_f32_16x16x32_bf16 v[8:11], v[244:247], v[204:207], v[8:11]
	v_mfma_f32_16x16x32_bf16 v[12:15], v[244:247], v[208:211], v[12:15]
	s_setprio 0
	s_nop 15
	s_nop 15
	v_permlane16_swap_b32_e32 v112, v116
	v_permlane16_swap_b32_e32 v113, v117
	v_permlane16_swap_b32_e32 v114, v118
	v_permlane16_swap_b32_e32 v115, v119
	v_permlane16_swap_b32_e32 v120, v124
	v_permlane16_swap_b32_e32 v121, v125
	v_permlane16_swap_b32_e32 v122, v126
	v_permlane16_swap_b32_e32 v123, v127
	v_permlane16_swap_b32_e32 v80, v84
	v_permlane16_swap_b32_e32 v81, v85
	v_permlane16_swap_b32_e32 v82, v86
	v_permlane16_swap_b32_e32 v83, v87
	v_permlane16_swap_b32_e32 v88, v92
	v_permlane16_swap_b32_e32 v89, v93
	v_permlane16_swap_b32_e32 v90, v94
	v_permlane16_swap_b32_e32 v91, v95
	v_permlane16_swap_b32_e32 v48, v52
	v_permlane16_swap_b32_e32 v49, v53
	v_permlane16_swap_b32_e32 v50, v54
	v_permlane16_swap_b32_e32 v51, v55
	v_permlane16_swap_b32_e32 v56, v60
	v_permlane16_swap_b32_e32 v57, v61
	v_permlane16_swap_b32_e32 v58, v62
	v_permlane16_swap_b32_e32 v59, v63
	v_permlane16_swap_b32_e32 v16, v20
	v_permlane16_swap_b32_e32 v17, v21
	v_permlane16_swap_b32_e32 v18, v22
	v_permlane16_swap_b32_e32 v19, v23
	v_permlane16_swap_b32_e32 v24, v28
	v_permlane16_swap_b32_e32 v25, v29
	v_permlane16_swap_b32_e32 v26, v30
	v_permlane16_swap_b32_e32 v27, v31
	v_permlane16_swap_b32_e32 v96, v100
	v_permlane16_swap_b32_e32 v97, v101
	v_permlane16_swap_b32_e32 v98, v102
	v_permlane16_swap_b32_e32 v99, v103
	v_permlane16_swap_b32_e32 v104, v108
	v_permlane16_swap_b32_e32 v105, v109
	v_permlane16_swap_b32_e32 v106, v110
	v_permlane16_swap_b32_e32 v107, v111
	v_permlane16_swap_b32_e32 v64, v68
	v_permlane16_swap_b32_e32 v65, v69
	v_permlane16_swap_b32_e32 v66, v70
	v_permlane16_swap_b32_e32 v67, v71
	v_permlane16_swap_b32_e32 v72, v76
	v_permlane16_swap_b32_e32 v73, v77
	v_permlane16_swap_b32_e32 v74, v78
	v_permlane16_swap_b32_e32 v75, v79
	v_permlane16_swap_b32_e32 v32, v36
	v_permlane16_swap_b32_e32 v33, v37
	v_permlane16_swap_b32_e32 v34, v38
	v_permlane16_swap_b32_e32 v35, v39
	v_permlane16_swap_b32_e32 v40, v44
	v_permlane16_swap_b32_e32 v41, v45
	v_permlane16_swap_b32_e32 v42, v46
	v_permlane16_swap_b32_e32 v43, v47
	v_permlane16_swap_b32_e32 v0, v4
	v_permlane16_swap_b32_e32 v1, v5
	v_permlane16_swap_b32_e32 v2, v6
	v_permlane16_swap_b32_e32 v3, v7
	v_permlane16_swap_b32_e32 v8, v12
	v_permlane16_swap_b32_e32 v9, v13
	v_permlane16_swap_b32_e32 v10, v14
	v_permlane16_swap_b32_e32 v11, v15
	s_nop 1
	v_or_b32_e32 v190, 8, v150
	v_or_b32_e32 v191, 9, v150
	v_or_b32_e32 v192, 10, v150
	v_or_b32_e32 v193, 11, v150
	v_or_b32_e32 v194, 16, v150
	v_or_b32_e32 v195, 17, v150
	v_or_b32_e32 v200, 18, v150
	v_or_b32_e32 v201, 19, v150
	v_or_b32_e32 v202, 24, v150
	v_or_b32_e32 v203, 25, v150
	v_or_b32_e32 v204, 26, v150
	v_or_b32_e32 v205, 27, v150
	v_or_b32_e32 v206, 32, v150
	v_or_b32_e32 v207, 33, v150
	v_or_b32_e32 v208, 34, v150
	v_or_b32_e32 v209, 35, v150
	v_or_b32_e32 v210, 40, v150
	v_or_b32_e32 v211, 41, v150
	v_or_b32_e32 v212, 42, v150
	v_or_b32_e32 v213, 43, v150
	v_or_b32_e32 v214, 48, v150
	v_or_b32_e32 v215, 49, v150
	v_or_b32_e32 v216, 50, v150
	v_or_b32_e32 v217, 51, v150
	v_or_b32_e32 v218, 56, v150
	v_or_b32_e32 v219, 57, v150
	v_or_b32_e32 v220, 58, v150
	v_or_b32_e32 v221, 59, v150
